# speedup vs baseline: 1.1079x; 1.0002x over previous
; #define PG8_STAGE(bufoff, gbase, voff) do { _Pragma("unroll") for (int _i = 0; _i < 2; ++_i) \
;         __builtin_amdgcn_global_load_lds((const unsigned*)((const char*)(gbase) + (voff)[_i]), (PG8_LAS unsigned*)(lds + (bufoff) + ldsw + _i * 8192), 16, 0, 0); } while (0)
; #define PG8_LDA(dst, b, h) do { _Pragma("unroll") for (int m = 0; m < 4; ++m) _Pragma("unroll") for (int k = 0; k < 2; ++k) dst[m][k] = *(const PG8_LAS bf16x8*)(lds + PG8_SA(b, h) + aoff + m * 2048 + k * 1024); } while (0)
; #define PG8_LDB(dst, b, h) do { _Pragma("unroll") for (int n = 0; n < 2; ++n) _Pragma("unroll") for (int k = 0; k < 2; ++k) dst[n][k] = *(const PG8_LAS bf16x8*)(lds + PG8_SB(b, h) + boff + n * 2048 + k * 1024); } while (0)
; #define PG8_WAIT_V(n) asm volatile("s_waitcnt vmcnt(" #n ")" ::: "memory")
; #define PG8_WAIT_L(n) asm volatile("s_waitcnt lgkmcnt(" #n ")" ::: "memory")
; #define PG8_BAR __builtin_amdgcn_s_barrier()
; #define PG8_SCHED __builtin_amdgcn_sched_barrier(0)
; template <class Epi, class Sched, bool ALIGN_EPI = false, bool SP2 = false>
; __device__ __forceinline__ void gemm_phase(PG8_LAS unsigned char* lds, const Gemm g, const Sched& S, const Epi& E) {
;     ...
;         const char* nA = has_next ? (const char*)g.A + (size_t)nxt.pm * tstep : cA; const char* nB = has_next ? (const char*)g.Bt + (size_t)nxt.pn * tstep : cB;
;         for (int t = 0; t < nt; t += 2) {
;             if constexpr (Epi::MID_HOOK) { if (t == Epi::MID_T) E.mid(acc, cur, wr, wc, fr, fq); }
;             const bool last = (t == nt - 2);
;             const char* a1 = cA + (size_t)(t + 1) * kstep;
;             const char* a2 = last ? nA : cA + (size_t)(t + 2) * kstep; const char* b2 = last ? nB : cB + (size_t)(t + 2) * kstep;
;             const char* a3 = a2 + kstep; const char* b3 = b2 + kstep;
;             if (last && has_next) S.a_ready(nxt);
;             if constexpr (SP2) {
;             PG8_LDB(B0, 0, 0); PG8_LDB(B1, 0, 1); PG8_SCHED; PG8_LDA(At, 0, 0); PG8_STAGE(PG8_SA(1, 1), a1 + hstep, voffA);
;             PG8_WAIT_V(8); PG8_WAIT_L(0); PG8_BAR; PG8_MMA(0, 0, At, B0); PG8_MMA(0, 1, At, B1); PG8_BAR; PG8_SCHED;
;             PG8_LDA(At, 0, 1); PG8_STAGE(PG8_SB(0, 0), b2, voffB); PG8_STAGE(PG8_SB(0, 1), b2 + hstep, voffB); PG8_STAGE(PG8_SA(0, 0), a2, voffA);
;             PG8_WAIT_V(8); PG8_WAIT_L(0); PG8_BAR; PG8_MMA(1, 0, At, B0); PG8_MMA(1, 1, At, B1); PG8_BAR; PG8_SCHED;
.LBB0_128:
	s_ashr_i32 s67, s66, 31
	s_lshl_b64 s[14:15], s[66:67], 20
	s_add_u32 s70, s37, s14
	s_addc_u32 s71, s38, s15
	s_and_b64 s[14:15], s[68:69], exec
	s_cselect_b32 s2, s71, s1
	s_cselect_b32 s11, s70, s0
	s_ashr_i32 s65, s64, 31
	s_lshl_b64 s[14:15], s[64:65], 20
	s_add_u32 s72, s31, s14
	s_addc_u32 s73, s36, s15
	s_and_b64 s[14:15], s[68:69], exec
	s_cselect_b32 s18, s73, s13
	s_cselect_b32 s19, s72, s12
	s_add_u32 s0, s0, 0x80080
	s_addc_u32 s1, s1, 0
	s_add_u32 s34, s12, 0x100
	s_addc_u32 s41, s13, 0
	s_mov_b32 s42, -2
	v_lshl_add_u64 v[194:195], s[0:1], 0, v[144:145]
	s_add_i32 m0, s74, 0xc000
	global_load_lds_dwordx4 v[194:195], off
	s_add_i32 m0, s74, 0xe000
	v_lshl_add_u64 v[194:195], s[0:1], 0, v[146:147]
	global_load_lds_dwordx4 v[194:195], off
	s_add_u32 s12, s0, 0xfff80080
	s_addc_u32 s13, s1, -1
	s_add_i32 s43, 0, 0x10000
	s_cmp_eq_u32 s42, 28
	s_cselect_b32 s15, s2, s13
	s_cselect_b32 s14, s11, s12
	s_cselect_b32 s13, s18, s41
	s_cselect_b32 s12, s19, s34
	s_add_i32 s65, 0, 0x14000
	s_waitcnt vmcnt(8)
	s_waitcnt lgkmcnt(0)
	s_barrier
	s_setprio 1
	s_waitcnt lgkmcnt(0)
	v_mfma_f32_16x16x32_bf16 v[124:127], v[128:131], v[172:175], 0
	v_mfma_f32_16x16x32_bf16 v[120:123], v[148:151], v[172:175], 0
	v_mfma_f32_16x16x32_bf16 v[108:111], v[128:131], v[184:187], 0
	v_mfma_f32_16x16x32_bf16 v[104:107], v[148:151], v[184:187], 0
	v_mfma_f32_16x16x32_bf16 v[92:95], v[128:131], v[206:209], 0
	v_mfma_f32_16x16x32_bf16 v[88:91], v[148:151], v[206:209], 0
	v_mfma_f32_16x16x32_bf16 v[76:79], v[128:131], v[214:217], 0
	v_mfma_f32_16x16x32_bf16 v[72:75], v[148:151], v[214:217], 0
	v_mfma_f32_16x16x32_bf16 v[124:127], v[132:135], v[180:183], v[124:127]
	v_mfma_f32_16x16x32_bf16 v[120:123], v[152:155], v[180:183], v[120:123]
	v_mfma_f32_16x16x32_bf16 v[108:111], v[132:135], v[188:191], v[108:111]
	v_mfma_f32_16x16x32_bf16 v[104:107], v[152:155], v[188:191], v[104:107]
	v_mfma_f32_16x16x32_bf16 v[92:95], v[132:135], v[210:213], v[92:95]
	v_mfma_f32_16x16x32_bf16 v[88:91], v[152:155], v[210:213], v[88:91]
	v_mfma_f32_16x16x32_bf16 v[76:79], v[132:135], v[218:221], v[76:79]
	v_mfma_f32_16x16x32_bf16 v[72:75], v[152:155], v[218:221], v[72:75]
	s_setprio 0
	s_setprio 1
	v_mfma_f32_16x16x32_bf16 v[116:119], v[156:159], v[172:175], 0
	v_mfma_f32_16x16x32_bf16 v[112:115], v[164:167], v[172:175], 0
	v_mfma_f32_16x16x32_bf16 v[100:103], v[156:159], v[184:187], 0
	v_mfma_f32_16x16x32_bf16 v[96:99], v[164:167], v[184:187], 0
	v_mfma_f32_16x16x32_bf16 v[84:87], v[156:159], v[206:209], 0
	v_mfma_f32_16x16x32_bf16 v[80:83], v[164:167], v[206:209], 0
	v_mfma_f32_16x16x32_bf16 v[68:71], v[156:159], v[214:217], 0
	v_mfma_f32_16x16x32_bf16 v[64:67], v[164:167], v[214:217], 0
	v_mfma_f32_16x16x32_bf16 v[116:119], v[160:163], v[180:183], v[116:119]
	v_mfma_f32_16x16x32_bf16 v[112:115], v[168:171], v[180:183], v[112:115]
	v_mfma_f32_16x16x32_bf16 v[100:103], v[160:163], v[188:191], v[100:103]
	v_mfma_f32_16x16x32_bf16 v[96:99], v[168:171], v[188:191], v[96:99]
	v_mfma_f32_16x16x32_bf16 v[84:87], v[160:163], v[210:213], v[84:87]
	v_mfma_f32_16x16x32_bf16 v[80:83], v[168:171], v[210:213], v[80:83]
	s_barrier
	s_setprio 2
	v_mfma_f32_16x16x32_bf16 v[68:71], v[160:163], v[218:221], v[68:71]
	v_mfma_f32_16x16x32_bf16 v[64:67], v[168:171], v[218:221], v[64:67]
	s_setprio 0
	s_add_i32 s43, s43, s39
	v_lshl_add_u64 v[194:195], s[12:13], 0, v[138:139]
	s_mov_b32 m0, s43
	ds_read_b128 v[172:175], v179 offset:16384
	ds_read_b128 v[180:183], v179 offset:17408
	ds_read_b128 v[184:187], v179 offset:18432
	ds_read_b128 v[188:191], v179 offset:19456
	ds_read_b128 v[206:209], v179 offset:20480
	ds_read_b128 v[210:213], v179 offset:21504
	ds_read_b128 v[214:217], v179 offset:22528
	ds_read_b128 v[218:221], v179 offset:23552
	global_load_lds_dwordx4 v[194:195], off
	s_add_i32 m0, s43, 0x2000
	s_add_u32 s86, s12, 0x80000
	v_lshl_add_u64 v[196:197], s[12:13], 0, v[142:143]
	s_addc_u32 s87, s13, 0
	s_add_i32 s43, s65, s39
	global_load_lds_dwordx4 v[196:197], off
	v_lshl_add_u64 v[202:203], s[86:87], 0, v[138:139]
	s_mov_b32 m0, s43
	v_lshl_add_u64 v[204:205], s[14:15], 0, v[140:141]
	global_load_lds_dwordx4 v[202:203], off
	s_add_i32 m0, s43, 0x2000
	v_lshl_add_u64 v[202:203], s[86:87], 0, v[142:143]
	global_load_lds_dwordx4 v[202:203], off
	s_mov_b32 m0, s74
	v_lshl_add_u64 v[202:203], s[14:15], 0, v[136:137]
	global_load_lds_dwordx4 v[202:203], off
	s_mov_b32 m0, s75
	s_nop 0
	global_load_lds_dwordx4 v[204:205], off
	s_waitcnt vmcnt(8)
	s_waitcnt lgkmcnt(0)
	s_barrier
	s_setprio 1
	s_waitcnt lgkmcnt(0)
	v_mfma_f32_16x16x32_bf16 v[60:63], v[128:131], v[172:175], 0
	v_mfma_f32_16x16x32_bf16 v[56:59], v[148:151], v[172:175], 0
	v_mfma_f32_16x16x32_bf16 v[44:47], v[128:131], v[184:187], 0
	v_mfma_f32_16x16x32_bf16 v[40:43], v[148:151], v[184:187], 0
	v_mfma_f32_16x16x32_bf16 v[28:31], v[128:131], v[206:209], 0
	v_mfma_f32_16x16x32_bf16 v[24:27], v[148:151], v[206:209], 0
	v_mfma_f32_16x16x32_bf16 v[12:15], v[128:131], v[214:217], 0
	v_mfma_f32_16x16x32_bf16 v[8:11], v[148:151], v[214:217], 0
	v_mfma_f32_16x16x32_bf16 v[60:63], v[132:135], v[180:183], v[60:63]
	v_mfma_f32_16x16x32_bf16 v[56:59], v[152:155], v[180:183], v[56:59]
	v_mfma_f32_16x16x32_bf16 v[44:47], v[132:135], v[188:191], v[44:47]
	v_mfma_f32_16x16x32_bf16 v[40:43], v[152:155], v[188:191], v[40:43]
	v_mfma_f32_16x16x32_bf16 v[28:31], v[132:135], v[210:213], v[28:31]
	v_mfma_f32_16x16x32_bf16 v[24:27], v[152:155], v[210:213], v[24:27]
	v_mfma_f32_16x16x32_bf16 v[12:15], v[132:135], v[218:221], v[12:15]
	v_mfma_f32_16x16x32_bf16 v[8:11], v[152:155], v[218:221], v[8:11]
	s_setprio 0
	s_setprio 1
	v_mfma_f32_16x16x32_bf16 v[52:55], v[156:159], v[172:175], 0
	v_mfma_f32_16x16x32_bf16 v[48:51], v[164:167], v[172:175], 0
	v_mfma_f32_16x16x32_bf16 v[36:39], v[156:159], v[184:187], 0
	v_mfma_f32_16x16x32_bf16 v[32:35], v[164:167], v[184:187], 0
	v_mfma_f32_16x16x32_bf16 v[20:23], v[156:159], v[206:209], 0
	v_mfma_f32_16x16x32_bf16 v[16:19], v[164:167], v[206:209], 0
	v_mfma_f32_16x16x32_bf16 v[4:7], v[156:159], v[214:217], 0
	v_mfma_f32_16x16x32_bf16 v[0:3], v[164:167], v[214:217], 0
	v_mfma_f32_16x16x32_bf16 v[52:55], v[160:163], v[180:183], v[52:55]
	v_mfma_f32_16x16x32_bf16 v[48:51], v[168:171], v[180:183], v[48:51]
	v_mfma_f32_16x16x32_bf16 v[36:39], v[160:163], v[188:191], v[36:39]
	v_mfma_f32_16x16x32_bf16 v[32:35], v[168:171], v[188:191], v[32:35]
	v_mfma_f32_16x16x32_bf16 v[20:23], v[160:163], v[210:213], v[20:23]
	v_mfma_f32_16x16x32_bf16 v[16:19], v[168:171], v[210:213], v[16:19]
	s_barrier
; #define PG8_STAGE(bufoff, gbase, voff) do { _Pragma("unroll") for (int _i = 0; _i < 2; ++_i) \
;         __builtin_amdgcn_global_load_lds((const unsigned*)((const char*)(gbase) + (voff)[_i]), (PG8_LAS unsigned*)(lds + (bufoff) + ldsw + _i * 8192), 16, 0, 0); } while (0)
; #define PG8_LDA(dst, b, h) do { _Pragma("unroll") for (int m = 0; m < 4; ++m) _Pragma("unroll") for (int k = 0; k < 2; ++k) dst[m][k] = *(const PG8_LAS bf16x8*)(lds + PG8_SA(b, h) + aoff + m * 2048 + k * 1024); } while (0)
; #define PG8_LDB(dst, b, h) do { _Pragma("unroll") for (int n = 0; n < 2; ++n) _Pragma("unroll") for (int k = 0; k < 2; ++k) dst[n][k] = *(const PG8_LAS bf16x8*)(lds + PG8_SB(b, h) + boff + n * 2048 + k * 1024); } while (0)
; #define PG8_MMA(ai, bj, At, Bt) do { __builtin_amdgcn_s_setprio(1); _Pragma("unroll") for (int m = 0; m < 4; ++m) _Pragma("unroll") for (int n = 0; n < 2; ++n) _Pragma("unroll") for (int k = 0; k < 2; ++k) \
;         acc[ai][bj][m][n] = __builtin_amdgcn_mfma_f32_16x16x32_bf16(Bt[n][k], At[m][k], acc[ai][bj][m][n], 0, 0, 0); __builtin_amdgcn_s_setprio(0); } while (0)
; #define PG8_WAIT_V(n) asm volatile("s_waitcnt vmcnt(" #n ")" ::: "memory")
; #define PG8_WAIT_L(n) asm volatile("s_waitcnt lgkmcnt(" #n ")" ::: "memory")
; #define PG8_BAR __builtin_amdgcn_s_barrier()
; #define PG8_SCHED __builtin_amdgcn_sched_barrier(0)
; template <class Epi, class Sched, bool ALIGN_EPI = false, bool SP2 = false>
; __device__ __forceinline__ void gemm_phase(PG8_LAS unsigned char* lds, const Gemm g, const Sched& S, const Epi& E) {
;     ...
;             PG8_WAIT_V(8); PG8_WAIT_L(0); PG8_BAR; PG8_MMA(1, 0, At, B0); PG8_MMA(1, 1, At, B1); PG8_BAR; PG8_SCHED;
;             PG8_LDB(B0, 1, 0); PG8_LDB(B1, 1, 1); PG8_SCHED; PG8_LDA(At, 1, 0); PG8_STAGE(PG8_SA(0, 1), a2 + hstep, voffA);
;             PG8_WAIT_V(8); PG8_WAIT_L(0); PG8_BAR; PG8_MMA(0, 0, At, B0); PG8_MMA(0, 1, At, B1); PG8_BAR; PG8_SCHED;
;             PG8_LDA(At, 1, 1); PG8_STAGE(PG8_SB(1, 0), b3, voffB); PG8_STAGE(PG8_SB(1, 1), b3 + hstep, voffB); PG8_STAGE(PG8_SA(1, 0), a3, voffA);
	s_setprio 2
	v_mfma_f32_16x16x32_bf16 v[4:7], v[160:163], v[218:221], v[4:7]
	v_mfma_f32_16x16x32_bf16 v[0:3], v[168:171], v[218:221], v[0:3]
	s_setprio 0
	s_add_i32 s43, 0, 0x18000
	s_add_i32 s65, 0, 0x1c000
	v_add_u32_e32 v152, 0x18000, v178
	v_add_u32_e32 v168, 0x1c000, v178
	ds_read_b128 v[128:131], v152
	ds_read_b128 v[132:135], v152 offset:1024
	ds_read_b128 v[148:151], v152 offset:2048
	ds_read_b128 v[152:155], v152 offset:3072
	ds_read_b128 v[156:159], v168
	ds_read_b128 v[160:163], v168 offset:1024
	ds_read_b128 v[164:167], v168 offset:2048
	ds_read_b128 v[168:171], v168 offset:3072
	s_add_u32 s14, s14, 0x80000
	s_addc_u32 s15, s15, 0
	s_mov_b32 m0, s76
	v_lshl_add_u64 v[232:233], s[14:15], 0, v[136:137]
	ds_read_b128 v[172:175], v179 offset:32768
	ds_read_b128 v[180:183], v179 offset:33792
	ds_read_b128 v[184:187], v179 offset:34816
	ds_read_b128 v[188:191], v179 offset:35840
	ds_read_b128 v[206:209], v179 offset:36864
	ds_read_b128 v[210:213], v179 offset:37888
	ds_read_b128 v[214:217], v179 offset:38912
	ds_read_b128 v[218:221], v179 offset:39936
	global_load_lds_dwordx4 v[232:233], off
	s_mov_b32 m0, s77
	v_lshl_add_u64 v[232:233], s[14:15], 0, v[140:141]
	global_load_lds_dwordx4 v[232:233], off
	s_waitcnt vmcnt(8)
	s_waitcnt lgkmcnt(0)
	s_barrier
	s_setprio 1
	s_waitcnt lgkmcnt(0)
	v_mfma_f32_16x16x32_bf16 v[124:127], v[128:131], v[172:175], v[124:127]
	v_mfma_f32_16x16x32_bf16 v[120:123], v[148:151], v[172:175], v[120:123]
	v_mfma_f32_16x16x32_bf16 v[108:111], v[128:131], v[184:187], v[108:111]
	v_mfma_f32_16x16x32_bf16 v[104:107], v[148:151], v[184:187], v[104:107]
	v_mfma_f32_16x16x32_bf16 v[92:95], v[128:131], v[206:209], v[92:95]
	v_mfma_f32_16x16x32_bf16 v[88:91], v[148:151], v[206:209], v[88:91]
	v_mfma_f32_16x16x32_bf16 v[76:79], v[128:131], v[214:217], v[76:79]
	v_mfma_f32_16x16x32_bf16 v[72:75], v[148:151], v[214:217], v[72:75]
	v_mfma_f32_16x16x32_bf16 v[124:127], v[132:135], v[180:183], v[124:127]
	v_mfma_f32_16x16x32_bf16 v[120:123], v[152:155], v[180:183], v[120:123]
	v_mfma_f32_16x16x32_bf16 v[108:111], v[132:135], v[188:191], v[108:111]
	v_mfma_f32_16x16x32_bf16 v[104:107], v[152:155], v[188:191], v[104:107]
	v_mfma_f32_16x16x32_bf16 v[92:95], v[132:135], v[210:213], v[92:95]
	v_mfma_f32_16x16x32_bf16 v[88:91], v[152:155], v[210:213], v[88:91]
	v_mfma_f32_16x16x32_bf16 v[76:79], v[132:135], v[218:221], v[76:79]
	v_mfma_f32_16x16x32_bf16 v[72:75], v[152:155], v[218:221], v[72:75]
	s_setprio 0
	s_setprio 1
	v_mfma_f32_16x16x32_bf16 v[116:119], v[156:159], v[172:175], v[116:119]
	v_mfma_f32_16x16x32_bf16 v[112:115], v[164:167], v[172:175], v[112:115]
	v_mfma_f32_16x16x32_bf16 v[100:103], v[156:159], v[184:187], v[100:103]
	v_mfma_f32_16x16x32_bf16 v[96:99], v[164:167], v[184:187], v[96:99]
	v_mfma_f32_16x16x32_bf16 v[84:87], v[156:159], v[206:209], v[84:87]
	v_mfma_f32_16x16x32_bf16 v[80:83], v[164:167], v[206:209], v[80:83]
	v_mfma_f32_16x16x32_bf16 v[68:71], v[156:159], v[214:217], v[68:71]
	v_mfma_f32_16x16x32_bf16 v[64:67], v[164:167], v[214:217], v[64:67]
	v_mfma_f32_16x16x32_bf16 v[116:119], v[160:163], v[180:183], v[116:119]
	v_mfma_f32_16x16x32_bf16 v[112:115], v[168:171], v[180:183], v[112:115]
	v_mfma_f32_16x16x32_bf16 v[100:103], v[160:163], v[188:191], v[100:103]
	v_mfma_f32_16x16x32_bf16 v[96:99], v[168:171], v[188:191], v[96:99]
	v_mfma_f32_16x16x32_bf16 v[84:87], v[160:163], v[210:213], v[84:87]
	v_mfma_f32_16x16x32_bf16 v[80:83], v[168:171], v[210:213], v[80:83]
	s_barrier
	s_setprio 2
	v_mfma_f32_16x16x32_bf16 v[68:71], v[160:163], v[218:221], v[68:71]
	v_mfma_f32_16x16x32_bf16 v[64:67], v[168:171], v[218:221], v[64:67]
	s_setprio 0
	s_add_i32 s14, s43, s39
	v_lshl_add_u64 v[194:195], v[194:195], 0, s[16:17]
	s_mov_b32 m0, s14
	ds_read_b128 v[172:175], v179 offset:49152
	ds_read_b128 v[180:183], v179 offset:50176
	ds_read_b128 v[184:187], v179 offset:51200
	ds_read_b128 v[188:191], v179 offset:52224
	ds_read_b128 v[206:209], v179 offset:53248
	ds_read_b128 v[210:213], v179 offset:54272
	ds_read_b128 v[214:217], v179 offset:55296
	ds_read_b128 v[218:221], v179 offset:56320
	global_load_lds_dwordx4 v[194:195], off
	s_add_i32 m0, s14, 0x2000
	s_add_u32 s12, s12, 0x80080
	v_lshl_add_u64 v[194:195], v[196:197], 0, s[16:17]
	s_addc_u32 s13, s13, 0
	s_add_i32 s14, s65, s39
	global_load_lds_dwordx4 v[194:195], off
	s_mov_b32 m0, s14
	v_lshl_add_u64 v[194:195], s[12:13], 0, v[138:139]
	global_load_lds_dwordx4 v[194:195], off
	s_add_i32 m0, s14, 0x2000
	v_lshl_add_u64 v[194:195], s[12:13], 0, v[142:143]
	global_load_lds_dwordx4 v[194:195], off
	s_mov_b32 m0, s80
	v_lshl_add_u64 v[194:195], v[202:203], 0, s[16:17]
	global_load_lds_dwordx4 v[194:195], off
	s_mov_b32 m0, s81
	v_lshl_add_u64 v[194:195], v[204:205], 0, s[16:17]
	global_load_lds_dwordx4 v[194:195], off
	s_waitcnt vmcnt(8)
	s_waitcnt lgkmcnt(0)
	s_barrier
; #define PG8_STAGE(bufoff, gbase, voff) do { _Pragma("unroll") for (int _i = 0; _i < 2; ++_i) \
;         __builtin_amdgcn_global_load_lds((const unsigned*)((const char*)(gbase) + (voff)[_i]), (PG8_LAS unsigned*)(lds + (bufoff) + ldsw + _i * 8192), 16, 0, 0); } while (0)
; #define PG8_LDA(dst, b, h) do { _Pragma("unroll") for (int m = 0; m < 4; ++m) _Pragma("unroll") for (int k = 0; k < 2; ++k) dst[m][k] = *(const PG8_LAS bf16x8*)(lds + PG8_SA(b, h) + aoff + m * 2048 + k * 1024); } while (0)
; #define PG8_LDB(dst, b, h) do { _Pragma("unroll") for (int n = 0; n < 2; ++n) _Pragma("unroll") for (int k = 0; k < 2; ++k) dst[n][k] = *(const PG8_LAS bf16x8*)(lds + PG8_SB(b, h) + boff + n * 2048 + k * 1024); } while (0)
; #define PG8_MMA(ai, bj, At, Bt) do { __builtin_amdgcn_s_setprio(1); _Pragma("unroll") for (int m = 0; m < 4; ++m) _Pragma("unroll") for (int n = 0; n < 2; ++n) _Pragma("unroll") for (int k = 0; k < 2; ++k) \
;         acc[ai][bj][m][n] = __builtin_amdgcn_mfma_f32_16x16x32_bf16(Bt[n][k], At[m][k], acc[ai][bj][m][n], 0, 0, 0); __builtin_amdgcn_s_setprio(0); } while (0)
; #define PG8_WAIT_V(n) asm volatile("s_waitcnt vmcnt(" #n ")" ::: "memory")
; template <class Epi, class Sched, bool ALIGN_EPI = false, bool SP2 = false>
; __device__ __forceinline__ void gemm_phase(PG8_LAS unsigned char* lds, const Gemm g, const Sched& S, const Epi& E) {
;     ...
;             PG8_LDB(B0, 0, 0); PG8_LDB(B1, 0, 1); PG8_SCHED; PG8_LDA(At, 0, 0); PG8_STAGE(PG8_SA(1, 1), a1 + hstep, voffA);
;             PG8_WAIT_V(8); PG8_WAIT_L(0); PG8_BAR; PG8_MMA(0, 0, At, B0); PG8_MMA(0, 1, At, B1); PG8_BAR; PG8_SCHED;
;             PG8_LDA(At, 0, 1); PG8_STAGE(PG8_SB(0, 0), b2, voffB); PG8_STAGE(PG8_SB(0, 1), b2 + hstep, voffB); PG8_STAGE(PG8_SA(0, 0), a2, voffA);
;             PG8_WAIT_V(8); PG8_WAIT_L(0); PG8_BAR; PG8_MMA(1, 0, At, B0); PG8_MMA(1, 1, At, B1); PG8_BAR; PG8_SCHED;
;             PG8_LDB(B0, 1, 0); PG8_LDB(B1, 1, 1); PG8_SCHED; PG8_LDA(At, 1, 0); PG8_STAGE(PG8_SA(0, 1), a2 + hstep, voffA);
;             PG8_WAIT_V(8); PG8_WAIT_L(0); PG8_BAR; PG8_MMA(0, 0, At, B0); PG8_MMA(0, 1, At, B1); PG8_BAR; PG8_SCHED;
;             PG8_LDA(At, 1, 1); PG8_STAGE(PG8_SB(1, 0), b3, voffB); PG8_STAGE(PG8_SB(1, 1), b3 + hstep, voffB); PG8_STAGE(PG8_SA(1, 0), a3, voffA);
;             PG8_WAIT_V(8); PG8_WAIT_L(0); PG8_BAR; PG8_MMA(1, 0, At, B0); PG8_MMA(1, 1, At, B1); PG8_BAR; PG8_SCHED;
	s_setprio 1
	s_waitcnt lgkmcnt(0)
	v_mfma_f32_16x16x32_bf16 v[60:63], v[128:131], v[172:175], v[60:63]
	v_mfma_f32_16x16x32_bf16 v[56:59], v[148:151], v[172:175], v[56:59]
	v_mfma_f32_16x16x32_bf16 v[44:47], v[128:131], v[184:187], v[44:47]
	v_mfma_f32_16x16x32_bf16 v[40:43], v[148:151], v[184:187], v[40:43]
	v_mfma_f32_16x16x32_bf16 v[28:31], v[128:131], v[206:209], v[28:31]
	v_mfma_f32_16x16x32_bf16 v[24:27], v[148:151], v[206:209], v[24:27]
	v_mfma_f32_16x16x32_bf16 v[12:15], v[128:131], v[214:217], v[12:15]
	v_mfma_f32_16x16x32_bf16 v[8:11], v[148:151], v[214:217], v[8:11]
	v_mfma_f32_16x16x32_bf16 v[60:63], v[132:135], v[180:183], v[60:63]
	v_mfma_f32_16x16x32_bf16 v[56:59], v[152:155], v[180:183], v[56:59]
	v_mfma_f32_16x16x32_bf16 v[44:47], v[132:135], v[188:191], v[44:47]
	v_mfma_f32_16x16x32_bf16 v[40:43], v[152:155], v[188:191], v[40:43]
	v_mfma_f32_16x16x32_bf16 v[28:31], v[132:135], v[210:213], v[28:31]
	v_mfma_f32_16x16x32_bf16 v[24:27], v[152:155], v[210:213], v[24:27]
	v_mfma_f32_16x16x32_bf16 v[12:15], v[132:135], v[218:221], v[12:15]
	v_mfma_f32_16x16x32_bf16 v[8:11], v[152:155], v[218:221], v[8:11]
	s_setprio 0
	s_setprio 1
	v_mfma_f32_16x16x32_bf16 v[52:55], v[156:159], v[172:175], v[52:55]
	v_mfma_f32_16x16x32_bf16 v[48:51], v[164:167], v[172:175], v[48:51]
	v_mfma_f32_16x16x32_bf16 v[36:39], v[156:159], v[184:187], v[36:39]
	v_mfma_f32_16x16x32_bf16 v[32:35], v[164:167], v[184:187], v[32:35]
	v_mfma_f32_16x16x32_bf16 v[20:23], v[156:159], v[206:209], v[20:23]
	v_mfma_f32_16x16x32_bf16 v[16:19], v[164:167], v[206:209], v[16:19]
	v_mfma_f32_16x16x32_bf16 v[4:7], v[156:159], v[214:217], v[4:7]
	v_mfma_f32_16x16x32_bf16 v[0:3], v[164:167], v[214:217], v[0:3]
	v_mfma_f32_16x16x32_bf16 v[52:55], v[160:163], v[180:183], v[52:55]
	v_mfma_f32_16x16x32_bf16 v[48:51], v[168:171], v[180:183], v[48:51]
	v_mfma_f32_16x16x32_bf16 v[36:39], v[160:163], v[188:191], v[36:39]
	v_mfma_f32_16x16x32_bf16 v[32:35], v[168:171], v[188:191], v[32:35]
	v_mfma_f32_16x16x32_bf16 v[20:23], v[160:163], v[210:213], v[20:23]
	v_mfma_f32_16x16x32_bf16 v[16:19], v[168:171], v[210:213], v[16:19]
	s_barrier
	s_setprio 2
	v_mfma_f32_16x16x32_bf16 v[4:7], v[160:163], v[218:221], v[4:7]
	v_mfma_f32_16x16x32_bf16 v[0:3], v[168:171], v[218:221], v[0:3]
	s_setprio 0
	s_add_i32 s42, s42, 2
	s_add_u32 s0, s0, 0x100
	s_addc_u32 s1, s1, 0
	s_add_u32 s34, s34, 0x100
	s_addc_u32 s41, s41, 0
	s_cmp_gt_u32 s42, 29
	s_branch .LBB0_129
.LBB0_129:
	v_add_u32_e32 v152, 0x10000, v178
	v_add_u32_e32 v168, 0x14000, v178
	ds_read_b128 v[128:131], v152
	ds_read_b128 v[132:135], v152 offset:1024
	ds_read_b128 v[148:151], v152 offset:2048
	ds_read_b128 v[152:155], v152 offset:3072
	ds_read_b128 v[156:159], v168
	ds_read_b128 v[160:163], v168 offset:1024
	ds_read_b128 v[164:167], v168 offset:2048
	ds_read_b128 v[168:171], v168 offset:3072
	v_lshl_add_u64 v[194:195], s[0:1], 0, v[144:145]
	s_add_i32 m0, s74, 0xc000
	ds_read_b128 v[172:175], v179
	ds_read_b128 v[180:183], v179 offset:1024
	ds_read_b128 v[184:187], v179 offset:2048
	ds_read_b128 v[188:191], v179 offset:3072
	ds_read_b128 v[206:209], v179 offset:4096
	ds_read_b128 v[210:213], v179 offset:5120
	ds_read_b128 v[214:217], v179 offset:6144
	ds_read_b128 v[218:221], v179 offset:7168
	global_load_lds_dwordx4 v[194:195], off
	s_add_i32 m0, s74, 0xe000
	v_lshl_add_u64 v[194:195], s[0:1], 0, v[146:147]
	global_load_lds_dwordx4 v[194:195], off
	s_add_u32 s12, s0, 0xfff80080
	s_addc_u32 s13, s1, -1
	s_add_i32 s43, 0, 0x10000
	s_cmp_eq_u32 s42, 28
	s_cselect_b32 s15, s2, s13
	s_cselect_b32 s14, s11, s12
	s_cselect_b32 s13, s18, s41
	s_cselect_b32 s12, s19, s34
	s_add_i32 s65, 0, 0x14000
	s_waitcnt vmcnt(8)
	s_waitcnt lgkmcnt(0)
	s_barrier
	s_setprio 1
	s_waitcnt lgkmcnt(0)
	v_mfma_f32_16x16x32_bf16 v[124:127], v[128:131], v[172:175], v[124:127]
	v_mfma_f32_16x16x32_bf16 v[120:123], v[148:151], v[172:175], v[120:123]
	v_mfma_f32_16x16x32_bf16 v[108:111], v[128:131], v[184:187], v[108:111]
	v_mfma_f32_16x16x32_bf16 v[104:107], v[148:151], v[184:187], v[104:107]
	v_mfma_f32_16x16x32_bf16 v[92:95], v[128:131], v[206:209], v[92:95]
	v_mfma_f32_16x16x32_bf16 v[88:91], v[148:151], v[206:209], v[88:91]
	v_mfma_f32_16x16x32_bf16 v[76:79], v[128:131], v[214:217], v[76:79]
	v_mfma_f32_16x16x32_bf16 v[72:75], v[148:151], v[214:217], v[72:75]
	v_mfma_f32_16x16x32_bf16 v[124:127], v[132:135], v[180:183], v[124:127]
	v_mfma_f32_16x16x32_bf16 v[120:123], v[152:155], v[180:183], v[120:123]
	v_mfma_f32_16x16x32_bf16 v[108:111], v[132:135], v[188:191], v[108:111]
	v_mfma_f32_16x16x32_bf16 v[104:107], v[152:155], v[188:191], v[104:107]
	v_mfma_f32_16x16x32_bf16 v[92:95], v[132:135], v[210:213], v[92:95]
	v_mfma_f32_16x16x32_bf16 v[88:91], v[152:155], v[210:213], v[88:91]
	v_mfma_f32_16x16x32_bf16 v[76:79], v[132:135], v[218:221], v[76:79]
	v_mfma_f32_16x16x32_bf16 v[72:75], v[152:155], v[218:221], v[72:75]
	s_setprio 0
	s_setprio 1
	v_mfma_f32_16x16x32_bf16 v[116:119], v[156:159], v[172:175], v[116:119]
	v_mfma_f32_16x16x32_bf16 v[112:115], v[164:167], v[172:175], v[112:115]
	v_mfma_f32_16x16x32_bf16 v[100:103], v[156:159], v[184:187], v[100:103]
	v_mfma_f32_16x16x32_bf16 v[96:99], v[164:167], v[184:187], v[96:99]
	v_mfma_f32_16x16x32_bf16 v[84:87], v[156:159], v[206:209], v[84:87]
	v_mfma_f32_16x16x32_bf16 v[80:83], v[164:167], v[206:209], v[80:83]
	v_mfma_f32_16x16x32_bf16 v[68:71], v[156:159], v[214:217], v[68:71]
	v_mfma_f32_16x16x32_bf16 v[64:67], v[164:167], v[214:217], v[64:67]
	v_mfma_f32_16x16x32_bf16 v[116:119], v[160:163], v[180:183], v[116:119]
	v_mfma_f32_16x16x32_bf16 v[112:115], v[168:171], v[180:183], v[112:115]
	v_mfma_f32_16x16x32_bf16 v[100:103], v[160:163], v[188:191], v[100:103]
	v_mfma_f32_16x16x32_bf16 v[96:99], v[168:171], v[188:191], v[96:99]
	v_mfma_f32_16x16x32_bf16 v[84:87], v[160:163], v[210:213], v[84:87]
	v_mfma_f32_16x16x32_bf16 v[80:83], v[168:171], v[210:213], v[80:83]
	s_barrier
; #define PG8_STAGE(bufoff, gbase, voff) do { _Pragma("unroll") for (int _i = 0; _i < 2; ++_i) \
;         __builtin_amdgcn_global_load_lds((const unsigned*)((const char*)(gbase) + (voff)[_i]), (PG8_LAS unsigned*)(lds + (bufoff) + ldsw + _i * 8192), 16, 0, 0); } while (0)
; #define PG8_LDA(dst, b, h) do { _Pragma("unroll") for (int m = 0; m < 4; ++m) _Pragma("unroll") for (int k = 0; k < 2; ++k) dst[m][k] = *(const PG8_LAS bf16x8*)(lds + PG8_SA(b, h) + aoff + m * 2048 + k * 1024); } while (0)
; #define PG8_LDB(dst, b, h) do { _Pragma("unroll") for (int n = 0; n < 2; ++n) _Pragma("unroll") for (int k = 0; k < 2; ++k) dst[n][k] = *(const PG8_LAS bf16x8*)(lds + PG8_SB(b, h) + boff + n * 2048 + k * 1024); } while (0)
; #define PG8_MMA(ai, bj, At, Bt) do { __builtin_amdgcn_s_setprio(1); _Pragma("unroll") for (int m = 0; m < 4; ++m) _Pragma("unroll") for (int n = 0; n < 2; ++n) _Pragma("unroll") for (int k = 0; k < 2; ++k) \
;         acc[ai][bj][m][n] = __builtin_amdgcn_mfma_f32_16x16x32_bf16(Bt[n][k], At[m][k], acc[ai][bj][m][n], 0, 0, 0); __builtin_amdgcn_s_setprio(0); } while (0)
; #define PG8_WAIT_V(n) asm volatile("s_waitcnt vmcnt(" #n ")" ::: "memory")
; #define PG8_WAIT_L(n) asm volatile("s_waitcnt lgkmcnt(" #n ")" ::: "memory")
; #define PG8_BAR __builtin_amdgcn_s_barrier()
; #define PG8_SCHED __builtin_amdgcn_sched_barrier(0)
; template <class Epi, class Sched, bool ALIGN_EPI = false, bool SP2 = false>
; __device__ __forceinline__ void gemm_phase(PG8_LAS unsigned char* lds, const Gemm g, const Sched& S, const Epi& E) {
;     ...
;             PG8_WAIT_V(8); PG8_WAIT_L(0); PG8_BAR; PG8_MMA(0, 0, At, B0); PG8_MMA(0, 1, At, B1); PG8_BAR; PG8_SCHED;
;             PG8_LDA(At, 0, 1); PG8_STAGE(PG8_SB(0, 0), b2, voffB); PG8_STAGE(PG8_SB(0, 1), b2 + hstep, voffB); PG8_STAGE(PG8_SA(0, 0), a2, voffA);
;             PG8_WAIT_V(8); PG8_WAIT_L(0); PG8_BAR; PG8_MMA(1, 0, At, B0); PG8_MMA(1, 1, At, B1); PG8_BAR; PG8_SCHED;
;             PG8_LDB(B0, 1, 0); PG8_LDB(B1, 1, 1); PG8_SCHED; PG8_LDA(At, 1, 0); PG8_STAGE(PG8_SA(0, 1), a2 + hstep, voffA);
	s_setprio 2
	v_mfma_f32_16x16x32_bf16 v[68:71], v[160:163], v[218:221], v[68:71]
	v_mfma_f32_16x16x32_bf16 v[64:67], v[168:171], v[218:221], v[64:67]
	s_setprio 0
	s_add_i32 s43, s43, s39
	v_lshl_add_u64 v[194:195], s[12:13], 0, v[138:139]
	s_mov_b32 m0, s43
	ds_read_b128 v[172:175], v179 offset:16384
	ds_read_b128 v[180:183], v179 offset:17408
	ds_read_b128 v[184:187], v179 offset:18432
	ds_read_b128 v[188:191], v179 offset:19456
	ds_read_b128 v[206:209], v179 offset:20480
	ds_read_b128 v[210:213], v179 offset:21504
	ds_read_b128 v[214:217], v179 offset:22528
	ds_read_b128 v[218:221], v179 offset:23552
	global_load_lds_dwordx4 v[194:195], off
	s_add_i32 m0, s43, 0x2000
	s_add_u32 s86, s12, 0x80000
	v_lshl_add_u64 v[196:197], s[12:13], 0, v[142:143]
	s_addc_u32 s87, s13, 0
	s_add_i32 s43, s65, s39
	global_load_lds_dwordx4 v[196:197], off
	v_lshl_add_u64 v[202:203], s[86:87], 0, v[138:139]
	s_mov_b32 m0, s43
	v_lshl_add_u64 v[204:205], s[14:15], 0, v[140:141]
	global_load_lds_dwordx4 v[202:203], off
	s_add_i32 m0, s43, 0x2000
	v_lshl_add_u64 v[202:203], s[86:87], 0, v[142:143]
	global_load_lds_dwordx4 v[202:203], off
	s_mov_b32 m0, s74
	v_lshl_add_u64 v[202:203], s[14:15], 0, v[136:137]
	global_load_lds_dwordx4 v[202:203], off
	s_mov_b32 m0, s75
	s_nop 0
	global_load_lds_dwordx4 v[204:205], off
	s_waitcnt vmcnt(8)
	s_waitcnt lgkmcnt(0)
	s_barrier
	s_setprio 1
	s_waitcnt lgkmcnt(0)
	v_mfma_f32_16x16x32_bf16 v[60:63], v[128:131], v[172:175], v[60:63]
	v_mfma_f32_16x16x32_bf16 v[56:59], v[148:151], v[172:175], v[56:59]
	v_mfma_f32_16x16x32_bf16 v[44:47], v[128:131], v[184:187], v[44:47]
	v_mfma_f32_16x16x32_bf16 v[40:43], v[148:151], v[184:187], v[40:43]
	v_mfma_f32_16x16x32_bf16 v[28:31], v[128:131], v[206:209], v[28:31]
	v_mfma_f32_16x16x32_bf16 v[24:27], v[148:151], v[206:209], v[24:27]
	v_mfma_f32_16x16x32_bf16 v[12:15], v[128:131], v[214:217], v[12:15]
	v_mfma_f32_16x16x32_bf16 v[8:11], v[148:151], v[214:217], v[8:11]
	v_mfma_f32_16x16x32_bf16 v[60:63], v[132:135], v[180:183], v[60:63]
	v_mfma_f32_16x16x32_bf16 v[56:59], v[152:155], v[180:183], v[56:59]
	v_mfma_f32_16x16x32_bf16 v[44:47], v[132:135], v[188:191], v[44:47]
	v_mfma_f32_16x16x32_bf16 v[40:43], v[152:155], v[188:191], v[40:43]
	v_mfma_f32_16x16x32_bf16 v[28:31], v[132:135], v[210:213], v[28:31]
	v_mfma_f32_16x16x32_bf16 v[24:27], v[152:155], v[210:213], v[24:27]
	v_mfma_f32_16x16x32_bf16 v[12:15], v[132:135], v[218:221], v[12:15]
	v_mfma_f32_16x16x32_bf16 v[8:11], v[152:155], v[218:221], v[8:11]
	s_setprio 0
	s_setprio 1
	v_mfma_f32_16x16x32_bf16 v[52:55], v[156:159], v[172:175], v[52:55]
	v_mfma_f32_16x16x32_bf16 v[48:51], v[164:167], v[172:175], v[48:51]
	v_mfma_f32_16x16x32_bf16 v[36:39], v[156:159], v[184:187], v[36:39]
	v_mfma_f32_16x16x32_bf16 v[32:35], v[164:167], v[184:187], v[32:35]
	v_mfma_f32_16x16x32_bf16 v[20:23], v[156:159], v[206:209], v[20:23]
	v_mfma_f32_16x16x32_bf16 v[16:19], v[164:167], v[206:209], v[16:19]
	v_mfma_f32_16x16x32_bf16 v[4:7], v[156:159], v[214:217], v[4:7]
	v_mfma_f32_16x16x32_bf16 v[0:3], v[164:167], v[214:217], v[0:3]
	v_mfma_f32_16x16x32_bf16 v[52:55], v[160:163], v[180:183], v[52:55]
	v_mfma_f32_16x16x32_bf16 v[48:51], v[168:171], v[180:183], v[48:51]
	v_mfma_f32_16x16x32_bf16 v[36:39], v[160:163], v[188:191], v[36:39]
	v_mfma_f32_16x16x32_bf16 v[32:35], v[168:171], v[188:191], v[32:35]
	v_mfma_f32_16x16x32_bf16 v[20:23], v[160:163], v[210:213], v[20:23]
	v_mfma_f32_16x16x32_bf16 v[16:19], v[168:171], v[210:213], v[16:19]
	s_barrier
	s_setprio 2
	v_mfma_f32_16x16x32_bf16 v[4:7], v[160:163], v[218:221], v[4:7]
	v_mfma_f32_16x16x32_bf16 v[0:3], v[168:171], v[218:221], v[0:3]
	s_setprio 0
	s_add_i32 s43, 0, 0x18000
	s_add_i32 s65, 0, 0x1c000
	v_add_u32_e32 v152, 0x18000, v178
	v_add_u32_e32 v168, 0x1c000, v178
	ds_read_b128 v[128:131], v152
	ds_read_b128 v[132:135], v152 offset:1024
	ds_read_b128 v[148:151], v152 offset:2048
	ds_read_b128 v[152:155], v152 offset:3072
	ds_read_b128 v[156:159], v168
	ds_read_b128 v[160:163], v168 offset:1024
	ds_read_b128 v[164:167], v168 offset:2048
	ds_read_b128 v[168:171], v168 offset:3072
	s_add_u32 s14, s14, 0x80000
	s_addc_u32 s15, s15, 0
	s_mov_b32 m0, s76
	v_lshl_add_u64 v[232:233], s[14:15], 0, v[136:137]
	ds_read_b128 v[172:175], v179 offset:32768
	ds_read_b128 v[180:183], v179 offset:33792
	ds_read_b128 v[184:187], v179 offset:34816
	ds_read_b128 v[188:191], v179 offset:35840
	ds_read_b128 v[206:209], v179 offset:36864
	ds_read_b128 v[210:213], v179 offset:37888
	ds_read_b128 v[214:217], v179 offset:38912
	ds_read_b128 v[218:221], v179 offset:39936
	global_load_lds_dwordx4 v[232:233], off
	s_mov_b32 m0, s77
	v_lshl_add_u64 v[232:233], s[14:15], 0, v[140:141]
	global_load_lds_dwordx4 v[232:233], off
	s_waitcnt vmcnt(8)
	s_waitcnt lgkmcnt(0)
	s_barrier
; #define PG8_STAGE(bufoff, gbase, voff) do { _Pragma("unroll") for (int _i = 0; _i < 2; ++_i) \
;         __builtin_amdgcn_global_load_lds((const unsigned*)((const char*)(gbase) + (voff)[_i]), (PG8_LAS unsigned*)(lds + (bufoff) + ldsw + _i * 8192), 16, 0, 0); } while (0)
; #define PG8_LDA(dst, b, h) do { _Pragma("unroll") for (int m = 0; m < 4; ++m) _Pragma("unroll") for (int k = 0; k < 2; ++k) dst[m][k] = *(const PG8_LAS bf16x8*)(lds + PG8_SA(b, h) + aoff + m * 2048 + k * 1024); } while (0)
; #define PG8_MMA(ai, bj, At, Bt) do { __builtin_amdgcn_s_setprio(1); _Pragma("unroll") for (int m = 0; m < 4; ++m) _Pragma("unroll") for (int n = 0; n < 2; ++n) _Pragma("unroll") for (int k = 0; k < 2; ++k) \
;         acc[ai][bj][m][n] = __builtin_amdgcn_mfma_f32_16x16x32_bf16(Bt[n][k], At[m][k], acc[ai][bj][m][n], 0, 0, 0); __builtin_amdgcn_s_setprio(0); } while (0)
; #define PG8_WAIT_V(n) asm volatile("s_waitcnt vmcnt(" #n ")" ::: "memory")
; #define PG8_WAIT_L(n) asm volatile("s_waitcnt lgkmcnt(" #n ")" ::: "memory")
; #define PG8_BAR __builtin_amdgcn_s_barrier()
; #define PG8_SCHED __builtin_amdgcn_sched_barrier(0)
; template <class Epi, class Sched, bool ALIGN_EPI = false, bool SP2 = false>
; __device__ __forceinline__ void gemm_phase(PG8_LAS unsigned char* lds, const Gemm g, const Sched& S, const Epi& E) {
;     ...
;             PG8_WAIT_V(8); PG8_WAIT_L(0); PG8_BAR; PG8_MMA(0, 0, At, B0); PG8_MMA(0, 1, At, B1); PG8_BAR; PG8_SCHED;
;             PG8_LDA(At, 1, 1); PG8_STAGE(PG8_SB(1, 0), b3, voffB); PG8_STAGE(PG8_SB(1, 1), b3 + hstep, voffB); PG8_STAGE(PG8_SA(1, 0), a3, voffA);
;             PG8_WAIT_V(8); PG8_WAIT_L(0); PG8_BAR; PG8_MMA(1, 0, At, B0); PG8_MMA(1, 1, At, B1); PG8_BAR; PG8_SCHED;
	s_setprio 1
	s_waitcnt lgkmcnt(0)
	v_mfma_f32_16x16x32_bf16 v[124:127], v[128:131], v[172:175], v[124:127]
	v_mfma_f32_16x16x32_bf16 v[120:123], v[148:151], v[172:175], v[120:123]
	v_mfma_f32_16x16x32_bf16 v[108:111], v[128:131], v[184:187], v[108:111]
	v_mfma_f32_16x16x32_bf16 v[104:107], v[148:151], v[184:187], v[104:107]
	v_mfma_f32_16x16x32_bf16 v[92:95], v[128:131], v[206:209], v[92:95]
	v_mfma_f32_16x16x32_bf16 v[88:91], v[148:151], v[206:209], v[88:91]
	v_mfma_f32_16x16x32_bf16 v[76:79], v[128:131], v[214:217], v[76:79]
	v_mfma_f32_16x16x32_bf16 v[72:75], v[148:151], v[214:217], v[72:75]
	v_mfma_f32_16x16x32_bf16 v[124:127], v[132:135], v[180:183], v[124:127]
	v_mfma_f32_16x16x32_bf16 v[120:123], v[152:155], v[180:183], v[120:123]
	v_mfma_f32_16x16x32_bf16 v[108:111], v[132:135], v[188:191], v[108:111]
	v_mfma_f32_16x16x32_bf16 v[104:107], v[152:155], v[188:191], v[104:107]
	v_mfma_f32_16x16x32_bf16 v[92:95], v[132:135], v[210:213], v[92:95]
	v_mfma_f32_16x16x32_bf16 v[88:91], v[152:155], v[210:213], v[88:91]
	v_mfma_f32_16x16x32_bf16 v[76:79], v[132:135], v[218:221], v[76:79]
	v_mfma_f32_16x16x32_bf16 v[72:75], v[152:155], v[218:221], v[72:75]
	s_setprio 0
	s_setprio 1
	v_mfma_f32_16x16x32_bf16 v[116:119], v[156:159], v[172:175], v[116:119]
	v_mfma_f32_16x16x32_bf16 v[112:115], v[164:167], v[172:175], v[112:115]
	v_mfma_f32_16x16x32_bf16 v[100:103], v[156:159], v[184:187], v[100:103]
	v_mfma_f32_16x16x32_bf16 v[96:99], v[164:167], v[184:187], v[96:99]
	v_mfma_f32_16x16x32_bf16 v[84:87], v[156:159], v[206:209], v[84:87]
	v_mfma_f32_16x16x32_bf16 v[80:83], v[164:167], v[206:209], v[80:83]
	v_mfma_f32_16x16x32_bf16 v[68:71], v[156:159], v[214:217], v[68:71]
	v_mfma_f32_16x16x32_bf16 v[64:67], v[164:167], v[214:217], v[64:67]
	v_mfma_f32_16x16x32_bf16 v[116:119], v[160:163], v[180:183], v[116:119]
	v_mfma_f32_16x16x32_bf16 v[112:115], v[168:171], v[180:183], v[112:115]
	v_mfma_f32_16x16x32_bf16 v[100:103], v[160:163], v[188:191], v[100:103]
	v_mfma_f32_16x16x32_bf16 v[96:99], v[168:171], v[188:191], v[96:99]
	v_mfma_f32_16x16x32_bf16 v[84:87], v[160:163], v[210:213], v[84:87]
	v_mfma_f32_16x16x32_bf16 v[80:83], v[168:171], v[210:213], v[80:83]
	s_barrier
	s_setprio 2
	v_mfma_f32_16x16x32_bf16 v[68:71], v[160:163], v[218:221], v[68:71]
	v_mfma_f32_16x16x32_bf16 v[64:67], v[168:171], v[218:221], v[64:67]
	s_setprio 0
	s_add_i32 s14, s43, s39
	v_lshl_add_u64 v[194:195], v[194:195], 0, s[16:17]
	s_mov_b32 m0, s14
	ds_read_b128 v[172:175], v179 offset:49152
	ds_read_b128 v[180:183], v179 offset:50176
	ds_read_b128 v[184:187], v179 offset:51200
	ds_read_b128 v[188:191], v179 offset:52224
	ds_read_b128 v[206:209], v179 offset:53248
	ds_read_b128 v[210:213], v179 offset:54272
	ds_read_b128 v[214:217], v179 offset:55296
	ds_read_b128 v[218:221], v179 offset:56320
	global_load_lds_dwordx4 v[194:195], off
	s_add_i32 m0, s14, 0x2000
	s_add_u32 s12, s12, 0x80080
	v_lshl_add_u64 v[194:195], v[196:197], 0, s[16:17]
	s_addc_u32 s13, s13, 0
	s_add_i32 s14, s65, s39
	global_load_lds_dwordx4 v[194:195], off
	s_mov_b32 m0, s14
	v_lshl_add_u64 v[194:195], s[12:13], 0, v[138:139]
	global_load_lds_dwordx4 v[194:195], off
	s_add_i32 m0, s14, 0x2000
	v_lshl_add_u64 v[194:195], s[12:13], 0, v[142:143]
	global_load_lds_dwordx4 v[194:195], off
	s_mov_b32 m0, s80
	v_lshl_add_u64 v[194:195], v[202:203], 0, s[16:17]
	global_load_lds_dwordx4 v[194:195], off
	s_mov_b32 m0, s81
	v_lshl_add_u64 v[194:195], v[204:205], 0, s[16:17]
	global_load_lds_dwordx4 v[194:195], off
	s_waitcnt vmcnt(8)
	s_waitcnt lgkmcnt(0)
	s_barrier
	s_setprio 1
	s_waitcnt lgkmcnt(0)
	v_mfma_f32_16x16x32_bf16 v[60:63], v[128:131], v[172:175], v[60:63]
	v_mfma_f32_16x16x32_bf16 v[56:59], v[148:151], v[172:175], v[56:59]
	v_mfma_f32_16x16x32_bf16 v[44:47], v[128:131], v[184:187], v[44:47]
	v_mfma_f32_16x16x32_bf16 v[40:43], v[148:151], v[184:187], v[40:43]
	v_mfma_f32_16x16x32_bf16 v[28:31], v[128:131], v[206:209], v[28:31]
	v_mfma_f32_16x16x32_bf16 v[24:27], v[148:151], v[206:209], v[24:27]
	v_mfma_f32_16x16x32_bf16 v[12:15], v[128:131], v[214:217], v[12:15]
	v_mfma_f32_16x16x32_bf16 v[8:11], v[148:151], v[214:217], v[8:11]
	v_mfma_f32_16x16x32_bf16 v[60:63], v[132:135], v[180:183], v[60:63]
	v_mfma_f32_16x16x32_bf16 v[56:59], v[152:155], v[180:183], v[56:59]
	v_mfma_f32_16x16x32_bf16 v[44:47], v[132:135], v[188:191], v[44:47]
	v_mfma_f32_16x16x32_bf16 v[40:43], v[152:155], v[188:191], v[40:43]
	v_mfma_f32_16x16x32_bf16 v[28:31], v[132:135], v[210:213], v[28:31]
	v_mfma_f32_16x16x32_bf16 v[24:27], v[152:155], v[210:213], v[24:27]
	v_mfma_f32_16x16x32_bf16 v[12:15], v[132:135], v[218:221], v[12:15]
	v_mfma_f32_16x16x32_bf16 v[8:11], v[152:155], v[218:221], v[8:11]
	s_setprio 0
	s_setprio 1
	v_mfma_f32_16x16x32_bf16 v[52:55], v[156:159], v[172:175], v[52:55]
	v_mfma_f32_16x16x32_bf16 v[48:51], v[164:167], v[172:175], v[48:51]
	v_mfma_f32_16x16x32_bf16 v[36:39], v[156:159], v[184:187], v[36:39]
	v_mfma_f32_16x16x32_bf16 v[32:35], v[164:167], v[184:187], v[32:35]
	v_mfma_f32_16x16x32_bf16 v[20:23], v[156:159], v[206:209], v[20:23]
	v_mfma_f32_16x16x32_bf16 v[16:19], v[164:167], v[206:209], v[16:19]
	v_mfma_f32_16x16x32_bf16 v[4:7], v[156:159], v[214:217], v[4:7]
	v_mfma_f32_16x16x32_bf16 v[0:3], v[164:167], v[214:217], v[0:3]
	v_mfma_f32_16x16x32_bf16 v[52:55], v[160:163], v[180:183], v[52:55]
	v_mfma_f32_16x16x32_bf16 v[48:51], v[168:171], v[180:183], v[48:51]
	v_mfma_f32_16x16x32_bf16 v[36:39], v[160:163], v[188:191], v[36:39]
	v_mfma_f32_16x16x32_bf16 v[32:35], v[168:171], v[188:191], v[32:35]
	v_mfma_f32_16x16x32_bf16 v[20:23], v[160:163], v[210:213], v[20:23]
	v_mfma_f32_16x16x32_bf16 v[16:19], v[168:171], v[210:213], v[16:19]
	s_barrier
	s_setprio 2
	v_mfma_f32_16x16x32_bf16 v[4:7], v[160:163], v[218:221], v[4:7]
	v_mfma_f32_16x16x32_bf16 v[0:3], v[168:171], v[218:221], v[0:3]
	s_setprio 0
	s_add_i32 s42, s42, 2
	s_add_u32 s0, s0, 0x100
	s_addc_u32 s1, s1, 0
	s_add_u32 s34, s34, 0x100
	s_addc_u32 s41, s41, 0
	s_cmp_gt_u32 s42, 29
	s_cbranch_scc0 .LBB0_129
	s_and_b64 vcc, exec, s[62:63]
	s_cbranch_vccz .LBB0_132
	s_barrier

; #define PG8_STAGE(bufoff, gbase, voff) do { _Pragma("unroll") for (int _i = 0; _i < 2; ++_i) \
;         __builtin_amdgcn_global_load_lds((const unsigned*)((const char*)(gbase) + (voff)[_i]), (PG8_LAS unsigned*)(lds + (bufoff) + ldsw + _i * 8192), 16, 0, 0); } while (0)
; #define PG8_LDA(dst, b, h) do { _Pragma("unroll") for (int m = 0; m < 4; ++m) _Pragma("unroll") for (int k = 0; k < 2; ++k) dst[m][k] = *(const PG8_LAS bf16x8*)(lds + PG8_SA(b, h) + aoff + m * 2048 + k * 1024); } while (0)
; #define PG8_LDB(dst, b, h) do { _Pragma("unroll") for (int n = 0; n < 2; ++n) _Pragma("unroll") for (int k = 0; k < 2; ++k) dst[n][k] = *(const PG8_LAS bf16x8*)(lds + PG8_SB(b, h) + boff + n * 2048 + k * 1024); } while (0)
; #define PG8_WAIT_V(n) asm volatile("s_waitcnt vmcnt(" #n ")" ::: "memory")
; #define PG8_WAIT_L(n) asm volatile("s_waitcnt lgkmcnt(" #n ")" ::: "memory")
; #define PG8_BAR __builtin_amdgcn_s_barrier()
; #define PG8_SCHED __builtin_amdgcn_sched_barrier(0)
; template <class Epi, class Sched, bool ALIGN_EPI = false, bool SP2 = false>
; __device__ __forceinline__ void gemm_phase(PG8_LAS unsigned char* lds, const Gemm g, const Sched& S, const Epi& E) {
;     ...
;         const char* nA = has_next ? (const char*)g.A + (size_t)nxt.pm * tstep : cA; const char* nB = has_next ? (const char*)g.Bt + (size_t)nxt.pn * tstep : cB;
;         for (int t = 0; t < nt; t += 2) {
;             if constexpr (Epi::MID_HOOK) { if (t == Epi::MID_T) E.mid(acc, cur, wr, wc, fr, fq); }
;             const bool last = (t == nt - 2);
;             const char* a1 = cA + (size_t)(t + 1) * kstep;
;             const char* a2 = last ? nA : cA + (size_t)(t + 2) * kstep; const char* b2 = last ? nB : cB + (size_t)(t + 2) * kstep;
;             const char* a3 = a2 + kstep; const char* b3 = b2 + kstep;
;             if (last && has_next) S.a_ready(nxt);
;             if constexpr (SP2) {
;             PG8_LDB(B0, 0, 0); PG8_LDB(B1, 0, 1); PG8_SCHED; PG8_LDA(At, 0, 0); PG8_STAGE(PG8_SA(1, 1), a1 + hstep, voffA);
;             PG8_WAIT_V(8); PG8_WAIT_L(0); PG8_BAR; PG8_MMA(0, 0, At, B0); PG8_MMA(0, 1, At, B1); PG8_BAR; PG8_SCHED;
;             PG8_LDA(At, 0, 1); PG8_STAGE(PG8_SB(0, 0), b2, voffB); PG8_STAGE(PG8_SB(0, 1), b2 + hstep, voffB); PG8_STAGE(PG8_SA(0, 0), a2, voffA);
;             PG8_WAIT_V(8); PG8_WAIT_L(0); PG8_BAR; PG8_MMA(1, 0, At, B0); PG8_MMA(1, 1, At, B1); PG8_BAR; PG8_SCHED;
.LBB0_634:
	s_ashr_i32 s15, s14, 31
	s_lshl_b64 s[18:19], s[14:15], 20
	s_add_u32 s18, s45, s18
	s_addc_u32 s19, s46, s19
	s_and_b64 s[30:31], s[0:1], exec
	s_cselect_b32 s15, s19, s37
	s_cselect_b32 s61, s18, s36
	s_ashr_i32 s13, s12, 31
	s_lshl_b64 s[30:31], s[12:13], 20
	s_add_u32 s30, s34, s30
	s_addc_u32 s31, s44, s31
	s_and_b64 s[42:43], s[0:1], exec
	s_cselect_b32 s13, s31, s39
	s_cselect_b32 s62, s30, s38
	s_add_u32 s36, s36, 0x80080
	s_addc_u32 s37, s37, 0
	s_add_u32 s63, s38, 0x100
	s_addc_u32 s64, s39, 0
	s_mov_b32 s65, -2
	s_waitcnt lgkmcnt(0)
	v_lshl_add_u64 v[168:169], s[36:37], 0, v[160:161]
	s_add_i32 m0, s2, 0xc000
	global_load_lds_dwordx4 v[168:169], off
	s_add_i32 m0, s2, 0xe000
	v_lshl_add_u64 v[168:169], s[36:37], 0, v[162:163]
	global_load_lds_dwordx4 v[168:169], off
	s_add_u32 s24, s36, 0xfff80080
	s_addc_u32 s25, s37, -1
	s_add_i32 s33, 0, 0x10000
	s_cmp_eq_u32 s65, 28
	s_cselect_b32 s43, s15, s25
	s_cselect_b32 s42, s61, s24
	s_cselect_b32 s39, s13, s64
	s_cselect_b32 s38, s62, s63
	s_add_i32 s24, 0, 0x14000
	s_waitcnt vmcnt(8)
	s_waitcnt lgkmcnt(0)
	s_barrier
	s_setprio 1
	s_waitcnt lgkmcnt(0)
	v_mfma_f32_16x16x32_bf16 v[124:127], v[128:131], v[178:181], 0
	v_mfma_f32_16x16x32_bf16 v[120:123], v[136:139], v[178:181], 0
	v_mfma_f32_16x16x32_bf16 v[108:111], v[128:131], v[186:189], 0
	v_mfma_f32_16x16x32_bf16 v[104:107], v[136:139], v[186:189], 0
	v_mfma_f32_16x16x32_bf16 v[92:95], v[128:131], v[202:205], 0
	v_mfma_f32_16x16x32_bf16 v[88:91], v[136:139], v[202:205], 0
	v_mfma_f32_16x16x32_bf16 v[76:79], v[128:131], v[210:213], 0
	v_mfma_f32_16x16x32_bf16 v[72:75], v[136:139], v[210:213], 0
	v_mfma_f32_16x16x32_bf16 v[124:127], v[132:135], v[182:185], v[124:127]
	v_mfma_f32_16x16x32_bf16 v[120:123], v[140:143], v[182:185], v[120:123]
	v_mfma_f32_16x16x32_bf16 v[108:111], v[132:135], v[194:197], v[108:111]
	v_mfma_f32_16x16x32_bf16 v[104:107], v[140:143], v[194:197], v[104:107]
	v_mfma_f32_16x16x32_bf16 v[92:95], v[132:135], v[206:209], v[92:95]
	v_mfma_f32_16x16x32_bf16 v[88:91], v[140:143], v[206:209], v[88:91]
	v_mfma_f32_16x16x32_bf16 v[76:79], v[132:135], v[214:217], v[76:79]
	v_mfma_f32_16x16x32_bf16 v[72:75], v[140:143], v[214:217], v[72:75]
	s_setprio 0
	s_setprio 1
	v_mfma_f32_16x16x32_bf16 v[116:119], v[144:147], v[178:181], 0
	v_mfma_f32_16x16x32_bf16 v[112:115], v[164:167], v[178:181], 0
	v_mfma_f32_16x16x32_bf16 v[100:103], v[144:147], v[186:189], 0
	v_mfma_f32_16x16x32_bf16 v[96:99], v[164:167], v[186:189], 0
	v_mfma_f32_16x16x32_bf16 v[84:87], v[144:147], v[202:205], 0
	v_mfma_f32_16x16x32_bf16 v[80:83], v[164:167], v[202:205], 0
	v_mfma_f32_16x16x32_bf16 v[68:71], v[144:147], v[210:213], 0
	v_mfma_f32_16x16x32_bf16 v[64:67], v[164:167], v[210:213], 0
	v_mfma_f32_16x16x32_bf16 v[116:119], v[148:151], v[182:185], v[116:119]
	v_mfma_f32_16x16x32_bf16 v[112:115], v[174:177], v[182:185], v[112:115]
	v_mfma_f32_16x16x32_bf16 v[100:103], v[148:151], v[194:197], v[100:103]
	v_mfma_f32_16x16x32_bf16 v[96:99], v[174:177], v[194:197], v[96:99]
	v_mfma_f32_16x16x32_bf16 v[84:87], v[148:151], v[206:209], v[84:87]
	v_mfma_f32_16x16x32_bf16 v[80:83], v[174:177], v[206:209], v[80:83]
	s_barrier
	s_setprio 2
	v_mfma_f32_16x16x32_bf16 v[68:71], v[148:151], v[214:217], v[68:71]
	v_mfma_f32_16x16x32_bf16 v[64:67], v[174:177], v[214:217], v[64:67]
	s_setprio 0
	s_add_i32 s25, s33, s47
	v_lshl_add_u64 v[168:169], s[38:39], 0, v[156:157]
	s_mov_b32 m0, s25
	ds_read_b128 v[178:181], v173 offset:16384
	ds_read_b128 v[182:185], v173 offset:17408
	ds_read_b128 v[186:189], v173 offset:18432
	ds_read_b128 v[194:197], v173 offset:19456
	ds_read_b128 v[202:205], v173 offset:20480
	ds_read_b128 v[206:209], v173 offset:21504
	ds_read_b128 v[210:213], v173 offset:22528
	ds_read_b128 v[214:217], v173 offset:23552
	global_load_lds_dwordx4 v[168:169], off
	s_add_i32 m0, s25, 0x2000
	s_add_u32 s66, s38, 0x80000
	v_lshl_add_u64 v[190:191], s[38:39], 0, v[152:153]
	s_addc_u32 s67, s39, 0
	s_add_i32 s24, s24, s47
	global_load_lds_dwordx4 v[190:191], off
	v_lshl_add_u64 v[218:219], s[66:67], 0, v[156:157]
	s_mov_b32 m0, s24
	v_lshl_add_u64 v[220:221], s[42:43], 0, v[154:155]
	global_load_lds_dwordx4 v[218:219], off
	s_add_i32 m0, s24, 0x2000
	v_lshl_add_u64 v[218:219], s[66:67], 0, v[152:153]
	global_load_lds_dwordx4 v[218:219], off
	s_mov_b32 m0, s2
	v_lshl_add_u64 v[218:219], s[42:43], 0, v[158:159]
	global_load_lds_dwordx4 v[218:219], off
	s_mov_b32 m0, s48
	s_nop 0
	global_load_lds_dwordx4 v[220:221], off
	s_waitcnt vmcnt(8)
	s_waitcnt lgkmcnt(0)
	s_barrier
	s_setprio 1
	s_waitcnt lgkmcnt(0)
	v_mfma_f32_16x16x32_bf16 v[60:63], v[128:131], v[178:181], 0
	v_mfma_f32_16x16x32_bf16 v[56:59], v[136:139], v[178:181], 0
	v_mfma_f32_16x16x32_bf16 v[44:47], v[128:131], v[186:189], 0
	v_mfma_f32_16x16x32_bf16 v[40:43], v[136:139], v[186:189], 0
	v_mfma_f32_16x16x32_bf16 v[28:31], v[128:131], v[202:205], 0
	v_mfma_f32_16x16x32_bf16 v[24:27], v[136:139], v[202:205], 0
	v_mfma_f32_16x16x32_bf16 v[12:15], v[128:131], v[210:213], 0
	v_mfma_f32_16x16x32_bf16 v[8:11], v[136:139], v[210:213], 0
	v_mfma_f32_16x16x32_bf16 v[60:63], v[132:135], v[182:185], v[60:63]
	v_mfma_f32_16x16x32_bf16 v[56:59], v[140:143], v[182:185], v[56:59]
	v_mfma_f32_16x16x32_bf16 v[44:47], v[132:135], v[194:197], v[44:47]
	v_mfma_f32_16x16x32_bf16 v[40:43], v[140:143], v[194:197], v[40:43]
	v_mfma_f32_16x16x32_bf16 v[28:31], v[132:135], v[206:209], v[28:31]
	v_mfma_f32_16x16x32_bf16 v[24:27], v[140:143], v[206:209], v[24:27]
	v_mfma_f32_16x16x32_bf16 v[12:15], v[132:135], v[214:217], v[12:15]
	v_mfma_f32_16x16x32_bf16 v[8:11], v[140:143], v[214:217], v[8:11]
	s_setprio 0
	s_setprio 1
	v_mfma_f32_16x16x32_bf16 v[52:55], v[144:147], v[178:181], 0
	v_mfma_f32_16x16x32_bf16 v[48:51], v[164:167], v[178:181], 0
	v_mfma_f32_16x16x32_bf16 v[36:39], v[144:147], v[186:189], 0
	v_mfma_f32_16x16x32_bf16 v[32:35], v[164:167], v[186:189], 0
	v_mfma_f32_16x16x32_bf16 v[20:23], v[144:147], v[202:205], 0
	v_mfma_f32_16x16x32_bf16 v[16:19], v[164:167], v[202:205], 0
	v_mfma_f32_16x16x32_bf16 v[4:7], v[144:147], v[210:213], 0
	v_mfma_f32_16x16x32_bf16 v[0:3], v[164:167], v[210:213], 0
	v_mfma_f32_16x16x32_bf16 v[52:55], v[148:151], v[182:185], v[52:55]
	v_mfma_f32_16x16x32_bf16 v[48:51], v[174:177], v[182:185], v[48:51]
	v_mfma_f32_16x16x32_bf16 v[36:39], v[148:151], v[194:197], v[36:39]
	v_mfma_f32_16x16x32_bf16 v[32:35], v[174:177], v[194:197], v[32:35]
	v_mfma_f32_16x16x32_bf16 v[20:23], v[148:151], v[206:209], v[20:23]
	v_mfma_f32_16x16x32_bf16 v[16:19], v[174:177], v[206:209], v[16:19]
	s_barrier
; #define PG8_STAGE(bufoff, gbase, voff) do { _Pragma("unroll") for (int _i = 0; _i < 2; ++_i) \
;         __builtin_amdgcn_global_load_lds((const unsigned*)((const char*)(gbase) + (voff)[_i]), (PG8_LAS unsigned*)(lds + (bufoff) + ldsw + _i * 8192), 16, 0, 0); } while (0)
; #define PG8_LDA(dst, b, h) do { _Pragma("unroll") for (int m = 0; m < 4; ++m) _Pragma("unroll") for (int k = 0; k < 2; ++k) dst[m][k] = *(const PG8_LAS bf16x8*)(lds + PG8_SA(b, h) + aoff + m * 2048 + k * 1024); } while (0)
; #define PG8_LDB(dst, b, h) do { _Pragma("unroll") for (int n = 0; n < 2; ++n) _Pragma("unroll") for (int k = 0; k < 2; ++k) dst[n][k] = *(const PG8_LAS bf16x8*)(lds + PG8_SB(b, h) + boff + n * 2048 + k * 1024); } while (0)
; #define PG8_MMA(ai, bj, At, Bt) do { __builtin_amdgcn_s_setprio(1); _Pragma("unroll") for (int m = 0; m < 4; ++m) _Pragma("unroll") for (int n = 0; n < 2; ++n) _Pragma("unroll") for (int k = 0; k < 2; ++k) \
;         acc[ai][bj][m][n] = __builtin_amdgcn_mfma_f32_16x16x32_bf16(Bt[n][k], At[m][k], acc[ai][bj][m][n], 0, 0, 0); __builtin_amdgcn_s_setprio(0); } while (0)
; #define PG8_WAIT_V(n) asm volatile("s_waitcnt vmcnt(" #n ")" ::: "memory")
; #define PG8_WAIT_L(n) asm volatile("s_waitcnt lgkmcnt(" #n ")" ::: "memory")
; #define PG8_BAR __builtin_amdgcn_s_barrier()
; #define PG8_SCHED __builtin_amdgcn_sched_barrier(0)
; template <class Epi, class Sched, bool ALIGN_EPI = false, bool SP2 = false>
; __device__ __forceinline__ void gemm_phase(PG8_LAS unsigned char* lds, const Gemm g, const Sched& S, const Epi& E) {
;     ...
;             PG8_WAIT_V(8); PG8_WAIT_L(0); PG8_BAR; PG8_MMA(1, 0, At, B0); PG8_MMA(1, 1, At, B1); PG8_BAR; PG8_SCHED;
;             PG8_LDB(B0, 1, 0); PG8_LDB(B1, 1, 1); PG8_SCHED; PG8_LDA(At, 1, 0); PG8_STAGE(PG8_SA(0, 1), a2 + hstep, voffA);
;             PG8_WAIT_V(8); PG8_WAIT_L(0); PG8_BAR; PG8_MMA(0, 0, At, B0); PG8_MMA(0, 1, At, B1); PG8_BAR; PG8_SCHED;
;             PG8_LDA(At, 1, 1); PG8_STAGE(PG8_SB(1, 0), b3, voffB); PG8_STAGE(PG8_SB(1, 1), b3 + hstep, voffB); PG8_STAGE(PG8_SA(1, 0), a3, voffA);
	s_setprio 2
	v_mfma_f32_16x16x32_bf16 v[4:7], v[148:151], v[214:217], v[4:7]
	v_mfma_f32_16x16x32_bf16 v[0:3], v[174:177], v[214:217], v[0:3]
	s_setprio 0
	s_add_i32 s24, 0, 0x18000
	s_add_i32 s25, 0, 0x1c000
	v_add_u32_e32 v140, 0x18000, v172
	v_add_u32_e32 v174, 0x1c000, v172
	ds_read_b128 v[128:131], v140
	ds_read_b128 v[132:135], v140 offset:1024
	ds_read_b128 v[136:139], v140 offset:2048
	ds_read_b128 v[140:143], v140 offset:3072
	ds_read_b128 v[144:147], v174
	ds_read_b128 v[148:151], v174 offset:1024
	ds_read_b128 v[164:167], v174 offset:2048
	ds_read_b128 v[174:177], v174 offset:3072
	s_add_u32 s42, s42, 0x80000
	s_addc_u32 s43, s43, 0
	s_mov_b32 m0, s49
	v_lshl_add_u64 v[230:231], s[42:43], 0, v[158:159]
	ds_read_b128 v[178:181], v173 offset:32768
	ds_read_b128 v[182:185], v173 offset:33792
	ds_read_b128 v[186:189], v173 offset:34816
	ds_read_b128 v[194:197], v173 offset:35840
	ds_read_b128 v[202:205], v173 offset:36864
	ds_read_b128 v[206:209], v173 offset:37888
	ds_read_b128 v[210:213], v173 offset:38912
	ds_read_b128 v[214:217], v173 offset:39936
	global_load_lds_dwordx4 v[230:231], off
	s_mov_b32 m0, s50
	v_lshl_add_u64 v[230:231], s[42:43], 0, v[154:155]
	global_load_lds_dwordx4 v[230:231], off
	s_waitcnt vmcnt(8)
	s_waitcnt lgkmcnt(0)
	s_barrier
	s_setprio 1
	s_waitcnt lgkmcnt(0)
	v_mfma_f32_16x16x32_bf16 v[124:127], v[128:131], v[178:181], v[124:127]
	v_mfma_f32_16x16x32_bf16 v[120:123], v[136:139], v[178:181], v[120:123]
	v_mfma_f32_16x16x32_bf16 v[108:111], v[128:131], v[186:189], v[108:111]
	v_mfma_f32_16x16x32_bf16 v[104:107], v[136:139], v[186:189], v[104:107]
	v_mfma_f32_16x16x32_bf16 v[92:95], v[128:131], v[202:205], v[92:95]
	v_mfma_f32_16x16x32_bf16 v[88:91], v[136:139], v[202:205], v[88:91]
	v_mfma_f32_16x16x32_bf16 v[76:79], v[128:131], v[210:213], v[76:79]
	v_mfma_f32_16x16x32_bf16 v[72:75], v[136:139], v[210:213], v[72:75]
	v_mfma_f32_16x16x32_bf16 v[124:127], v[132:135], v[182:185], v[124:127]
	v_mfma_f32_16x16x32_bf16 v[120:123], v[140:143], v[182:185], v[120:123]
	v_mfma_f32_16x16x32_bf16 v[108:111], v[132:135], v[194:197], v[108:111]
	v_mfma_f32_16x16x32_bf16 v[104:107], v[140:143], v[194:197], v[104:107]
	v_mfma_f32_16x16x32_bf16 v[92:95], v[132:135], v[206:209], v[92:95]
	v_mfma_f32_16x16x32_bf16 v[88:91], v[140:143], v[206:209], v[88:91]
	v_mfma_f32_16x16x32_bf16 v[76:79], v[132:135], v[214:217], v[76:79]
	v_mfma_f32_16x16x32_bf16 v[72:75], v[140:143], v[214:217], v[72:75]
	s_setprio 0
	s_setprio 1
	v_mfma_f32_16x16x32_bf16 v[116:119], v[144:147], v[178:181], v[116:119]
	v_mfma_f32_16x16x32_bf16 v[112:115], v[164:167], v[178:181], v[112:115]
	v_mfma_f32_16x16x32_bf16 v[100:103], v[144:147], v[186:189], v[100:103]
	v_mfma_f32_16x16x32_bf16 v[96:99], v[164:167], v[186:189], v[96:99]
	v_mfma_f32_16x16x32_bf16 v[84:87], v[144:147], v[202:205], v[84:87]
	v_mfma_f32_16x16x32_bf16 v[80:83], v[164:167], v[202:205], v[80:83]
	v_mfma_f32_16x16x32_bf16 v[68:71], v[144:147], v[210:213], v[68:71]
	v_mfma_f32_16x16x32_bf16 v[64:67], v[164:167], v[210:213], v[64:67]
	v_mfma_f32_16x16x32_bf16 v[116:119], v[148:151], v[182:185], v[116:119]
	v_mfma_f32_16x16x32_bf16 v[112:115], v[174:177], v[182:185], v[112:115]
	v_mfma_f32_16x16x32_bf16 v[100:103], v[148:151], v[194:197], v[100:103]
	v_mfma_f32_16x16x32_bf16 v[96:99], v[174:177], v[194:197], v[96:99]
	v_mfma_f32_16x16x32_bf16 v[84:87], v[148:151], v[206:209], v[84:87]
	v_mfma_f32_16x16x32_bf16 v[80:83], v[174:177], v[206:209], v[80:83]
	s_barrier
	s_setprio 2
	v_mfma_f32_16x16x32_bf16 v[68:71], v[148:151], v[214:217], v[68:71]
	v_mfma_f32_16x16x32_bf16 v[64:67], v[174:177], v[214:217], v[64:67]
	s_setprio 0
	s_add_i32 s24, s24, s47
	v_lshl_add_u64 v[168:169], v[168:169], 0, s[16:17]
	s_mov_b32 m0, s24
	ds_read_b128 v[178:181], v173 offset:49152
	ds_read_b128 v[182:185], v173 offset:50176
	ds_read_b128 v[186:189], v173 offset:51200
	ds_read_b128 v[194:197], v173 offset:52224
	ds_read_b128 v[202:205], v173 offset:53248
	ds_read_b128 v[206:209], v173 offset:54272
	ds_read_b128 v[210:213], v173 offset:55296
	ds_read_b128 v[214:217], v173 offset:56320
	global_load_lds_dwordx4 v[168:169], off
	s_add_i32 m0, s24, 0x2000
	s_add_u32 s38, s38, 0x80080
	v_lshl_add_u64 v[168:169], v[190:191], 0, s[16:17]
	s_addc_u32 s39, s39, 0
	s_add_i32 s24, s25, s47
	global_load_lds_dwordx4 v[168:169], off
	s_mov_b32 m0, s24
	v_lshl_add_u64 v[168:169], s[38:39], 0, v[156:157]
	global_load_lds_dwordx4 v[168:169], off
	s_add_i32 m0, s24, 0x2000
	v_lshl_add_u64 v[168:169], s[38:39], 0, v[152:153]
	global_load_lds_dwordx4 v[168:169], off
	s_mov_b32 m0, s55
	v_lshl_add_u64 v[168:169], v[218:219], 0, s[16:17]
	global_load_lds_dwordx4 v[168:169], off
	s_mov_b32 m0, s56
	v_lshl_add_u64 v[168:169], v[220:221], 0, s[16:17]
	global_load_lds_dwordx4 v[168:169], off
	s_waitcnt vmcnt(8)
	s_waitcnt lgkmcnt(0)
	s_barrier
; #define PG8_STAGE(bufoff, gbase, voff) do { _Pragma("unroll") for (int _i = 0; _i < 2; ++_i) \
;         __builtin_amdgcn_global_load_lds((const unsigned*)((const char*)(gbase) + (voff)[_i]), (PG8_LAS unsigned*)(lds + (bufoff) + ldsw + _i * 8192), 16, 0, 0); } while (0)
; #define PG8_LDA(dst, b, h) do { _Pragma("unroll") for (int m = 0; m < 4; ++m) _Pragma("unroll") for (int k = 0; k < 2; ++k) dst[m][k] = *(const PG8_LAS bf16x8*)(lds + PG8_SA(b, h) + aoff + m * 2048 + k * 1024); } while (0)
; #define PG8_LDB(dst, b, h) do { _Pragma("unroll") for (int n = 0; n < 2; ++n) _Pragma("unroll") for (int k = 0; k < 2; ++k) dst[n][k] = *(const PG8_LAS bf16x8*)(lds + PG8_SB(b, h) + boff + n * 2048 + k * 1024); } while (0)
; #define PG8_MMA(ai, bj, At, Bt) do { __builtin_amdgcn_s_setprio(1); _Pragma("unroll") for (int m = 0; m < 4; ++m) _Pragma("unroll") for (int n = 0; n < 2; ++n) _Pragma("unroll") for (int k = 0; k < 2; ++k) \
;         acc[ai][bj][m][n] = __builtin_amdgcn_mfma_f32_16x16x32_bf16(Bt[n][k], At[m][k], acc[ai][bj][m][n], 0, 0, 0); __builtin_amdgcn_s_setprio(0); } while (0)
; #define PG8_WAIT_V(n) asm volatile("s_waitcnt vmcnt(" #n ")" ::: "memory")
; template <class Epi, class Sched, bool ALIGN_EPI = false, bool SP2 = false>
; __device__ __forceinline__ void gemm_phase(PG8_LAS unsigned char* lds, const Gemm g, const Sched& S, const Epi& E) {
;     ...
;             PG8_LDB(B0, 0, 0); PG8_LDB(B1, 0, 1); PG8_SCHED; PG8_LDA(At, 0, 0); PG8_STAGE(PG8_SA(1, 1), a1 + hstep, voffA);
;             PG8_WAIT_V(8); PG8_WAIT_L(0); PG8_BAR; PG8_MMA(0, 0, At, B0); PG8_MMA(0, 1, At, B1); PG8_BAR; PG8_SCHED;
;             PG8_LDA(At, 0, 1); PG8_STAGE(PG8_SB(0, 0), b2, voffB); PG8_STAGE(PG8_SB(0, 1), b2 + hstep, voffB); PG8_STAGE(PG8_SA(0, 0), a2, voffA);
;             PG8_WAIT_V(8); PG8_WAIT_L(0); PG8_BAR; PG8_MMA(1, 0, At, B0); PG8_MMA(1, 1, At, B1); PG8_BAR; PG8_SCHED;
;             PG8_LDB(B0, 1, 0); PG8_LDB(B1, 1, 1); PG8_SCHED; PG8_LDA(At, 1, 0); PG8_STAGE(PG8_SA(0, 1), a2 + hstep, voffA);
;             PG8_WAIT_V(8); PG8_WAIT_L(0); PG8_BAR; PG8_MMA(0, 0, At, B0); PG8_MMA(0, 1, At, B1); PG8_BAR; PG8_SCHED;
;             PG8_LDA(At, 1, 1); PG8_STAGE(PG8_SB(1, 0), b3, voffB); PG8_STAGE(PG8_SB(1, 1), b3 + hstep, voffB); PG8_STAGE(PG8_SA(1, 0), a3, voffA);
;             PG8_WAIT_V(8); PG8_WAIT_L(0); PG8_BAR; PG8_MMA(1, 0, At, B0); PG8_MMA(1, 1, At, B1); PG8_BAR; PG8_SCHED;
	s_setprio 1
	s_waitcnt lgkmcnt(0)
	v_mfma_f32_16x16x32_bf16 v[60:63], v[128:131], v[178:181], v[60:63]
	v_mfma_f32_16x16x32_bf16 v[56:59], v[136:139], v[178:181], v[56:59]
	v_mfma_f32_16x16x32_bf16 v[44:47], v[128:131], v[186:189], v[44:47]
	v_mfma_f32_16x16x32_bf16 v[40:43], v[136:139], v[186:189], v[40:43]
	v_mfma_f32_16x16x32_bf16 v[28:31], v[128:131], v[202:205], v[28:31]
	v_mfma_f32_16x16x32_bf16 v[24:27], v[136:139], v[202:205], v[24:27]
	v_mfma_f32_16x16x32_bf16 v[12:15], v[128:131], v[210:213], v[12:15]
	v_mfma_f32_16x16x32_bf16 v[8:11], v[136:139], v[210:213], v[8:11]
	v_mfma_f32_16x16x32_bf16 v[60:63], v[132:135], v[182:185], v[60:63]
	v_mfma_f32_16x16x32_bf16 v[56:59], v[140:143], v[182:185], v[56:59]
	v_mfma_f32_16x16x32_bf16 v[44:47], v[132:135], v[194:197], v[44:47]
	v_mfma_f32_16x16x32_bf16 v[40:43], v[140:143], v[194:197], v[40:43]
	v_mfma_f32_16x16x32_bf16 v[28:31], v[132:135], v[206:209], v[28:31]
	v_mfma_f32_16x16x32_bf16 v[24:27], v[140:143], v[206:209], v[24:27]
	v_mfma_f32_16x16x32_bf16 v[12:15], v[132:135], v[214:217], v[12:15]
	v_mfma_f32_16x16x32_bf16 v[8:11], v[140:143], v[214:217], v[8:11]
	s_setprio 0
	s_setprio 1
	v_mfma_f32_16x16x32_bf16 v[52:55], v[144:147], v[178:181], v[52:55]
	v_mfma_f32_16x16x32_bf16 v[48:51], v[164:167], v[178:181], v[48:51]
	v_mfma_f32_16x16x32_bf16 v[36:39], v[144:147], v[186:189], v[36:39]
	v_mfma_f32_16x16x32_bf16 v[32:35], v[164:167], v[186:189], v[32:35]
	v_mfma_f32_16x16x32_bf16 v[20:23], v[144:147], v[202:205], v[20:23]
	v_mfma_f32_16x16x32_bf16 v[16:19], v[164:167], v[202:205], v[16:19]
	v_mfma_f32_16x16x32_bf16 v[4:7], v[144:147], v[210:213], v[4:7]
	v_mfma_f32_16x16x32_bf16 v[0:3], v[164:167], v[210:213], v[0:3]
	v_mfma_f32_16x16x32_bf16 v[52:55], v[148:151], v[182:185], v[52:55]
	v_mfma_f32_16x16x32_bf16 v[48:51], v[174:177], v[182:185], v[48:51]
	v_mfma_f32_16x16x32_bf16 v[36:39], v[148:151], v[194:197], v[36:39]
	v_mfma_f32_16x16x32_bf16 v[32:35], v[174:177], v[194:197], v[32:35]
	v_mfma_f32_16x16x32_bf16 v[20:23], v[148:151], v[206:209], v[20:23]
	v_mfma_f32_16x16x32_bf16 v[16:19], v[174:177], v[206:209], v[16:19]
	s_barrier
	s_setprio 2
	v_mfma_f32_16x16x32_bf16 v[4:7], v[148:151], v[214:217], v[4:7]
	v_mfma_f32_16x16x32_bf16 v[0:3], v[174:177], v[214:217], v[0:3]
	s_setprio 0
	s_add_i32 s65, s65, 2
	s_add_u32 s36, s36, 0x100
	s_addc_u32 s37, s37, 0
	s_add_u32 s63, s63, 0x100
	s_addc_u32 s64, s64, 0
	s_cmp_gt_u32 s65, 29
	s_branch .LBB0_635
.LBB0_635:
	v_add_u32_e32 v140, 0x10000, v172
	v_add_u32_e32 v168, 0x14000, v172
	ds_read_b128 v[128:131], v140
	ds_read_b128 v[132:135], v140 offset:1024
	ds_read_b128 v[136:139], v140 offset:2048
	ds_read_b128 v[140:143], v140 offset:3072
	ds_read_b128 v[144:147], v168
	ds_read_b128 v[148:151], v168 offset:1024
	ds_read_b128 v[164:167], v168 offset:2048
	ds_read_b128 v[174:177], v168 offset:3072
	v_lshl_add_u64 v[168:169], s[36:37], 0, v[160:161]
	s_add_i32 m0, s2, 0xc000
	ds_read_b128 v[178:181], v173
	ds_read_b128 v[182:185], v173 offset:1024
	ds_read_b128 v[186:189], v173 offset:2048
	ds_read_b128 v[194:197], v173 offset:3072
	ds_read_b128 v[202:205], v173 offset:4096
	ds_read_b128 v[206:209], v173 offset:5120
	ds_read_b128 v[210:213], v173 offset:6144
	ds_read_b128 v[214:217], v173 offset:7168
	global_load_lds_dwordx4 v[168:169], off
	s_add_i32 m0, s2, 0xe000
	v_lshl_add_u64 v[168:169], s[36:37], 0, v[162:163]
	global_load_lds_dwordx4 v[168:169], off
	s_add_u32 s24, s36, 0xfff80080
	s_addc_u32 s25, s37, -1
	s_add_i32 s33, 0, 0x10000
	s_cmp_eq_u32 s65, 28
	s_cselect_b32 s43, s15, s25
	s_cselect_b32 s42, s61, s24
	s_cselect_b32 s39, s13, s64
	s_cselect_b32 s38, s62, s63
	s_add_i32 s24, 0, 0x14000
	s_waitcnt vmcnt(8)
	s_waitcnt lgkmcnt(0)
	s_barrier
	s_setprio 1
	s_waitcnt lgkmcnt(0)
	v_mfma_f32_16x16x32_bf16 v[124:127], v[128:131], v[178:181], v[124:127]
	v_mfma_f32_16x16x32_bf16 v[120:123], v[136:139], v[178:181], v[120:123]
	v_mfma_f32_16x16x32_bf16 v[108:111], v[128:131], v[186:189], v[108:111]
	v_mfma_f32_16x16x32_bf16 v[104:107], v[136:139], v[186:189], v[104:107]
	v_mfma_f32_16x16x32_bf16 v[92:95], v[128:131], v[202:205], v[92:95]
	v_mfma_f32_16x16x32_bf16 v[88:91], v[136:139], v[202:205], v[88:91]
	v_mfma_f32_16x16x32_bf16 v[76:79], v[128:131], v[210:213], v[76:79]
	v_mfma_f32_16x16x32_bf16 v[72:75], v[136:139], v[210:213], v[72:75]
	v_mfma_f32_16x16x32_bf16 v[124:127], v[132:135], v[182:185], v[124:127]
	v_mfma_f32_16x16x32_bf16 v[120:123], v[140:143], v[182:185], v[120:123]
	v_mfma_f32_16x16x32_bf16 v[108:111], v[132:135], v[194:197], v[108:111]
	v_mfma_f32_16x16x32_bf16 v[104:107], v[140:143], v[194:197], v[104:107]
	v_mfma_f32_16x16x32_bf16 v[92:95], v[132:135], v[206:209], v[92:95]
	v_mfma_f32_16x16x32_bf16 v[88:91], v[140:143], v[206:209], v[88:91]
	v_mfma_f32_16x16x32_bf16 v[76:79], v[132:135], v[214:217], v[76:79]
	v_mfma_f32_16x16x32_bf16 v[72:75], v[140:143], v[214:217], v[72:75]
	s_setprio 0
	s_setprio 1
	v_mfma_f32_16x16x32_bf16 v[116:119], v[144:147], v[178:181], v[116:119]
	v_mfma_f32_16x16x32_bf16 v[112:115], v[164:167], v[178:181], v[112:115]
	v_mfma_f32_16x16x32_bf16 v[100:103], v[144:147], v[186:189], v[100:103]
	v_mfma_f32_16x16x32_bf16 v[96:99], v[164:167], v[186:189], v[96:99]
	v_mfma_f32_16x16x32_bf16 v[84:87], v[144:147], v[202:205], v[84:87]
	v_mfma_f32_16x16x32_bf16 v[80:83], v[164:167], v[202:205], v[80:83]
	v_mfma_f32_16x16x32_bf16 v[68:71], v[144:147], v[210:213], v[68:71]
	v_mfma_f32_16x16x32_bf16 v[64:67], v[164:167], v[210:213], v[64:67]
	v_mfma_f32_16x16x32_bf16 v[116:119], v[148:151], v[182:185], v[116:119]
	v_mfma_f32_16x16x32_bf16 v[112:115], v[174:177], v[182:185], v[112:115]
	v_mfma_f32_16x16x32_bf16 v[100:103], v[148:151], v[194:197], v[100:103]
	v_mfma_f32_16x16x32_bf16 v[96:99], v[174:177], v[194:197], v[96:99]
	v_mfma_f32_16x16x32_bf16 v[84:87], v[148:151], v[206:209], v[84:87]
	v_mfma_f32_16x16x32_bf16 v[80:83], v[174:177], v[206:209], v[80:83]
	s_barrier
; #define PG8_STAGE(bufoff, gbase, voff) do { _Pragma("unroll") for (int _i = 0; _i < 2; ++_i) \
;         __builtin_amdgcn_global_load_lds((const unsigned*)((const char*)(gbase) + (voff)[_i]), (PG8_LAS unsigned*)(lds + (bufoff) + ldsw + _i * 8192), 16, 0, 0); } while (0)
; #define PG8_LDA(dst, b, h) do { _Pragma("unroll") for (int m = 0; m < 4; ++m) _Pragma("unroll") for (int k = 0; k < 2; ++k) dst[m][k] = *(const PG8_LAS bf16x8*)(lds + PG8_SA(b, h) + aoff + m * 2048 + k * 1024); } while (0)
; #define PG8_LDB(dst, b, h) do { _Pragma("unroll") for (int n = 0; n < 2; ++n) _Pragma("unroll") for (int k = 0; k < 2; ++k) dst[n][k] = *(const PG8_LAS bf16x8*)(lds + PG8_SB(b, h) + boff + n * 2048 + k * 1024); } while (0)
; #define PG8_MMA(ai, bj, At, Bt) do { __builtin_amdgcn_s_setprio(1); _Pragma("unroll") for (int m = 0; m < 4; ++m) _Pragma("unroll") for (int n = 0; n < 2; ++n) _Pragma("unroll") for (int k = 0; k < 2; ++k) \
;         acc[ai][bj][m][n] = __builtin_amdgcn_mfma_f32_16x16x32_bf16(Bt[n][k], At[m][k], acc[ai][bj][m][n], 0, 0, 0); __builtin_amdgcn_s_setprio(0); } while (0)
; #define PG8_WAIT_V(n) asm volatile("s_waitcnt vmcnt(" #n ")" ::: "memory")
; #define PG8_WAIT_L(n) asm volatile("s_waitcnt lgkmcnt(" #n ")" ::: "memory")
; #define PG8_BAR __builtin_amdgcn_s_barrier()
; #define PG8_SCHED __builtin_amdgcn_sched_barrier(0)
; template <class Epi, class Sched, bool ALIGN_EPI = false, bool SP2 = false>
; __device__ __forceinline__ void gemm_phase(PG8_LAS unsigned char* lds, const Gemm g, const Sched& S, const Epi& E) {
;     ...
;             PG8_WAIT_V(8); PG8_WAIT_L(0); PG8_BAR; PG8_MMA(0, 0, At, B0); PG8_MMA(0, 1, At, B1); PG8_BAR; PG8_SCHED;
;             PG8_LDA(At, 0, 1); PG8_STAGE(PG8_SB(0, 0), b2, voffB); PG8_STAGE(PG8_SB(0, 1), b2 + hstep, voffB); PG8_STAGE(PG8_SA(0, 0), a2, voffA);
;             PG8_WAIT_V(8); PG8_WAIT_L(0); PG8_BAR; PG8_MMA(1, 0, At, B0); PG8_MMA(1, 1, At, B1); PG8_BAR; PG8_SCHED;
;             PG8_LDB(B0, 1, 0); PG8_LDB(B1, 1, 1); PG8_SCHED; PG8_LDA(At, 1, 0); PG8_STAGE(PG8_SA(0, 1), a2 + hstep, voffA);
	s_setprio 2
	v_mfma_f32_16x16x32_bf16 v[68:71], v[148:151], v[214:217], v[68:71]
	v_mfma_f32_16x16x32_bf16 v[64:67], v[174:177], v[214:217], v[64:67]
	s_setprio 0
	s_add_i32 s25, s33, s47
	v_lshl_add_u64 v[168:169], s[38:39], 0, v[156:157]
	s_mov_b32 m0, s25
	ds_read_b128 v[178:181], v173 offset:16384
	ds_read_b128 v[182:185], v173 offset:17408
	ds_read_b128 v[186:189], v173 offset:18432
	ds_read_b128 v[194:197], v173 offset:19456
	ds_read_b128 v[202:205], v173 offset:20480
	ds_read_b128 v[206:209], v173 offset:21504
	ds_read_b128 v[210:213], v173 offset:22528
	ds_read_b128 v[214:217], v173 offset:23552
	global_load_lds_dwordx4 v[168:169], off
	s_add_i32 m0, s25, 0x2000
	s_add_u32 s66, s38, 0x80000
	v_lshl_add_u64 v[190:191], s[38:39], 0, v[152:153]
	s_addc_u32 s67, s39, 0
	s_add_i32 s24, s24, s47
	global_load_lds_dwordx4 v[190:191], off
	v_lshl_add_u64 v[218:219], s[66:67], 0, v[156:157]
	s_mov_b32 m0, s24
	v_lshl_add_u64 v[220:221], s[42:43], 0, v[154:155]
	global_load_lds_dwordx4 v[218:219], off
	s_add_i32 m0, s24, 0x2000
	v_lshl_add_u64 v[218:219], s[66:67], 0, v[152:153]
	global_load_lds_dwordx4 v[218:219], off
	s_mov_b32 m0, s2
	v_lshl_add_u64 v[218:219], s[42:43], 0, v[158:159]
	global_load_lds_dwordx4 v[218:219], off
	s_mov_b32 m0, s48
	s_nop 0
	global_load_lds_dwordx4 v[220:221], off
	s_waitcnt vmcnt(8)
	s_waitcnt lgkmcnt(0)
	s_barrier
	s_setprio 1
	s_waitcnt lgkmcnt(0)
	v_mfma_f32_16x16x32_bf16 v[60:63], v[128:131], v[178:181], v[60:63]
	v_mfma_f32_16x16x32_bf16 v[56:59], v[136:139], v[178:181], v[56:59]
	v_mfma_f32_16x16x32_bf16 v[44:47], v[128:131], v[186:189], v[44:47]
	v_mfma_f32_16x16x32_bf16 v[40:43], v[136:139], v[186:189], v[40:43]
	v_mfma_f32_16x16x32_bf16 v[28:31], v[128:131], v[202:205], v[28:31]
	v_mfma_f32_16x16x32_bf16 v[24:27], v[136:139], v[202:205], v[24:27]
	v_mfma_f32_16x16x32_bf16 v[12:15], v[128:131], v[210:213], v[12:15]
	v_mfma_f32_16x16x32_bf16 v[8:11], v[136:139], v[210:213], v[8:11]
	v_mfma_f32_16x16x32_bf16 v[60:63], v[132:135], v[182:185], v[60:63]
	v_mfma_f32_16x16x32_bf16 v[56:59], v[140:143], v[182:185], v[56:59]
	v_mfma_f32_16x16x32_bf16 v[44:47], v[132:135], v[194:197], v[44:47]
	v_mfma_f32_16x16x32_bf16 v[40:43], v[140:143], v[194:197], v[40:43]
	v_mfma_f32_16x16x32_bf16 v[28:31], v[132:135], v[206:209], v[28:31]
	v_mfma_f32_16x16x32_bf16 v[24:27], v[140:143], v[206:209], v[24:27]
	v_mfma_f32_16x16x32_bf16 v[12:15], v[132:135], v[214:217], v[12:15]
	v_mfma_f32_16x16x32_bf16 v[8:11], v[140:143], v[214:217], v[8:11]
	s_setprio 0
	s_setprio 1
	v_mfma_f32_16x16x32_bf16 v[52:55], v[144:147], v[178:181], v[52:55]
	v_mfma_f32_16x16x32_bf16 v[48:51], v[164:167], v[178:181], v[48:51]
	v_mfma_f32_16x16x32_bf16 v[36:39], v[144:147], v[186:189], v[36:39]
	v_mfma_f32_16x16x32_bf16 v[32:35], v[164:167], v[186:189], v[32:35]
	v_mfma_f32_16x16x32_bf16 v[20:23], v[144:147], v[202:205], v[20:23]
	v_mfma_f32_16x16x32_bf16 v[16:19], v[164:167], v[202:205], v[16:19]
	v_mfma_f32_16x16x32_bf16 v[4:7], v[144:147], v[210:213], v[4:7]
	v_mfma_f32_16x16x32_bf16 v[0:3], v[164:167], v[210:213], v[0:3]
	v_mfma_f32_16x16x32_bf16 v[52:55], v[148:151], v[182:185], v[52:55]
	v_mfma_f32_16x16x32_bf16 v[48:51], v[174:177], v[182:185], v[48:51]
	v_mfma_f32_16x16x32_bf16 v[36:39], v[148:151], v[194:197], v[36:39]
	v_mfma_f32_16x16x32_bf16 v[32:35], v[174:177], v[194:197], v[32:35]
	v_mfma_f32_16x16x32_bf16 v[20:23], v[148:151], v[206:209], v[20:23]
	v_mfma_f32_16x16x32_bf16 v[16:19], v[174:177], v[206:209], v[16:19]
	s_barrier
	s_setprio 2
	v_mfma_f32_16x16x32_bf16 v[4:7], v[148:151], v[214:217], v[4:7]
	v_mfma_f32_16x16x32_bf16 v[0:3], v[174:177], v[214:217], v[0:3]
	s_setprio 0
	s_add_i32 s24, 0, 0x18000
	s_add_i32 s25, 0, 0x1c000
	v_add_u32_e32 v140, 0x18000, v172
	v_add_u32_e32 v174, 0x1c000, v172
	ds_read_b128 v[128:131], v140
	ds_read_b128 v[132:135], v140 offset:1024
	ds_read_b128 v[136:139], v140 offset:2048
	ds_read_b128 v[140:143], v140 offset:3072
	ds_read_b128 v[144:147], v174
	ds_read_b128 v[148:151], v174 offset:1024
	ds_read_b128 v[164:167], v174 offset:2048
	ds_read_b128 v[174:177], v174 offset:3072
	s_add_u32 s42, s42, 0x80000
	s_addc_u32 s43, s43, 0
	s_mov_b32 m0, s49
	v_lshl_add_u64 v[230:231], s[42:43], 0, v[158:159]
	ds_read_b128 v[178:181], v173 offset:32768
	ds_read_b128 v[182:185], v173 offset:33792
	ds_read_b128 v[186:189], v173 offset:34816
	ds_read_b128 v[194:197], v173 offset:35840
	ds_read_b128 v[202:205], v173 offset:36864
	ds_read_b128 v[206:209], v173 offset:37888
	ds_read_b128 v[210:213], v173 offset:38912
	ds_read_b128 v[214:217], v173 offset:39936
	global_load_lds_dwordx4 v[230:231], off
	s_mov_b32 m0, s50
	v_lshl_add_u64 v[230:231], s[42:43], 0, v[154:155]
	global_load_lds_dwordx4 v[230:231], off
	s_waitcnt vmcnt(8)
	s_waitcnt lgkmcnt(0)
	s_barrier
; #define PG8_STAGE(bufoff, gbase, voff) do { _Pragma("unroll") for (int _i = 0; _i < 2; ++_i) \
;         __builtin_amdgcn_global_load_lds((const unsigned*)((const char*)(gbase) + (voff)[_i]), (PG8_LAS unsigned*)(lds + (bufoff) + ldsw + _i * 8192), 16, 0, 0); } while (0)
; #define PG8_LDA(dst, b, h) do { _Pragma("unroll") for (int m = 0; m < 4; ++m) _Pragma("unroll") for (int k = 0; k < 2; ++k) dst[m][k] = *(const PG8_LAS bf16x8*)(lds + PG8_SA(b, h) + aoff + m * 2048 + k * 1024); } while (0)
; #define PG8_MMA(ai, bj, At, Bt) do { __builtin_amdgcn_s_setprio(1); _Pragma("unroll") for (int m = 0; m < 4; ++m) _Pragma("unroll") for (int n = 0; n < 2; ++n) _Pragma("unroll") for (int k = 0; k < 2; ++k) \
;         acc[ai][bj][m][n] = __builtin_amdgcn_mfma_f32_16x16x32_bf16(Bt[n][k], At[m][k], acc[ai][bj][m][n], 0, 0, 0); __builtin_amdgcn_s_setprio(0); } while (0)
; #define PG8_WAIT_V(n) asm volatile("s_waitcnt vmcnt(" #n ")" ::: "memory")
; #define PG8_WAIT_L(n) asm volatile("s_waitcnt lgkmcnt(" #n ")" ::: "memory")
; #define PG8_BAR __builtin_amdgcn_s_barrier()
; #define PG8_SCHED __builtin_amdgcn_sched_barrier(0)
; template <class Epi, class Sched, bool ALIGN_EPI = false, bool SP2 = false>
; __device__ __forceinline__ void gemm_phase(PG8_LAS unsigned char* lds, const Gemm g, const Sched& S, const Epi& E) {
;     ...
;             PG8_WAIT_V(8); PG8_WAIT_L(0); PG8_BAR; PG8_MMA(0, 0, At, B0); PG8_MMA(0, 1, At, B1); PG8_BAR; PG8_SCHED;
;             PG8_LDA(At, 1, 1); PG8_STAGE(PG8_SB(1, 0), b3, voffB); PG8_STAGE(PG8_SB(1, 1), b3 + hstep, voffB); PG8_STAGE(PG8_SA(1, 0), a3, voffA);
;             PG8_WAIT_V(8); PG8_WAIT_L(0); PG8_BAR; PG8_MMA(1, 0, At, B0); PG8_MMA(1, 1, At, B1); PG8_BAR; PG8_SCHED;
	s_setprio 1
	s_waitcnt lgkmcnt(0)
	v_mfma_f32_16x16x32_bf16 v[124:127], v[128:131], v[178:181], v[124:127]
	v_mfma_f32_16x16x32_bf16 v[120:123], v[136:139], v[178:181], v[120:123]
	v_mfma_f32_16x16x32_bf16 v[108:111], v[128:131], v[186:189], v[108:111]
	v_mfma_f32_16x16x32_bf16 v[104:107], v[136:139], v[186:189], v[104:107]
	v_mfma_f32_16x16x32_bf16 v[92:95], v[128:131], v[202:205], v[92:95]
	v_mfma_f32_16x16x32_bf16 v[88:91], v[136:139], v[202:205], v[88:91]
	v_mfma_f32_16x16x32_bf16 v[76:79], v[128:131], v[210:213], v[76:79]
	v_mfma_f32_16x16x32_bf16 v[72:75], v[136:139], v[210:213], v[72:75]
	v_mfma_f32_16x16x32_bf16 v[124:127], v[132:135], v[182:185], v[124:127]
	v_mfma_f32_16x16x32_bf16 v[120:123], v[140:143], v[182:185], v[120:123]
	v_mfma_f32_16x16x32_bf16 v[108:111], v[132:135], v[194:197], v[108:111]
	v_mfma_f32_16x16x32_bf16 v[104:107], v[140:143], v[194:197], v[104:107]
	v_mfma_f32_16x16x32_bf16 v[92:95], v[132:135], v[206:209], v[92:95]
	v_mfma_f32_16x16x32_bf16 v[88:91], v[140:143], v[206:209], v[88:91]
	v_mfma_f32_16x16x32_bf16 v[76:79], v[132:135], v[214:217], v[76:79]
	v_mfma_f32_16x16x32_bf16 v[72:75], v[140:143], v[214:217], v[72:75]
	s_setprio 0
	s_setprio 1
	v_mfma_f32_16x16x32_bf16 v[116:119], v[144:147], v[178:181], v[116:119]
	v_mfma_f32_16x16x32_bf16 v[112:115], v[164:167], v[178:181], v[112:115]
	v_mfma_f32_16x16x32_bf16 v[100:103], v[144:147], v[186:189], v[100:103]
	v_mfma_f32_16x16x32_bf16 v[96:99], v[164:167], v[186:189], v[96:99]
	v_mfma_f32_16x16x32_bf16 v[84:87], v[144:147], v[202:205], v[84:87]
	v_mfma_f32_16x16x32_bf16 v[80:83], v[164:167], v[202:205], v[80:83]
	v_mfma_f32_16x16x32_bf16 v[68:71], v[144:147], v[210:213], v[68:71]
	v_mfma_f32_16x16x32_bf16 v[64:67], v[164:167], v[210:213], v[64:67]
	v_mfma_f32_16x16x32_bf16 v[116:119], v[148:151], v[182:185], v[116:119]
	v_mfma_f32_16x16x32_bf16 v[112:115], v[174:177], v[182:185], v[112:115]
	v_mfma_f32_16x16x32_bf16 v[100:103], v[148:151], v[194:197], v[100:103]
	v_mfma_f32_16x16x32_bf16 v[96:99], v[174:177], v[194:197], v[96:99]
	v_mfma_f32_16x16x32_bf16 v[84:87], v[148:151], v[206:209], v[84:87]
	v_mfma_f32_16x16x32_bf16 v[80:83], v[174:177], v[206:209], v[80:83]
	s_barrier
	s_setprio 2
	v_mfma_f32_16x16x32_bf16 v[68:71], v[148:151], v[214:217], v[68:71]
	v_mfma_f32_16x16x32_bf16 v[64:67], v[174:177], v[214:217], v[64:67]
	s_setprio 0
	s_add_i32 s24, s24, s47
	v_lshl_add_u64 v[168:169], v[168:169], 0, s[16:17]
	s_mov_b32 m0, s24
	ds_read_b128 v[178:181], v173 offset:49152
	ds_read_b128 v[182:185], v173 offset:50176
	ds_read_b128 v[186:189], v173 offset:51200
	ds_read_b128 v[194:197], v173 offset:52224
	ds_read_b128 v[202:205], v173 offset:53248
	ds_read_b128 v[206:209], v173 offset:54272
	ds_read_b128 v[210:213], v173 offset:55296
	ds_read_b128 v[214:217], v173 offset:56320
	global_load_lds_dwordx4 v[168:169], off
	s_add_i32 m0, s24, 0x2000
	s_add_u32 s38, s38, 0x80080
	v_lshl_add_u64 v[168:169], v[190:191], 0, s[16:17]
	s_addc_u32 s39, s39, 0
	s_add_i32 s24, s25, s47
	global_load_lds_dwordx4 v[168:169], off
	s_mov_b32 m0, s24
	v_lshl_add_u64 v[168:169], s[38:39], 0, v[156:157]
	global_load_lds_dwordx4 v[168:169], off
	s_add_i32 m0, s24, 0x2000
	v_lshl_add_u64 v[168:169], s[38:39], 0, v[152:153]
	global_load_lds_dwordx4 v[168:169], off
	s_mov_b32 m0, s55
	v_lshl_add_u64 v[168:169], v[218:219], 0, s[16:17]
	global_load_lds_dwordx4 v[168:169], off
	s_mov_b32 m0, s56
	v_lshl_add_u64 v[168:169], v[220:221], 0, s[16:17]
	global_load_lds_dwordx4 v[168:169], off
	s_waitcnt vmcnt(8)
	s_waitcnt lgkmcnt(0)
	s_barrier
	s_setprio 1
	s_waitcnt lgkmcnt(0)
	v_mfma_f32_16x16x32_bf16 v[60:63], v[128:131], v[178:181], v[60:63]
	v_mfma_f32_16x16x32_bf16 v[56:59], v[136:139], v[178:181], v[56:59]
	v_mfma_f32_16x16x32_bf16 v[44:47], v[128:131], v[186:189], v[44:47]
	v_mfma_f32_16x16x32_bf16 v[40:43], v[136:139], v[186:189], v[40:43]
	v_mfma_f32_16x16x32_bf16 v[28:31], v[128:131], v[202:205], v[28:31]
	v_mfma_f32_16x16x32_bf16 v[24:27], v[136:139], v[202:205], v[24:27]
	v_mfma_f32_16x16x32_bf16 v[12:15], v[128:131], v[210:213], v[12:15]
	v_mfma_f32_16x16x32_bf16 v[8:11], v[136:139], v[210:213], v[8:11]
	v_mfma_f32_16x16x32_bf16 v[60:63], v[132:135], v[182:185], v[60:63]
	v_mfma_f32_16x16x32_bf16 v[56:59], v[140:143], v[182:185], v[56:59]
	v_mfma_f32_16x16x32_bf16 v[44:47], v[132:135], v[194:197], v[44:47]
	v_mfma_f32_16x16x32_bf16 v[40:43], v[140:143], v[194:197], v[40:43]
	v_mfma_f32_16x16x32_bf16 v[28:31], v[132:135], v[206:209], v[28:31]
	v_mfma_f32_16x16x32_bf16 v[24:27], v[140:143], v[206:209], v[24:27]
	v_mfma_f32_16x16x32_bf16 v[12:15], v[132:135], v[214:217], v[12:15]
	v_mfma_f32_16x16x32_bf16 v[8:11], v[140:143], v[214:217], v[8:11]
	s_setprio 0
	s_setprio 1
	v_mfma_f32_16x16x32_bf16 v[52:55], v[144:147], v[178:181], v[52:55]
	v_mfma_f32_16x16x32_bf16 v[48:51], v[164:167], v[178:181], v[48:51]
	v_mfma_f32_16x16x32_bf16 v[36:39], v[144:147], v[186:189], v[36:39]
	v_mfma_f32_16x16x32_bf16 v[32:35], v[164:167], v[186:189], v[32:35]
	v_mfma_f32_16x16x32_bf16 v[20:23], v[144:147], v[202:205], v[20:23]
	v_mfma_f32_16x16x32_bf16 v[16:19], v[164:167], v[202:205], v[16:19]
	v_mfma_f32_16x16x32_bf16 v[4:7], v[144:147], v[210:213], v[4:7]
	v_mfma_f32_16x16x32_bf16 v[0:3], v[164:167], v[210:213], v[0:3]
	v_mfma_f32_16x16x32_bf16 v[52:55], v[148:151], v[182:185], v[52:55]
	v_mfma_f32_16x16x32_bf16 v[48:51], v[174:177], v[182:185], v[48:51]
	v_mfma_f32_16x16x32_bf16 v[36:39], v[148:151], v[194:197], v[36:39]
	v_mfma_f32_16x16x32_bf16 v[32:35], v[174:177], v[194:197], v[32:35]
	v_mfma_f32_16x16x32_bf16 v[20:23], v[148:151], v[206:209], v[20:23]
	v_mfma_f32_16x16x32_bf16 v[16:19], v[174:177], v[206:209], v[16:19]
	s_barrier
	s_setprio 2
	v_mfma_f32_16x16x32_bf16 v[4:7], v[148:151], v[214:217], v[4:7]
	v_mfma_f32_16x16x32_bf16 v[0:3], v[174:177], v[214:217], v[0:3]
	s_setprio 0
	s_add_i32 s65, s65, 2
	s_add_u32 s36, s36, 0x100
	s_addc_u32 s37, s37, 0
	s_add_u32 s63, s63, 0x100
	s_addc_u32 s64, s64, 0
	s_cmp_gt_u32 s65, 29
	s_cbranch_scc0 .LBB0_635
	s_and_b64 vcc, exec, s[10:11]
	s_cbranch_vccz .LBB0_638
	s_barrier

; #define PG8_STAGE(bufoff, gbase, voff) do { _Pragma("unroll") for (int _i = 0; _i < 2; ++_i) \
;         __builtin_amdgcn_global_load_lds((const unsigned*)((const char*)(gbase) + (voff)[_i]), (PG8_LAS unsigned*)(lds + (bufoff) + ldsw + _i * 8192), 16, 0, 0); } while (0)
; #define PG8_LDA(dst, b, h) do { _Pragma("unroll") for (int m = 0; m < 4; ++m) _Pragma("unroll") for (int k = 0; k < 2; ++k) dst[m][k] = *(const PG8_LAS bf16x8*)(lds + PG8_SA(b, h) + aoff + m * 2048 + k * 1024); } while (0)
; #define PG8_LDB(dst, b, h) do { _Pragma("unroll") for (int n = 0; n < 2; ++n) _Pragma("unroll") for (int k = 0; k < 2; ++k) dst[n][k] = *(const PG8_LAS bf16x8*)(lds + PG8_SB(b, h) + boff + n * 2048 + k * 1024); } while (0)
; #define PG8_WAIT_V(n) asm volatile("s_waitcnt vmcnt(" #n ")" ::: "memory")
; #define PG8_WAIT_L(n) asm volatile("s_waitcnt lgkmcnt(" #n ")" ::: "memory")
; #define PG8_BAR __builtin_amdgcn_s_barrier()
; #define PG8_SCHED __builtin_amdgcn_sched_barrier(0)
; template <class Epi, class Sched, bool ALIGN_EPI = false, bool SP2 = false>
; __device__ __forceinline__ void gemm_phase(PG8_LAS unsigned char* lds, const Gemm g, const Sched& S, const Epi& E) {
;     ...
;         const char* nA = has_next ? (const char*)g.A + (size_t)nxt.pm * tstep : cA; const char* nB = has_next ? (const char*)g.Bt + (size_t)nxt.pn * tstep : cB;
;         for (int t = 0; t < nt; t += 2) {
;             if constexpr (Epi::MID_HOOK) { if (t == Epi::MID_T) E.mid(acc, cur, wr, wc, fr, fq); }
;             const bool last = (t == nt - 2);
;             const char* a1 = cA + (size_t)(t + 1) * kstep;
;             const char* a2 = last ? nA : cA + (size_t)(t + 2) * kstep; const char* b2 = last ? nB : cB + (size_t)(t + 2) * kstep;
;             const char* a3 = a2 + kstep; const char* b3 = b2 + kstep;
;             if (last && has_next) S.a_ready(nxt);
;             if constexpr (SP2) {
;             PG8_LDB(B0, 0, 0); PG8_LDB(B1, 0, 1); PG8_SCHED; PG8_LDA(At, 0, 0); PG8_STAGE(PG8_SA(1, 1), a1 + hstep, voffA);
;             PG8_WAIT_V(8); PG8_WAIT_L(0); PG8_BAR; PG8_MMA(0, 0, At, B0); PG8_MMA(0, 1, At, B1); PG8_BAR; PG8_SCHED;
;             PG8_LDA(At, 0, 1); PG8_STAGE(PG8_SB(0, 0), b2, voffB); PG8_STAGE(PG8_SB(0, 1), b2 + hstep, voffB); PG8_STAGE(PG8_SA(0, 0), a2, voffA);
;             PG8_WAIT_V(8); PG8_WAIT_L(0); PG8_BAR; PG8_MMA(1, 0, At, B0); PG8_MMA(1, 1, At, B1); PG8_BAR; PG8_SCHED;
.LBB0_729:
	s_ashr_i32 s49, s48, 31
	s_lshl_b64 s[12:13], s[48:49], 20
	s_add_u32 s50, s18, s12
	s_addc_u32 s51, s19, s13
	s_and_b64 s[12:13], s[42:43], exec
	s_cselect_b32 s49, s51, s1
	s_cselect_b32 s60, s50, s0
	s_ashr_i32 s47, s46, 31
	s_lshl_b64 s[12:13], s[46:47], 20
	s_add_u32 s52, s14, s12
	s_addc_u32 s53, s15, s13
	s_and_b64 s[12:13], s[42:43], exec
	s_cselect_b32 s47, s53, s11
	s_cselect_b32 s61, s52, s10
	s_add_u32 s0, s0, 0x80080
	s_addc_u32 s1, s1, 0
	s_add_u32 s62, s10, 0x100
	s_addc_u32 s63, s11, 0
	s_mov_b32 s64, -2
	v_lshl_add_u64 v[190:191], s[0:1], 0, v[136:137]
	s_add_i32 m0, s31, 0xc000
	global_load_lds_dwordx4 v[190:191], off
	s_add_i32 m0, s31, 0xe000
	v_lshl_add_u64 v[190:191], s[0:1], 0, v[138:139]
	global_load_lds_dwordx4 v[190:191], off
	s_add_u32 s10, s0, 0xfff80080
	s_addc_u32 s11, s1, -1
	s_add_i32 s24, 0, 0x10000
	s_cmp_eq_u32 s64, 28
	s_cselect_b32 s13, s49, s11
	s_cselect_b32 s12, s60, s10
	s_cselect_b32 s11, s47, s63
	s_cselect_b32 s10, s61, s62
	s_add_i32 s25, 0, 0x14000
	s_waitcnt vmcnt(8)
	s_waitcnt lgkmcnt(0)
	s_barrier
	s_setprio 1
	s_waitcnt lgkmcnt(0)
	v_mfma_f32_16x16x32_bf16 v[124:127], v[140:143], v[178:181], 0
	v_mfma_f32_16x16x32_bf16 v[112:115], v[154:157], v[178:181], 0
	v_mfma_f32_16x16x32_bf16 v[108:111], v[140:143], v[186:189], 0
	v_mfma_f32_16x16x32_bf16 v[100:103], v[154:157], v[186:189], 0
	v_mfma_f32_16x16x32_bf16 v[92:95], v[140:143], v[202:205], 0
	v_mfma_f32_16x16x32_bf16 v[84:87], v[154:157], v[202:205], 0
	v_mfma_f32_16x16x32_bf16 v[76:79], v[140:143], v[210:213], 0
	v_mfma_f32_16x16x32_bf16 v[68:71], v[154:157], v[210:213], 0
	v_mfma_f32_16x16x32_bf16 v[124:127], v[144:147], v[182:185], v[124:127]
	v_mfma_f32_16x16x32_bf16 v[112:115], v[158:161], v[182:185], v[112:115]
	v_mfma_f32_16x16x32_bf16 v[108:111], v[144:147], v[194:197], v[108:111]
	v_mfma_f32_16x16x32_bf16 v[100:103], v[158:161], v[194:197], v[100:103]
	v_mfma_f32_16x16x32_bf16 v[92:95], v[144:147], v[206:209], v[92:95]
	v_mfma_f32_16x16x32_bf16 v[84:87], v[158:161], v[206:209], v[84:87]
	v_mfma_f32_16x16x32_bf16 v[76:79], v[144:147], v[214:217], v[76:79]
	v_mfma_f32_16x16x32_bf16 v[68:71], v[158:161], v[214:217], v[68:71]
	s_setprio 0
	s_setprio 1
	v_mfma_f32_16x16x32_bf16 v[120:123], v[162:165], v[178:181], 0
	v_mfma_f32_16x16x32_bf16 v[116:119], v[170:173], v[178:181], 0
	v_mfma_f32_16x16x32_bf16 v[104:107], v[162:165], v[186:189], 0
	v_mfma_f32_16x16x32_bf16 v[96:99], v[170:173], v[186:189], 0
	v_mfma_f32_16x16x32_bf16 v[88:91], v[162:165], v[202:205], 0
	v_mfma_f32_16x16x32_bf16 v[80:83], v[170:173], v[202:205], 0
	v_mfma_f32_16x16x32_bf16 v[72:75], v[162:165], v[210:213], 0
	v_mfma_f32_16x16x32_bf16 v[64:67], v[170:173], v[210:213], 0
	v_mfma_f32_16x16x32_bf16 v[120:123], v[166:169], v[182:185], v[120:123]
	v_mfma_f32_16x16x32_bf16 v[116:119], v[174:177], v[182:185], v[116:119]
	v_mfma_f32_16x16x32_bf16 v[104:107], v[166:169], v[194:197], v[104:107]
	v_mfma_f32_16x16x32_bf16 v[96:99], v[174:177], v[194:197], v[96:99]
	v_mfma_f32_16x16x32_bf16 v[88:91], v[166:169], v[206:209], v[88:91]
	v_mfma_f32_16x16x32_bf16 v[80:83], v[174:177], v[206:209], v[80:83]
	s_barrier
	s_setprio 2
	v_mfma_f32_16x16x32_bf16 v[72:75], v[166:169], v[214:217], v[72:75]
	v_mfma_f32_16x16x32_bf16 v[64:67], v[174:177], v[214:217], v[64:67]
	s_setprio 0
	s_add_i32 s24, s24, s30
	v_lshl_add_u64 v[190:191], s[10:11], 0, v[132:133]
	s_mov_b32 m0, s24
	ds_read_b128 v[178:181], v152 offset:16384
	ds_read_b128 v[182:185], v152 offset:17408
	ds_read_b128 v[186:189], v152 offset:18432
	ds_read_b128 v[194:197], v152 offset:19456
	ds_read_b128 v[202:205], v152 offset:20480
	ds_read_b128 v[206:209], v152 offset:21504
	ds_read_b128 v[210:213], v152 offset:22528
	ds_read_b128 v[214:217], v152 offset:23552
	global_load_lds_dwordx4 v[190:191], off
	s_add_i32 m0, s24, 0x2000
	s_add_u32 s66, s10, 0x80000
	v_lshl_add_u64 v[218:219], s[10:11], 0, v[128:129]
	s_addc_u32 s67, s11, 0
	s_add_i32 s24, s25, s30
	global_load_lds_dwordx4 v[218:219], off
	v_lshl_add_u64 v[220:221], s[66:67], 0, v[132:133]
	s_mov_b32 m0, s24
	v_lshl_add_u64 v[230:231], s[12:13], 0, v[130:131]
	global_load_lds_dwordx4 v[220:221], off
	s_add_i32 m0, s24, 0x2000
	v_lshl_add_u64 v[220:221], s[66:67], 0, v[128:129]
	global_load_lds_dwordx4 v[220:221], off
	s_mov_b32 m0, s31
	v_lshl_add_u64 v[220:221], s[12:13], 0, v[134:135]
	global_load_lds_dwordx4 v[220:221], off
	s_mov_b32 m0, s34
	s_nop 0
	global_load_lds_dwordx4 v[230:231], off
	s_waitcnt vmcnt(8)
	s_waitcnt lgkmcnt(0)
	s_barrier
	s_setprio 1
	s_waitcnt lgkmcnt(0)
	v_mfma_f32_16x16x32_bf16 v[60:63], v[140:143], v[178:181], 0
	v_mfma_f32_16x16x32_bf16 v[52:55], v[154:157], v[178:181], 0
	v_mfma_f32_16x16x32_bf16 v[44:47], v[140:143], v[186:189], 0
	v_mfma_f32_16x16x32_bf16 v[36:39], v[154:157], v[186:189], 0
	v_mfma_f32_16x16x32_bf16 v[28:31], v[140:143], v[202:205], 0
	v_mfma_f32_16x16x32_bf16 v[20:23], v[154:157], v[202:205], 0
	v_mfma_f32_16x16x32_bf16 v[12:15], v[140:143], v[210:213], 0
	v_mfma_f32_16x16x32_bf16 v[4:7], v[154:157], v[210:213], 0
	v_mfma_f32_16x16x32_bf16 v[60:63], v[144:147], v[182:185], v[60:63]
	v_mfma_f32_16x16x32_bf16 v[52:55], v[158:161], v[182:185], v[52:55]
	v_mfma_f32_16x16x32_bf16 v[44:47], v[144:147], v[194:197], v[44:47]
	v_mfma_f32_16x16x32_bf16 v[36:39], v[158:161], v[194:197], v[36:39]
	v_mfma_f32_16x16x32_bf16 v[28:31], v[144:147], v[206:209], v[28:31]
	v_mfma_f32_16x16x32_bf16 v[20:23], v[158:161], v[206:209], v[20:23]
	v_mfma_f32_16x16x32_bf16 v[12:15], v[144:147], v[214:217], v[12:15]
	v_mfma_f32_16x16x32_bf16 v[4:7], v[158:161], v[214:217], v[4:7]
	s_setprio 0
	s_setprio 1
	v_mfma_f32_16x16x32_bf16 v[56:59], v[162:165], v[178:181], 0
	v_mfma_f32_16x16x32_bf16 v[48:51], v[170:173], v[178:181], 0
	v_mfma_f32_16x16x32_bf16 v[40:43], v[162:165], v[186:189], 0
	v_mfma_f32_16x16x32_bf16 v[32:35], v[170:173], v[186:189], 0
	v_mfma_f32_16x16x32_bf16 v[24:27], v[162:165], v[202:205], 0
	v_mfma_f32_16x16x32_bf16 v[16:19], v[170:173], v[202:205], 0
	v_mfma_f32_16x16x32_bf16 v[8:11], v[162:165], v[210:213], 0
	v_mfma_f32_16x16x32_bf16 v[0:3], v[170:173], v[210:213], 0
	v_mfma_f32_16x16x32_bf16 v[56:59], v[166:169], v[182:185], v[56:59]
	v_mfma_f32_16x16x32_bf16 v[48:51], v[174:177], v[182:185], v[48:51]
	v_mfma_f32_16x16x32_bf16 v[40:43], v[166:169], v[194:197], v[40:43]
	v_mfma_f32_16x16x32_bf16 v[32:35], v[174:177], v[194:197], v[32:35]
	v_mfma_f32_16x16x32_bf16 v[24:27], v[166:169], v[206:209], v[24:27]
	v_mfma_f32_16x16x32_bf16 v[16:19], v[174:177], v[206:209], v[16:19]
	s_barrier
; #define PG8_STAGE(bufoff, gbase, voff) do { _Pragma("unroll") for (int _i = 0; _i < 2; ++_i) \
;         __builtin_amdgcn_global_load_lds((const unsigned*)((const char*)(gbase) + (voff)[_i]), (PG8_LAS unsigned*)(lds + (bufoff) + ldsw + _i * 8192), 16, 0, 0); } while (0)
; #define PG8_LDA(dst, b, h) do { _Pragma("unroll") for (int m = 0; m < 4; ++m) _Pragma("unroll") for (int k = 0; k < 2; ++k) dst[m][k] = *(const PG8_LAS bf16x8*)(lds + PG8_SA(b, h) + aoff + m * 2048 + k * 1024); } while (0)
; #define PG8_LDB(dst, b, h) do { _Pragma("unroll") for (int n = 0; n < 2; ++n) _Pragma("unroll") for (int k = 0; k < 2; ++k) dst[n][k] = *(const PG8_LAS bf16x8*)(lds + PG8_SB(b, h) + boff + n * 2048 + k * 1024); } while (0)
; #define PG8_MMA(ai, bj, At, Bt) do { __builtin_amdgcn_s_setprio(1); _Pragma("unroll") for (int m = 0; m < 4; ++m) _Pragma("unroll") for (int n = 0; n < 2; ++n) _Pragma("unroll") for (int k = 0; k < 2; ++k) \
;         acc[ai][bj][m][n] = __builtin_amdgcn_mfma_f32_16x16x32_bf16(Bt[n][k], At[m][k], acc[ai][bj][m][n], 0, 0, 0); __builtin_amdgcn_s_setprio(0); } while (0)
; #define PG8_WAIT_V(n) asm volatile("s_waitcnt vmcnt(" #n ")" ::: "memory")
; #define PG8_WAIT_L(n) asm volatile("s_waitcnt lgkmcnt(" #n ")" ::: "memory")
; #define PG8_BAR __builtin_amdgcn_s_barrier()
; #define PG8_SCHED __builtin_amdgcn_sched_barrier(0)
; template <class Epi, class Sched, bool ALIGN_EPI = false, bool SP2 = false>
; __device__ __forceinline__ void gemm_phase(PG8_LAS unsigned char* lds, const Gemm g, const Sched& S, const Epi& E) {
;     ...
;             PG8_WAIT_V(8); PG8_WAIT_L(0); PG8_BAR; PG8_MMA(1, 0, At, B0); PG8_MMA(1, 1, At, B1); PG8_BAR; PG8_SCHED;
;             PG8_LDB(B0, 1, 0); PG8_LDB(B1, 1, 1); PG8_SCHED; PG8_LDA(At, 1, 0); PG8_STAGE(PG8_SA(0, 1), a2 + hstep, voffA);
;             PG8_WAIT_V(8); PG8_WAIT_L(0); PG8_BAR; PG8_MMA(0, 0, At, B0); PG8_MMA(0, 1, At, B1); PG8_BAR; PG8_SCHED;
;             PG8_LDA(At, 1, 1); PG8_STAGE(PG8_SB(1, 0), b3, voffB); PG8_STAGE(PG8_SB(1, 1), b3 + hstep, voffB); PG8_STAGE(PG8_SA(1, 0), a3, voffA);
	s_setprio 2
	v_mfma_f32_16x16x32_bf16 v[8:11], v[166:169], v[214:217], v[8:11]
	v_mfma_f32_16x16x32_bf16 v[0:3], v[174:177], v[214:217], v[0:3]
	s_setprio 0
	s_add_i32 s24, 0, 0x18000
	v_add_u32_e32 v148, 0x18000, v151
	s_add_i32 s25, 0, 0x1c000
	ds_read_b128 v[140:143], v148
	ds_read_b128 v[144:147], v148 offset:1024
	ds_read_b128 v[154:157], v148 offset:2048
	ds_read_b128 v[158:161], v148 offset:3072
	v_add_u32_e32 v148, 0x1c000, v151
	ds_read_b128 v[162:165], v148
	ds_read_b128 v[166:169], v148 offset:1024
	ds_read_b128 v[170:173], v148 offset:2048
	ds_read_b128 v[174:177], v148 offset:3072
	s_add_u32 s12, s12, 0x80000
	s_addc_u32 s13, s13, 0
	s_mov_b32 m0, s36
	v_lshl_add_u64 v[232:233], s[12:13], 0, v[134:135]
	ds_read_b128 v[178:181], v152 offset:32768
	ds_read_b128 v[182:185], v152 offset:33792
	ds_read_b128 v[186:189], v152 offset:34816
	ds_read_b128 v[194:197], v152 offset:35840
	ds_read_b128 v[202:205], v152 offset:36864
	ds_read_b128 v[206:209], v152 offset:37888
	ds_read_b128 v[210:213], v152 offset:38912
	ds_read_b128 v[214:217], v152 offset:39936
	global_load_lds_dwordx4 v[232:233], off
	s_mov_b32 m0, s37
	v_lshl_add_u64 v[232:233], s[12:13], 0, v[130:131]
	global_load_lds_dwordx4 v[232:233], off
	s_waitcnt vmcnt(8)
	s_waitcnt lgkmcnt(0)
	s_barrier
	s_setprio 1
	s_waitcnt lgkmcnt(0)
	v_mfma_f32_16x16x32_bf16 v[124:127], v[140:143], v[178:181], v[124:127]
	v_mfma_f32_16x16x32_bf16 v[112:115], v[154:157], v[178:181], v[112:115]
	v_mfma_f32_16x16x32_bf16 v[108:111], v[140:143], v[186:189], v[108:111]
	v_mfma_f32_16x16x32_bf16 v[100:103], v[154:157], v[186:189], v[100:103]
	v_mfma_f32_16x16x32_bf16 v[92:95], v[140:143], v[202:205], v[92:95]
	v_mfma_f32_16x16x32_bf16 v[84:87], v[154:157], v[202:205], v[84:87]
	v_mfma_f32_16x16x32_bf16 v[76:79], v[140:143], v[210:213], v[76:79]
	v_mfma_f32_16x16x32_bf16 v[68:71], v[154:157], v[210:213], v[68:71]
	v_mfma_f32_16x16x32_bf16 v[124:127], v[144:147], v[182:185], v[124:127]
	v_mfma_f32_16x16x32_bf16 v[112:115], v[158:161], v[182:185], v[112:115]
	v_mfma_f32_16x16x32_bf16 v[108:111], v[144:147], v[194:197], v[108:111]
	v_mfma_f32_16x16x32_bf16 v[100:103], v[158:161], v[194:197], v[100:103]
	v_mfma_f32_16x16x32_bf16 v[92:95], v[144:147], v[206:209], v[92:95]
	v_mfma_f32_16x16x32_bf16 v[84:87], v[158:161], v[206:209], v[84:87]
	v_mfma_f32_16x16x32_bf16 v[76:79], v[144:147], v[214:217], v[76:79]
	v_mfma_f32_16x16x32_bf16 v[68:71], v[158:161], v[214:217], v[68:71]
	s_setprio 0
	s_setprio 1
	v_mfma_f32_16x16x32_bf16 v[120:123], v[162:165], v[178:181], v[120:123]
	v_mfma_f32_16x16x32_bf16 v[116:119], v[170:173], v[178:181], v[116:119]
	v_mfma_f32_16x16x32_bf16 v[104:107], v[162:165], v[186:189], v[104:107]
	v_mfma_f32_16x16x32_bf16 v[96:99], v[170:173], v[186:189], v[96:99]
	v_mfma_f32_16x16x32_bf16 v[88:91], v[162:165], v[202:205], v[88:91]
	v_mfma_f32_16x16x32_bf16 v[80:83], v[170:173], v[202:205], v[80:83]
	v_mfma_f32_16x16x32_bf16 v[72:75], v[162:165], v[210:213], v[72:75]
	v_mfma_f32_16x16x32_bf16 v[64:67], v[170:173], v[210:213], v[64:67]
	v_mfma_f32_16x16x32_bf16 v[120:123], v[166:169], v[182:185], v[120:123]
	v_mfma_f32_16x16x32_bf16 v[116:119], v[174:177], v[182:185], v[116:119]
	v_mfma_f32_16x16x32_bf16 v[104:107], v[166:169], v[194:197], v[104:107]
	v_mfma_f32_16x16x32_bf16 v[96:99], v[174:177], v[194:197], v[96:99]
	v_mfma_f32_16x16x32_bf16 v[88:91], v[166:169], v[206:209], v[88:91]
	v_mfma_f32_16x16x32_bf16 v[80:83], v[174:177], v[206:209], v[80:83]
	s_barrier
	s_setprio 2
	v_mfma_f32_16x16x32_bf16 v[72:75], v[166:169], v[214:217], v[72:75]
	v_mfma_f32_16x16x32_bf16 v[64:67], v[174:177], v[214:217], v[64:67]
	s_setprio 0
	s_add_i32 s12, s24, s30
	v_lshl_add_u64 v[190:191], v[190:191], 0, s[16:17]
	s_mov_b32 m0, s12
	ds_read_b128 v[178:181], v152 offset:49152
	ds_read_b128 v[182:185], v152 offset:50176
	ds_read_b128 v[186:189], v152 offset:51200
	ds_read_b128 v[194:197], v152 offset:52224
	ds_read_b128 v[202:205], v152 offset:53248
	ds_read_b128 v[206:209], v152 offset:54272
	ds_read_b128 v[210:213], v152 offset:55296
	ds_read_b128 v[214:217], v152 offset:56320
	global_load_lds_dwordx4 v[190:191], off
	s_add_i32 m0, s12, 0x2000
	s_add_u32 s10, s10, 0x80080
	v_lshl_add_u64 v[190:191], v[218:219], 0, s[16:17]
	s_addc_u32 s11, s11, 0
	s_add_i32 s12, s25, s30
	global_load_lds_dwordx4 v[190:191], off
	s_mov_b32 m0, s12
	v_lshl_add_u64 v[190:191], s[10:11], 0, v[132:133]
	global_load_lds_dwordx4 v[190:191], off
	s_add_i32 m0, s12, 0x2000
	v_lshl_add_u64 v[190:191], s[10:11], 0, v[128:129]
	global_load_lds_dwordx4 v[190:191], off
	s_mov_b32 m0, s56
	v_lshl_add_u64 v[190:191], v[220:221], 0, s[16:17]
	global_load_lds_dwordx4 v[190:191], off
	s_mov_b32 m0, s57
	v_lshl_add_u64 v[190:191], v[230:231], 0, s[16:17]
	global_load_lds_dwordx4 v[190:191], off
	s_waitcnt vmcnt(8)
	s_waitcnt lgkmcnt(0)
	s_barrier
; #define PG8_STAGE(bufoff, gbase, voff) do { _Pragma("unroll") for (int _i = 0; _i < 2; ++_i) \
;         __builtin_amdgcn_global_load_lds((const unsigned*)((const char*)(gbase) + (voff)[_i]), (PG8_LAS unsigned*)(lds + (bufoff) + ldsw + _i * 8192), 16, 0, 0); } while (0)
; #define PG8_LDA(dst, b, h) do { _Pragma("unroll") for (int m = 0; m < 4; ++m) _Pragma("unroll") for (int k = 0; k < 2; ++k) dst[m][k] = *(const PG8_LAS bf16x8*)(lds + PG8_SA(b, h) + aoff + m * 2048 + k * 1024); } while (0)
; #define PG8_LDB(dst, b, h) do { _Pragma("unroll") for (int n = 0; n < 2; ++n) _Pragma("unroll") for (int k = 0; k < 2; ++k) dst[n][k] = *(const PG8_LAS bf16x8*)(lds + PG8_SB(b, h) + boff + n * 2048 + k * 1024); } while (0)
; #define PG8_MMA(ai, bj, At, Bt) do { __builtin_amdgcn_s_setprio(1); _Pragma("unroll") for (int m = 0; m < 4; ++m) _Pragma("unroll") for (int n = 0; n < 2; ++n) _Pragma("unroll") for (int k = 0; k < 2; ++k) \
;         acc[ai][bj][m][n] = __builtin_amdgcn_mfma_f32_16x16x32_bf16(Bt[n][k], At[m][k], acc[ai][bj][m][n], 0, 0, 0); __builtin_amdgcn_s_setprio(0); } while (0)
; #define PG8_WAIT_V(n) asm volatile("s_waitcnt vmcnt(" #n ")" ::: "memory")
; template <class Epi, class Sched, bool ALIGN_EPI = false, bool SP2 = false>
; __device__ __forceinline__ void gemm_phase(PG8_LAS unsigned char* lds, const Gemm g, const Sched& S, const Epi& E) {
;     ...
;             PG8_LDB(B0, 0, 0); PG8_LDB(B1, 0, 1); PG8_SCHED; PG8_LDA(At, 0, 0); PG8_STAGE(PG8_SA(1, 1), a1 + hstep, voffA);
;             PG8_WAIT_V(8); PG8_WAIT_L(0); PG8_BAR; PG8_MMA(0, 0, At, B0); PG8_MMA(0, 1, At, B1); PG8_BAR; PG8_SCHED;
;             PG8_LDA(At, 0, 1); PG8_STAGE(PG8_SB(0, 0), b2, voffB); PG8_STAGE(PG8_SB(0, 1), b2 + hstep, voffB); PG8_STAGE(PG8_SA(0, 0), a2, voffA);
;             PG8_WAIT_V(8); PG8_WAIT_L(0); PG8_BAR; PG8_MMA(1, 0, At, B0); PG8_MMA(1, 1, At, B1); PG8_BAR; PG8_SCHED;
;             PG8_LDB(B0, 1, 0); PG8_LDB(B1, 1, 1); PG8_SCHED; PG8_LDA(At, 1, 0); PG8_STAGE(PG8_SA(0, 1), a2 + hstep, voffA);
;             PG8_WAIT_V(8); PG8_WAIT_L(0); PG8_BAR; PG8_MMA(0, 0, At, B0); PG8_MMA(0, 1, At, B1); PG8_BAR; PG8_SCHED;
;             PG8_LDA(At, 1, 1); PG8_STAGE(PG8_SB(1, 0), b3, voffB); PG8_STAGE(PG8_SB(1, 1), b3 + hstep, voffB); PG8_STAGE(PG8_SA(1, 0), a3, voffA);
;             PG8_WAIT_V(8); PG8_WAIT_L(0); PG8_BAR; PG8_MMA(1, 0, At, B0); PG8_MMA(1, 1, At, B1); PG8_BAR; PG8_SCHED;
	s_setprio 1
	s_waitcnt lgkmcnt(0)
	v_mfma_f32_16x16x32_bf16 v[60:63], v[140:143], v[178:181], v[60:63]
	v_mfma_f32_16x16x32_bf16 v[52:55], v[154:157], v[178:181], v[52:55]
	v_mfma_f32_16x16x32_bf16 v[44:47], v[140:143], v[186:189], v[44:47]
	v_mfma_f32_16x16x32_bf16 v[36:39], v[154:157], v[186:189], v[36:39]
	v_mfma_f32_16x16x32_bf16 v[28:31], v[140:143], v[202:205], v[28:31]
	v_mfma_f32_16x16x32_bf16 v[20:23], v[154:157], v[202:205], v[20:23]
	v_mfma_f32_16x16x32_bf16 v[12:15], v[140:143], v[210:213], v[12:15]
	v_mfma_f32_16x16x32_bf16 v[4:7], v[154:157], v[210:213], v[4:7]
	v_mfma_f32_16x16x32_bf16 v[60:63], v[144:147], v[182:185], v[60:63]
	v_mfma_f32_16x16x32_bf16 v[52:55], v[158:161], v[182:185], v[52:55]
	v_mfma_f32_16x16x32_bf16 v[44:47], v[144:147], v[194:197], v[44:47]
	v_mfma_f32_16x16x32_bf16 v[36:39], v[158:161], v[194:197], v[36:39]
	v_mfma_f32_16x16x32_bf16 v[28:31], v[144:147], v[206:209], v[28:31]
	v_mfma_f32_16x16x32_bf16 v[20:23], v[158:161], v[206:209], v[20:23]
	v_mfma_f32_16x16x32_bf16 v[12:15], v[144:147], v[214:217], v[12:15]
	v_mfma_f32_16x16x32_bf16 v[4:7], v[158:161], v[214:217], v[4:7]
	s_setprio 0
	s_setprio 1
	v_mfma_f32_16x16x32_bf16 v[56:59], v[162:165], v[178:181], v[56:59]
	v_mfma_f32_16x16x32_bf16 v[48:51], v[170:173], v[178:181], v[48:51]
	v_mfma_f32_16x16x32_bf16 v[40:43], v[162:165], v[186:189], v[40:43]
	v_mfma_f32_16x16x32_bf16 v[32:35], v[170:173], v[186:189], v[32:35]
	v_mfma_f32_16x16x32_bf16 v[24:27], v[162:165], v[202:205], v[24:27]
	v_mfma_f32_16x16x32_bf16 v[16:19], v[170:173], v[202:205], v[16:19]
	v_mfma_f32_16x16x32_bf16 v[8:11], v[162:165], v[210:213], v[8:11]
	v_mfma_f32_16x16x32_bf16 v[0:3], v[170:173], v[210:213], v[0:3]
	v_mfma_f32_16x16x32_bf16 v[56:59], v[166:169], v[182:185], v[56:59]
	v_mfma_f32_16x16x32_bf16 v[48:51], v[174:177], v[182:185], v[48:51]
	v_mfma_f32_16x16x32_bf16 v[40:43], v[166:169], v[194:197], v[40:43]
	v_mfma_f32_16x16x32_bf16 v[32:35], v[174:177], v[194:197], v[32:35]
	v_mfma_f32_16x16x32_bf16 v[24:27], v[166:169], v[206:209], v[24:27]
	v_mfma_f32_16x16x32_bf16 v[16:19], v[174:177], v[206:209], v[16:19]
	s_barrier
	s_setprio 2
	v_mfma_f32_16x16x32_bf16 v[8:11], v[166:169], v[214:217], v[8:11]
	v_mfma_f32_16x16x32_bf16 v[0:3], v[174:177], v[214:217], v[0:3]
	s_setprio 0
	s_add_i32 s64, s64, 2
	s_add_u32 s0, s0, 0x100
	s_addc_u32 s1, s1, 0
	s_add_u32 s62, s62, 0x100
	s_addc_u32 s63, s63, 0
	s_cmp_gt_u32 s64, 29
	s_branch .LBB0_730
.LBB0_730:
	v_add_u32_e32 v148, 0x10000, v151
	ds_read_b128 v[140:143], v148
	ds_read_b128 v[144:147], v148 offset:1024
	ds_read_b128 v[154:157], v148 offset:2048
	ds_read_b128 v[158:161], v148 offset:3072
	v_add_u32_e32 v148, 0x14000, v151
	ds_read_b128 v[162:165], v148
	ds_read_b128 v[166:169], v148 offset:1024
	ds_read_b128 v[170:173], v148 offset:2048
	ds_read_b128 v[174:177], v148 offset:3072
	v_lshl_add_u64 v[190:191], s[0:1], 0, v[136:137]
	s_add_i32 m0, s31, 0xc000
	ds_read_b128 v[178:181], v152
	ds_read_b128 v[182:185], v152 offset:1024
	ds_read_b128 v[186:189], v152 offset:2048
	ds_read_b128 v[194:197], v152 offset:3072
	ds_read_b128 v[202:205], v152 offset:4096
	ds_read_b128 v[206:209], v152 offset:5120
	ds_read_b128 v[210:213], v152 offset:6144
	ds_read_b128 v[214:217], v152 offset:7168
	global_load_lds_dwordx4 v[190:191], off
	s_add_i32 m0, s31, 0xe000
	v_lshl_add_u64 v[190:191], s[0:1], 0, v[138:139]
	global_load_lds_dwordx4 v[190:191], off
	s_add_u32 s10, s0, 0xfff80080
	s_addc_u32 s11, s1, -1
	s_add_i32 s24, 0, 0x10000
	s_cmp_eq_u32 s64, 28
	s_cselect_b32 s13, s49, s11
	s_cselect_b32 s12, s60, s10
	s_cselect_b32 s11, s47, s63
	s_cselect_b32 s10, s61, s62
	s_add_i32 s25, 0, 0x14000
	s_waitcnt vmcnt(8)
	s_waitcnt lgkmcnt(0)
	s_barrier
	s_setprio 1
	s_waitcnt lgkmcnt(0)
	v_mfma_f32_16x16x32_bf16 v[124:127], v[140:143], v[178:181], v[124:127]
	v_mfma_f32_16x16x32_bf16 v[112:115], v[154:157], v[178:181], v[112:115]
	v_mfma_f32_16x16x32_bf16 v[108:111], v[140:143], v[186:189], v[108:111]
	v_mfma_f32_16x16x32_bf16 v[100:103], v[154:157], v[186:189], v[100:103]
	v_mfma_f32_16x16x32_bf16 v[92:95], v[140:143], v[202:205], v[92:95]
	v_mfma_f32_16x16x32_bf16 v[84:87], v[154:157], v[202:205], v[84:87]
	v_mfma_f32_16x16x32_bf16 v[76:79], v[140:143], v[210:213], v[76:79]
	v_mfma_f32_16x16x32_bf16 v[68:71], v[154:157], v[210:213], v[68:71]
	v_mfma_f32_16x16x32_bf16 v[124:127], v[144:147], v[182:185], v[124:127]
	v_mfma_f32_16x16x32_bf16 v[112:115], v[158:161], v[182:185], v[112:115]
	v_mfma_f32_16x16x32_bf16 v[108:111], v[144:147], v[194:197], v[108:111]
	v_mfma_f32_16x16x32_bf16 v[100:103], v[158:161], v[194:197], v[100:103]
	v_mfma_f32_16x16x32_bf16 v[92:95], v[144:147], v[206:209], v[92:95]
	v_mfma_f32_16x16x32_bf16 v[84:87], v[158:161], v[206:209], v[84:87]
	v_mfma_f32_16x16x32_bf16 v[76:79], v[144:147], v[214:217], v[76:79]
	v_mfma_f32_16x16x32_bf16 v[68:71], v[158:161], v[214:217], v[68:71]
	s_setprio 0
	s_setprio 1
	v_mfma_f32_16x16x32_bf16 v[120:123], v[162:165], v[178:181], v[120:123]
	v_mfma_f32_16x16x32_bf16 v[116:119], v[170:173], v[178:181], v[116:119]
	v_mfma_f32_16x16x32_bf16 v[104:107], v[162:165], v[186:189], v[104:107]
	v_mfma_f32_16x16x32_bf16 v[96:99], v[170:173], v[186:189], v[96:99]
	v_mfma_f32_16x16x32_bf16 v[88:91], v[162:165], v[202:205], v[88:91]
	v_mfma_f32_16x16x32_bf16 v[80:83], v[170:173], v[202:205], v[80:83]
	v_mfma_f32_16x16x32_bf16 v[72:75], v[162:165], v[210:213], v[72:75]
	v_mfma_f32_16x16x32_bf16 v[64:67], v[170:173], v[210:213], v[64:67]
	v_mfma_f32_16x16x32_bf16 v[120:123], v[166:169], v[182:185], v[120:123]
	v_mfma_f32_16x16x32_bf16 v[116:119], v[174:177], v[182:185], v[116:119]
	v_mfma_f32_16x16x32_bf16 v[104:107], v[166:169], v[194:197], v[104:107]
	v_mfma_f32_16x16x32_bf16 v[96:99], v[174:177], v[194:197], v[96:99]
	v_mfma_f32_16x16x32_bf16 v[88:91], v[166:169], v[206:209], v[88:91]
	v_mfma_f32_16x16x32_bf16 v[80:83], v[174:177], v[206:209], v[80:83]
	s_barrier
; #define PG8_STAGE(bufoff, gbase, voff) do { _Pragma("unroll") for (int _i = 0; _i < 2; ++_i) \
;         __builtin_amdgcn_global_load_lds((const unsigned*)((const char*)(gbase) + (voff)[_i]), (PG8_LAS unsigned*)(lds + (bufoff) + ldsw + _i * 8192), 16, 0, 0); } while (0)
; #define PG8_LDA(dst, b, h) do { _Pragma("unroll") for (int m = 0; m < 4; ++m) _Pragma("unroll") for (int k = 0; k < 2; ++k) dst[m][k] = *(const PG8_LAS bf16x8*)(lds + PG8_SA(b, h) + aoff + m * 2048 + k * 1024); } while (0)
; #define PG8_LDB(dst, b, h) do { _Pragma("unroll") for (int n = 0; n < 2; ++n) _Pragma("unroll") for (int k = 0; k < 2; ++k) dst[n][k] = *(const PG8_LAS bf16x8*)(lds + PG8_SB(b, h) + boff + n * 2048 + k * 1024); } while (0)
; #define PG8_MMA(ai, bj, At, Bt) do { __builtin_amdgcn_s_setprio(1); _Pragma("unroll") for (int m = 0; m < 4; ++m) _Pragma("unroll") for (int n = 0; n < 2; ++n) _Pragma("unroll") for (int k = 0; k < 2; ++k) \
;         acc[ai][bj][m][n] = __builtin_amdgcn_mfma_f32_16x16x32_bf16(Bt[n][k], At[m][k], acc[ai][bj][m][n], 0, 0, 0); __builtin_amdgcn_s_setprio(0); } while (0)
; #define PG8_WAIT_V(n) asm volatile("s_waitcnt vmcnt(" #n ")" ::: "memory")
; #define PG8_WAIT_L(n) asm volatile("s_waitcnt lgkmcnt(" #n ")" ::: "memory")
; #define PG8_BAR __builtin_amdgcn_s_barrier()
; #define PG8_SCHED __builtin_amdgcn_sched_barrier(0)
; template <class Epi, class Sched, bool ALIGN_EPI = false, bool SP2 = false>
; __device__ __forceinline__ void gemm_phase(PG8_LAS unsigned char* lds, const Gemm g, const Sched& S, const Epi& E) {
;     ...
;             PG8_WAIT_V(8); PG8_WAIT_L(0); PG8_BAR; PG8_MMA(0, 0, At, B0); PG8_MMA(0, 1, At, B1); PG8_BAR; PG8_SCHED;
;             PG8_LDA(At, 0, 1); PG8_STAGE(PG8_SB(0, 0), b2, voffB); PG8_STAGE(PG8_SB(0, 1), b2 + hstep, voffB); PG8_STAGE(PG8_SA(0, 0), a2, voffA);
;             PG8_WAIT_V(8); PG8_WAIT_L(0); PG8_BAR; PG8_MMA(1, 0, At, B0); PG8_MMA(1, 1, At, B1); PG8_BAR; PG8_SCHED;
;             PG8_LDB(B0, 1, 0); PG8_LDB(B1, 1, 1); PG8_SCHED; PG8_LDA(At, 1, 0); PG8_STAGE(PG8_SA(0, 1), a2 + hstep, voffA);
	s_setprio 2
	v_mfma_f32_16x16x32_bf16 v[72:75], v[166:169], v[214:217], v[72:75]
	v_mfma_f32_16x16x32_bf16 v[64:67], v[174:177], v[214:217], v[64:67]
	s_setprio 0
	s_add_i32 s24, s24, s30
	v_lshl_add_u64 v[190:191], s[10:11], 0, v[132:133]
	s_mov_b32 m0, s24
	ds_read_b128 v[178:181], v152 offset:16384
	ds_read_b128 v[182:185], v152 offset:17408
	ds_read_b128 v[186:189], v152 offset:18432
	ds_read_b128 v[194:197], v152 offset:19456
	ds_read_b128 v[202:205], v152 offset:20480
	ds_read_b128 v[206:209], v152 offset:21504
	ds_read_b128 v[210:213], v152 offset:22528
	ds_read_b128 v[214:217], v152 offset:23552
	global_load_lds_dwordx4 v[190:191], off
	s_add_i32 m0, s24, 0x2000
	s_add_u32 s66, s10, 0x80000
	v_lshl_add_u64 v[218:219], s[10:11], 0, v[128:129]
	s_addc_u32 s67, s11, 0
	s_add_i32 s24, s25, s30
	global_load_lds_dwordx4 v[218:219], off
	v_lshl_add_u64 v[220:221], s[66:67], 0, v[132:133]
	s_mov_b32 m0, s24
	v_lshl_add_u64 v[230:231], s[12:13], 0, v[130:131]
	global_load_lds_dwordx4 v[220:221], off
	s_add_i32 m0, s24, 0x2000
	v_lshl_add_u64 v[220:221], s[66:67], 0, v[128:129]
	global_load_lds_dwordx4 v[220:221], off
	s_mov_b32 m0, s31
	v_lshl_add_u64 v[220:221], s[12:13], 0, v[134:135]
	global_load_lds_dwordx4 v[220:221], off
	s_mov_b32 m0, s34
	s_nop 0
	global_load_lds_dwordx4 v[230:231], off
	s_waitcnt vmcnt(8)
	s_waitcnt lgkmcnt(0)
	s_barrier
	s_setprio 1
	s_waitcnt lgkmcnt(0)
	v_mfma_f32_16x16x32_bf16 v[60:63], v[140:143], v[178:181], v[60:63]
	v_mfma_f32_16x16x32_bf16 v[52:55], v[154:157], v[178:181], v[52:55]
	v_mfma_f32_16x16x32_bf16 v[44:47], v[140:143], v[186:189], v[44:47]
	v_mfma_f32_16x16x32_bf16 v[36:39], v[154:157], v[186:189], v[36:39]
	v_mfma_f32_16x16x32_bf16 v[28:31], v[140:143], v[202:205], v[28:31]
	v_mfma_f32_16x16x32_bf16 v[20:23], v[154:157], v[202:205], v[20:23]
	v_mfma_f32_16x16x32_bf16 v[12:15], v[140:143], v[210:213], v[12:15]
	v_mfma_f32_16x16x32_bf16 v[4:7], v[154:157], v[210:213], v[4:7]
	v_mfma_f32_16x16x32_bf16 v[60:63], v[144:147], v[182:185], v[60:63]
	v_mfma_f32_16x16x32_bf16 v[52:55], v[158:161], v[182:185], v[52:55]
	v_mfma_f32_16x16x32_bf16 v[44:47], v[144:147], v[194:197], v[44:47]
	v_mfma_f32_16x16x32_bf16 v[36:39], v[158:161], v[194:197], v[36:39]
	v_mfma_f32_16x16x32_bf16 v[28:31], v[144:147], v[206:209], v[28:31]
	v_mfma_f32_16x16x32_bf16 v[20:23], v[158:161], v[206:209], v[20:23]
	v_mfma_f32_16x16x32_bf16 v[12:15], v[144:147], v[214:217], v[12:15]
	v_mfma_f32_16x16x32_bf16 v[4:7], v[158:161], v[214:217], v[4:7]
	s_setprio 0
	s_setprio 1
	v_mfma_f32_16x16x32_bf16 v[56:59], v[162:165], v[178:181], v[56:59]
	v_mfma_f32_16x16x32_bf16 v[48:51], v[170:173], v[178:181], v[48:51]
	v_mfma_f32_16x16x32_bf16 v[40:43], v[162:165], v[186:189], v[40:43]
	v_mfma_f32_16x16x32_bf16 v[32:35], v[170:173], v[186:189], v[32:35]
	v_mfma_f32_16x16x32_bf16 v[24:27], v[162:165], v[202:205], v[24:27]
	v_mfma_f32_16x16x32_bf16 v[16:19], v[170:173], v[202:205], v[16:19]
	v_mfma_f32_16x16x32_bf16 v[8:11], v[162:165], v[210:213], v[8:11]
	v_mfma_f32_16x16x32_bf16 v[0:3], v[170:173], v[210:213], v[0:3]
	v_mfma_f32_16x16x32_bf16 v[56:59], v[166:169], v[182:185], v[56:59]
	v_mfma_f32_16x16x32_bf16 v[48:51], v[174:177], v[182:185], v[48:51]
	v_mfma_f32_16x16x32_bf16 v[40:43], v[166:169], v[194:197], v[40:43]
	v_mfma_f32_16x16x32_bf16 v[32:35], v[174:177], v[194:197], v[32:35]
	v_mfma_f32_16x16x32_bf16 v[24:27], v[166:169], v[206:209], v[24:27]
	v_mfma_f32_16x16x32_bf16 v[16:19], v[174:177], v[206:209], v[16:19]
	s_barrier
	s_setprio 2
	v_mfma_f32_16x16x32_bf16 v[8:11], v[166:169], v[214:217], v[8:11]
	v_mfma_f32_16x16x32_bf16 v[0:3], v[174:177], v[214:217], v[0:3]
	s_setprio 0
	s_add_i32 s24, 0, 0x18000
	v_add_u32_e32 v148, 0x18000, v151
	s_add_i32 s25, 0, 0x1c000
	ds_read_b128 v[140:143], v148
	ds_read_b128 v[144:147], v148 offset:1024
	ds_read_b128 v[154:157], v148 offset:2048
	ds_read_b128 v[158:161], v148 offset:3072
	v_add_u32_e32 v148, 0x1c000, v151
	ds_read_b128 v[162:165], v148
	ds_read_b128 v[166:169], v148 offset:1024
	ds_read_b128 v[170:173], v148 offset:2048
	ds_read_b128 v[174:177], v148 offset:3072
	s_add_u32 s12, s12, 0x80000
	s_addc_u32 s13, s13, 0
	s_mov_b32 m0, s36
	v_lshl_add_u64 v[232:233], s[12:13], 0, v[134:135]
	ds_read_b128 v[178:181], v152 offset:32768
	ds_read_b128 v[182:185], v152 offset:33792
	ds_read_b128 v[186:189], v152 offset:34816
	ds_read_b128 v[194:197], v152 offset:35840
	ds_read_b128 v[202:205], v152 offset:36864
	ds_read_b128 v[206:209], v152 offset:37888
	ds_read_b128 v[210:213], v152 offset:38912
	ds_read_b128 v[214:217], v152 offset:39936
	global_load_lds_dwordx4 v[232:233], off
	s_mov_b32 m0, s37
	v_lshl_add_u64 v[232:233], s[12:13], 0, v[130:131]
	global_load_lds_dwordx4 v[232:233], off
	s_waitcnt vmcnt(8)
	s_waitcnt lgkmcnt(0)
	s_barrier
; #define PG8_STAGE(bufoff, gbase, voff) do { _Pragma("unroll") for (int _i = 0; _i < 2; ++_i) \
;         __builtin_amdgcn_global_load_lds((const unsigned*)((const char*)(gbase) + (voff)[_i]), (PG8_LAS unsigned*)(lds + (bufoff) + ldsw + _i * 8192), 16, 0, 0); } while (0)
; #define PG8_LDA(dst, b, h) do { _Pragma("unroll") for (int m = 0; m < 4; ++m) _Pragma("unroll") for (int k = 0; k < 2; ++k) dst[m][k] = *(const PG8_LAS bf16x8*)(lds + PG8_SA(b, h) + aoff + m * 2048 + k * 1024); } while (0)
; #define PG8_MMA(ai, bj, At, Bt) do { __builtin_amdgcn_s_setprio(1); _Pragma("unroll") for (int m = 0; m < 4; ++m) _Pragma("unroll") for (int n = 0; n < 2; ++n) _Pragma("unroll") for (int k = 0; k < 2; ++k) \
;         acc[ai][bj][m][n] = __builtin_amdgcn_mfma_f32_16x16x32_bf16(Bt[n][k], At[m][k], acc[ai][bj][m][n], 0, 0, 0); __builtin_amdgcn_s_setprio(0); } while (0)
; #define PG8_WAIT_V(n) asm volatile("s_waitcnt vmcnt(" #n ")" ::: "memory")
; #define PG8_WAIT_L(n) asm volatile("s_waitcnt lgkmcnt(" #n ")" ::: "memory")
; #define PG8_BAR __builtin_amdgcn_s_barrier()
; #define PG8_SCHED __builtin_amdgcn_sched_barrier(0)
; template <class Epi, class Sched, bool ALIGN_EPI = false, bool SP2 = false>
; __device__ __forceinline__ void gemm_phase(PG8_LAS unsigned char* lds, const Gemm g, const Sched& S, const Epi& E) {
;     ...
;             PG8_WAIT_V(8); PG8_WAIT_L(0); PG8_BAR; PG8_MMA(0, 0, At, B0); PG8_MMA(0, 1, At, B1); PG8_BAR; PG8_SCHED;
;             PG8_LDA(At, 1, 1); PG8_STAGE(PG8_SB(1, 0), b3, voffB); PG8_STAGE(PG8_SB(1, 1), b3 + hstep, voffB); PG8_STAGE(PG8_SA(1, 0), a3, voffA);
;             PG8_WAIT_V(8); PG8_WAIT_L(0); PG8_BAR; PG8_MMA(1, 0, At, B0); PG8_MMA(1, 1, At, B1); PG8_BAR; PG8_SCHED;
	s_setprio 1
	s_waitcnt lgkmcnt(0)
	v_mfma_f32_16x16x32_bf16 v[124:127], v[140:143], v[178:181], v[124:127]
	v_mfma_f32_16x16x32_bf16 v[112:115], v[154:157], v[178:181], v[112:115]
	v_mfma_f32_16x16x32_bf16 v[108:111], v[140:143], v[186:189], v[108:111]
	v_mfma_f32_16x16x32_bf16 v[100:103], v[154:157], v[186:189], v[100:103]
	v_mfma_f32_16x16x32_bf16 v[92:95], v[140:143], v[202:205], v[92:95]
	v_mfma_f32_16x16x32_bf16 v[84:87], v[154:157], v[202:205], v[84:87]
	v_mfma_f32_16x16x32_bf16 v[76:79], v[140:143], v[210:213], v[76:79]
	v_mfma_f32_16x16x32_bf16 v[68:71], v[154:157], v[210:213], v[68:71]
	v_mfma_f32_16x16x32_bf16 v[124:127], v[144:147], v[182:185], v[124:127]
	v_mfma_f32_16x16x32_bf16 v[112:115], v[158:161], v[182:185], v[112:115]
	v_mfma_f32_16x16x32_bf16 v[108:111], v[144:147], v[194:197], v[108:111]
	v_mfma_f32_16x16x32_bf16 v[100:103], v[158:161], v[194:197], v[100:103]
	v_mfma_f32_16x16x32_bf16 v[92:95], v[144:147], v[206:209], v[92:95]
	v_mfma_f32_16x16x32_bf16 v[84:87], v[158:161], v[206:209], v[84:87]
	v_mfma_f32_16x16x32_bf16 v[76:79], v[144:147], v[214:217], v[76:79]
	v_mfma_f32_16x16x32_bf16 v[68:71], v[158:161], v[214:217], v[68:71]
	s_setprio 0
	s_setprio 1
	v_mfma_f32_16x16x32_bf16 v[120:123], v[162:165], v[178:181], v[120:123]
	v_mfma_f32_16x16x32_bf16 v[116:119], v[170:173], v[178:181], v[116:119]
	v_mfma_f32_16x16x32_bf16 v[104:107], v[162:165], v[186:189], v[104:107]
	v_mfma_f32_16x16x32_bf16 v[96:99], v[170:173], v[186:189], v[96:99]
	v_mfma_f32_16x16x32_bf16 v[88:91], v[162:165], v[202:205], v[88:91]
	v_mfma_f32_16x16x32_bf16 v[80:83], v[170:173], v[202:205], v[80:83]
	v_mfma_f32_16x16x32_bf16 v[72:75], v[162:165], v[210:213], v[72:75]
	v_mfma_f32_16x16x32_bf16 v[64:67], v[170:173], v[210:213], v[64:67]
	v_mfma_f32_16x16x32_bf16 v[120:123], v[166:169], v[182:185], v[120:123]
	v_mfma_f32_16x16x32_bf16 v[116:119], v[174:177], v[182:185], v[116:119]
	v_mfma_f32_16x16x32_bf16 v[104:107], v[166:169], v[194:197], v[104:107]
	v_mfma_f32_16x16x32_bf16 v[96:99], v[174:177], v[194:197], v[96:99]
	v_mfma_f32_16x16x32_bf16 v[88:91], v[166:169], v[206:209], v[88:91]
	v_mfma_f32_16x16x32_bf16 v[80:83], v[174:177], v[206:209], v[80:83]
	s_barrier
	s_setprio 2
	v_mfma_f32_16x16x32_bf16 v[72:75], v[166:169], v[214:217], v[72:75]
	v_mfma_f32_16x16x32_bf16 v[64:67], v[174:177], v[214:217], v[64:67]
	s_setprio 0
	s_add_i32 s12, s24, s30
	v_lshl_add_u64 v[190:191], v[190:191], 0, s[16:17]
	s_mov_b32 m0, s12
	ds_read_b128 v[178:181], v152 offset:49152
	ds_read_b128 v[182:185], v152 offset:50176
	ds_read_b128 v[186:189], v152 offset:51200
	ds_read_b128 v[194:197], v152 offset:52224
	ds_read_b128 v[202:205], v152 offset:53248
	ds_read_b128 v[206:209], v152 offset:54272
	ds_read_b128 v[210:213], v152 offset:55296
	ds_read_b128 v[214:217], v152 offset:56320
	global_load_lds_dwordx4 v[190:191], off
	s_add_i32 m0, s12, 0x2000
	s_add_u32 s10, s10, 0x80080
	v_lshl_add_u64 v[190:191], v[218:219], 0, s[16:17]
	s_addc_u32 s11, s11, 0
	s_add_i32 s12, s25, s30
	global_load_lds_dwordx4 v[190:191], off
	s_mov_b32 m0, s12
	v_lshl_add_u64 v[190:191], s[10:11], 0, v[132:133]
	global_load_lds_dwordx4 v[190:191], off
	s_add_i32 m0, s12, 0x2000
	v_lshl_add_u64 v[190:191], s[10:11], 0, v[128:129]
	global_load_lds_dwordx4 v[190:191], off
	s_mov_b32 m0, s56
	v_lshl_add_u64 v[190:191], v[220:221], 0, s[16:17]
	global_load_lds_dwordx4 v[190:191], off
	s_mov_b32 m0, s57
	v_lshl_add_u64 v[190:191], v[230:231], 0, s[16:17]
	global_load_lds_dwordx4 v[190:191], off
	s_waitcnt vmcnt(8)
	s_waitcnt lgkmcnt(0)
	s_barrier
	s_setprio 1
	s_waitcnt lgkmcnt(0)
	v_mfma_f32_16x16x32_bf16 v[60:63], v[140:143], v[178:181], v[60:63]
	v_mfma_f32_16x16x32_bf16 v[52:55], v[154:157], v[178:181], v[52:55]
	v_mfma_f32_16x16x32_bf16 v[44:47], v[140:143], v[186:189], v[44:47]
	v_mfma_f32_16x16x32_bf16 v[36:39], v[154:157], v[186:189], v[36:39]
	v_mfma_f32_16x16x32_bf16 v[28:31], v[140:143], v[202:205], v[28:31]
	v_mfma_f32_16x16x32_bf16 v[20:23], v[154:157], v[202:205], v[20:23]
	v_mfma_f32_16x16x32_bf16 v[12:15], v[140:143], v[210:213], v[12:15]
	v_mfma_f32_16x16x32_bf16 v[4:7], v[154:157], v[210:213], v[4:7]
	v_mfma_f32_16x16x32_bf16 v[60:63], v[144:147], v[182:185], v[60:63]
	v_mfma_f32_16x16x32_bf16 v[52:55], v[158:161], v[182:185], v[52:55]
	v_mfma_f32_16x16x32_bf16 v[44:47], v[144:147], v[194:197], v[44:47]
	v_mfma_f32_16x16x32_bf16 v[36:39], v[158:161], v[194:197], v[36:39]
	v_mfma_f32_16x16x32_bf16 v[28:31], v[144:147], v[206:209], v[28:31]
	v_mfma_f32_16x16x32_bf16 v[20:23], v[158:161], v[206:209], v[20:23]
	v_mfma_f32_16x16x32_bf16 v[12:15], v[144:147], v[214:217], v[12:15]
	v_mfma_f32_16x16x32_bf16 v[4:7], v[158:161], v[214:217], v[4:7]
	s_setprio 0
	s_setprio 1
	v_mfma_f32_16x16x32_bf16 v[56:59], v[162:165], v[178:181], v[56:59]
	v_mfma_f32_16x16x32_bf16 v[48:51], v[170:173], v[178:181], v[48:51]
	v_mfma_f32_16x16x32_bf16 v[40:43], v[162:165], v[186:189], v[40:43]
	v_mfma_f32_16x16x32_bf16 v[32:35], v[170:173], v[186:189], v[32:35]
	v_mfma_f32_16x16x32_bf16 v[24:27], v[162:165], v[202:205], v[24:27]
	v_mfma_f32_16x16x32_bf16 v[16:19], v[170:173], v[202:205], v[16:19]
	v_mfma_f32_16x16x32_bf16 v[8:11], v[162:165], v[210:213], v[8:11]
	v_mfma_f32_16x16x32_bf16 v[0:3], v[170:173], v[210:213], v[0:3]
	v_mfma_f32_16x16x32_bf16 v[56:59], v[166:169], v[182:185], v[56:59]
	v_mfma_f32_16x16x32_bf16 v[48:51], v[174:177], v[182:185], v[48:51]
	v_mfma_f32_16x16x32_bf16 v[40:43], v[166:169], v[194:197], v[40:43]
	v_mfma_f32_16x16x32_bf16 v[32:35], v[174:177], v[194:197], v[32:35]
	v_mfma_f32_16x16x32_bf16 v[24:27], v[166:169], v[206:209], v[24:27]
	v_mfma_f32_16x16x32_bf16 v[16:19], v[174:177], v[206:209], v[16:19]
	s_barrier
	s_setprio 2
	v_mfma_f32_16x16x32_bf16 v[8:11], v[166:169], v[214:217], v[8:11]
	v_mfma_f32_16x16x32_bf16 v[0:3], v[174:177], v[214:217], v[0:3]
	s_setprio 0
	s_add_i32 s64, s64, 2
	s_add_u32 s0, s0, 0x100
	s_addc_u32 s1, s1, 0
	s_add_u32 s62, s62, 0x100
	s_addc_u32 s63, s63, 0
	s_cmp_gt_u32 s64, 29
	s_cbranch_scc0 .LBB0_730
	s_and_b64 vcc, exec, s[44:45]
	s_cbranch_vccz .LBB0_733
	s_barrier

; #define PG8_STAGE(bufoff, gbase, voff) do { _Pragma("unroll") for (int _i = 0; _i < 2; ++_i) \
;         __builtin_amdgcn_global_load_lds((const unsigned*)((const char*)(gbase) + (voff)[_i]), (PG8_LAS unsigned*)(lds + (bufoff) + ldsw + _i * 8192), 16, 0, 0); } while (0)
; #define PG8_LDA(dst, b, h) do { _Pragma("unroll") for (int m = 0; m < 4; ++m) _Pragma("unroll") for (int k = 0; k < 2; ++k) dst[m][k] = *(const PG8_LAS bf16x8*)(lds + PG8_SA(b, h) + aoff + m * 2048 + k * 1024); } while (0)
; #define PG8_LDB(dst, b, h) do { _Pragma("unroll") for (int n = 0; n < 2; ++n) _Pragma("unroll") for (int k = 0; k < 2; ++k) dst[n][k] = *(const PG8_LAS bf16x8*)(lds + PG8_SB(b, h) + boff + n * 2048 + k * 1024); } while (0)
; #define PG8_MMA(ai, bj, At, Bt) do { __builtin_amdgcn_s_setprio(1); _Pragma("unroll") for (int m = 0; m < 4; ++m) _Pragma("unroll") for (int n = 0; n < 2; ++n) _Pragma("unroll") for (int k = 0; k < 2; ++k) \
;         acc[ai][bj][m][n] = __builtin_amdgcn_mfma_f32_16x16x32_bf16(Bt[n][k], At[m][k], acc[ai][bj][m][n], 0, 0, 0); __builtin_amdgcn_s_setprio(0); } while (0)
; #define PG8_WAIT_V(n) asm volatile("s_waitcnt vmcnt(" #n ")" ::: "memory")
; #define PG8_WAIT_L(n) asm volatile("s_waitcnt lgkmcnt(" #n ")" ::: "memory")
; #define PG8_BAR __builtin_amdgcn_s_barrier()
; #define PG8_SCHED __builtin_amdgcn_sched_barrier(0)
; template <class Epi, class Sched, bool ALIGN_EPI = false, bool SP2 = false>
; __device__ __forceinline__ void gemm_phase(PG8_LAS unsigned char* lds, const Gemm g, const Sched& S, const Epi& E) {
;     ...
;             PG8_LDB(B0, 0, 0); PG8_LDB(B1, 0, 1); PG8_SCHED; PG8_LDA(At, 0, 0); PG8_STAGE(PG8_SA(1, 1), a1 + hstep, voffA);
;             PG8_WAIT_V(8); PG8_WAIT_L(0); PG8_BAR; PG8_MMA(0, 0, At, B0); PG8_MMA(0, 1, At, B1); PG8_BAR; PG8_SCHED;
;             PG8_LDA(At, 0, 1); PG8_STAGE(PG8_SB(0, 0), b2, voffB); PG8_STAGE(PG8_SB(0, 1), b2 + hstep, voffB); PG8_STAGE(PG8_SA(0, 0), a2, voffA);
;             PG8_WAIT_V(8); PG8_WAIT_L(0); PG8_BAR; PG8_MMA(1, 0, At, B0); PG8_MMA(1, 1, At, B1); PG8_BAR; PG8_SCHED;
.LBB0_816:
	s_add_u32 s59, s30, 0x100
	s_addc_u32 s60, s31, 0
	s_mov_b32 s61, -2
	s_waitcnt lgkmcnt(0)
	v_lshl_add_u64 v[168:169], s[18:19], 0, v[160:161]
	s_add_i32 m0, s2, 0xc000
	global_load_lds_dwordx4 v[168:169], off
	s_add_i32 m0, s2, 0xe000
	v_lshl_add_u64 v[168:169], s[18:19], 0, v[162:163]
	global_load_lds_dwordx4 v[168:169], off
	s_add_u32 s30, s18, 0x100
	s_addc_u32 s31, s19, 0
	s_add_i32 s24, 0, 0x10000
	s_cmpk_eq_i32 s61, 0x54
	s_cselect_b32 s39, s5, s31
	s_cselect_b32 s38, s4, s30
	s_cselect_b32 s37, s15, s60
	s_cselect_b32 s36, s14, s59
	s_add_i32 s25, 0, 0x14000
	s_waitcnt vmcnt(8)
	s_waitcnt lgkmcnt(0)
	s_barrier
	s_setprio 1
	s_waitcnt lgkmcnt(0)
	v_mfma_f32_16x16x32_bf16 v[124:127], v[128:131], v[178:181], 0
	v_mfma_f32_16x16x32_bf16 v[120:123], v[136:139], v[178:181], 0
	v_mfma_f32_16x16x32_bf16 v[108:111], v[128:131], v[186:189], 0
	v_mfma_f32_16x16x32_bf16 v[104:107], v[136:139], v[186:189], 0
	v_mfma_f32_16x16x32_bf16 v[92:95], v[128:131], v[202:205], 0
	v_mfma_f32_16x16x32_bf16 v[88:91], v[136:139], v[202:205], 0
	v_mfma_f32_16x16x32_bf16 v[76:79], v[128:131], v[210:213], 0
	v_mfma_f32_16x16x32_bf16 v[72:75], v[136:139], v[210:213], 0
	v_mfma_f32_16x16x32_bf16 v[124:127], v[132:135], v[182:185], v[124:127]
	v_mfma_f32_16x16x32_bf16 v[120:123], v[140:143], v[182:185], v[120:123]
	v_mfma_f32_16x16x32_bf16 v[108:111], v[132:135], v[194:197], v[108:111]
	v_mfma_f32_16x16x32_bf16 v[104:107], v[140:143], v[194:197], v[104:107]
	v_mfma_f32_16x16x32_bf16 v[92:95], v[132:135], v[206:209], v[92:95]
	v_mfma_f32_16x16x32_bf16 v[88:91], v[140:143], v[206:209], v[88:91]
	v_mfma_f32_16x16x32_bf16 v[76:79], v[132:135], v[214:217], v[76:79]
	v_mfma_f32_16x16x32_bf16 v[72:75], v[140:143], v[214:217], v[72:75]
	s_setprio 0
	s_setprio 1
	v_mfma_f32_16x16x32_bf16 v[116:119], v[144:147], v[178:181], 0
	v_mfma_f32_16x16x32_bf16 v[112:115], v[164:167], v[178:181], 0
	v_mfma_f32_16x16x32_bf16 v[100:103], v[144:147], v[186:189], 0
	v_mfma_f32_16x16x32_bf16 v[96:99], v[164:167], v[186:189], 0
	v_mfma_f32_16x16x32_bf16 v[84:87], v[144:147], v[202:205], 0
	v_mfma_f32_16x16x32_bf16 v[80:83], v[164:167], v[202:205], 0
	v_mfma_f32_16x16x32_bf16 v[68:71], v[144:147], v[210:213], 0
	v_mfma_f32_16x16x32_bf16 v[64:67], v[164:167], v[210:213], 0
	v_mfma_f32_16x16x32_bf16 v[116:119], v[148:151], v[182:185], v[116:119]
	v_mfma_f32_16x16x32_bf16 v[112:115], v[174:177], v[182:185], v[112:115]
	v_mfma_f32_16x16x32_bf16 v[100:103], v[148:151], v[194:197], v[100:103]
	v_mfma_f32_16x16x32_bf16 v[96:99], v[174:177], v[194:197], v[96:99]
	v_mfma_f32_16x16x32_bf16 v[84:87], v[148:151], v[206:209], v[84:87]
	v_mfma_f32_16x16x32_bf16 v[80:83], v[174:177], v[206:209], v[80:83]
	s_barrier
	s_setprio 2
	v_mfma_f32_16x16x32_bf16 v[68:71], v[148:151], v[214:217], v[68:71]
	v_mfma_f32_16x16x32_bf16 v[64:67], v[174:177], v[214:217], v[64:67]
	s_setprio 0
	s_add_i32 s18, s24, s43
	v_lshl_add_u64 v[168:169], s[36:37], 0, v[156:157]
	s_mov_b32 m0, s18
	ds_read_b128 v[178:181], v173 offset:16384
	ds_read_b128 v[182:185], v173 offset:17408
	ds_read_b128 v[186:189], v173 offset:18432
	ds_read_b128 v[194:197], v173 offset:19456
	ds_read_b128 v[202:205], v173 offset:20480
	ds_read_b128 v[206:209], v173 offset:21504
	ds_read_b128 v[210:213], v173 offset:22528
	ds_read_b128 v[214:217], v173 offset:23552
	global_load_lds_dwordx4 v[168:169], off
	s_add_i32 m0, s18, 0x2000
	s_add_u32 s18, s36, 0x160000
	v_lshl_add_u64 v[190:191], s[36:37], 0, v[152:153]
	s_addc_u32 s19, s37, 0
	s_add_i32 s24, s25, s43
	global_load_lds_dwordx4 v[190:191], off
	v_lshl_add_u64 v[218:219], s[18:19], 0, v[156:157]
	s_mov_b32 m0, s24
	v_lshl_add_u64 v[220:221], s[38:39], 0, v[154:155]
	global_load_lds_dwordx4 v[218:219], off
	s_add_i32 m0, s24, 0x2000
	v_lshl_add_u64 v[218:219], s[18:19], 0, v[152:153]
	global_load_lds_dwordx4 v[218:219], off
	s_mov_b32 m0, s2
	v_lshl_add_u64 v[218:219], s[38:39], 0, v[158:159]
	global_load_lds_dwordx4 v[218:219], off
	s_mov_b32 m0, s44
	s_nop 0
	global_load_lds_dwordx4 v[220:221], off
	s_waitcnt vmcnt(8)
	s_waitcnt lgkmcnt(0)
	s_barrier
	s_setprio 1
	s_waitcnt lgkmcnt(0)
	v_mfma_f32_16x16x32_bf16 v[60:63], v[128:131], v[178:181], 0
	v_mfma_f32_16x16x32_bf16 v[56:59], v[136:139], v[178:181], 0
	v_mfma_f32_16x16x32_bf16 v[44:47], v[128:131], v[186:189], 0
	v_mfma_f32_16x16x32_bf16 v[40:43], v[136:139], v[186:189], 0
	v_mfma_f32_16x16x32_bf16 v[28:31], v[128:131], v[202:205], 0
	v_mfma_f32_16x16x32_bf16 v[24:27], v[136:139], v[202:205], 0
	v_mfma_f32_16x16x32_bf16 v[12:15], v[128:131], v[210:213], 0
	v_mfma_f32_16x16x32_bf16 v[8:11], v[136:139], v[210:213], 0
	v_mfma_f32_16x16x32_bf16 v[60:63], v[132:135], v[182:185], v[60:63]
	v_mfma_f32_16x16x32_bf16 v[56:59], v[140:143], v[182:185], v[56:59]
	v_mfma_f32_16x16x32_bf16 v[44:47], v[132:135], v[194:197], v[44:47]
	v_mfma_f32_16x16x32_bf16 v[40:43], v[140:143], v[194:197], v[40:43]
	v_mfma_f32_16x16x32_bf16 v[28:31], v[132:135], v[206:209], v[28:31]
	v_mfma_f32_16x16x32_bf16 v[24:27], v[140:143], v[206:209], v[24:27]
	v_mfma_f32_16x16x32_bf16 v[12:15], v[132:135], v[214:217], v[12:15]
	v_mfma_f32_16x16x32_bf16 v[8:11], v[140:143], v[214:217], v[8:11]
	s_setprio 0
	s_setprio 1
	v_mfma_f32_16x16x32_bf16 v[52:55], v[144:147], v[178:181], 0
	v_mfma_f32_16x16x32_bf16 v[48:51], v[164:167], v[178:181], 0
	v_mfma_f32_16x16x32_bf16 v[36:39], v[144:147], v[186:189], 0
	v_mfma_f32_16x16x32_bf16 v[32:35], v[164:167], v[186:189], 0
	v_mfma_f32_16x16x32_bf16 v[20:23], v[144:147], v[202:205], 0
	v_mfma_f32_16x16x32_bf16 v[16:19], v[164:167], v[202:205], 0
	v_mfma_f32_16x16x32_bf16 v[4:7], v[144:147], v[210:213], 0
	v_mfma_f32_16x16x32_bf16 v[0:3], v[164:167], v[210:213], 0
	v_mfma_f32_16x16x32_bf16 v[52:55], v[148:151], v[182:185], v[52:55]
	v_mfma_f32_16x16x32_bf16 v[48:51], v[174:177], v[182:185], v[48:51]
	v_mfma_f32_16x16x32_bf16 v[36:39], v[148:151], v[194:197], v[36:39]
	v_mfma_f32_16x16x32_bf16 v[32:35], v[174:177], v[194:197], v[32:35]
	v_mfma_f32_16x16x32_bf16 v[20:23], v[148:151], v[206:209], v[20:23]
	v_mfma_f32_16x16x32_bf16 v[16:19], v[174:177], v[206:209], v[16:19]
	s_barrier
; #define PG8_STAGE(bufoff, gbase, voff) do { _Pragma("unroll") for (int _i = 0; _i < 2; ++_i) \
;         __builtin_amdgcn_global_load_lds((const unsigned*)((const char*)(gbase) + (voff)[_i]), (PG8_LAS unsigned*)(lds + (bufoff) + ldsw + _i * 8192), 16, 0, 0); } while (0)
; #define PG8_LDA(dst, b, h) do { _Pragma("unroll") for (int m = 0; m < 4; ++m) _Pragma("unroll") for (int k = 0; k < 2; ++k) dst[m][k] = *(const PG8_LAS bf16x8*)(lds + PG8_SA(b, h) + aoff + m * 2048 + k * 1024); } while (0)
; #define PG8_LDB(dst, b, h) do { _Pragma("unroll") for (int n = 0; n < 2; ++n) _Pragma("unroll") for (int k = 0; k < 2; ++k) dst[n][k] = *(const PG8_LAS bf16x8*)(lds + PG8_SB(b, h) + boff + n * 2048 + k * 1024); } while (0)
; #define PG8_MMA(ai, bj, At, Bt) do { __builtin_amdgcn_s_setprio(1); _Pragma("unroll") for (int m = 0; m < 4; ++m) _Pragma("unroll") for (int n = 0; n < 2; ++n) _Pragma("unroll") for (int k = 0; k < 2; ++k) \
;         acc[ai][bj][m][n] = __builtin_amdgcn_mfma_f32_16x16x32_bf16(Bt[n][k], At[m][k], acc[ai][bj][m][n], 0, 0, 0); __builtin_amdgcn_s_setprio(0); } while (0)
; #define PG8_WAIT_V(n) asm volatile("s_waitcnt vmcnt(" #n ")" ::: "memory")
; #define PG8_WAIT_L(n) asm volatile("s_waitcnt lgkmcnt(" #n ")" ::: "memory")
; #define PG8_BAR __builtin_amdgcn_s_barrier()
; #define PG8_SCHED __builtin_amdgcn_sched_barrier(0)
; template <class Epi, class Sched, bool ALIGN_EPI = false, bool SP2 = false>
; __device__ __forceinline__ void gemm_phase(PG8_LAS unsigned char* lds, const Gemm g, const Sched& S, const Epi& E) {
;     ...
;             PG8_WAIT_V(8); PG8_WAIT_L(0); PG8_BAR; PG8_MMA(1, 0, At, B0); PG8_MMA(1, 1, At, B1); PG8_BAR; PG8_SCHED;
;             PG8_LDB(B0, 1, 0); PG8_LDB(B1, 1, 1); PG8_SCHED; PG8_LDA(At, 1, 0); PG8_STAGE(PG8_SA(0, 1), a2 + hstep, voffA);
;             PG8_WAIT_V(8); PG8_WAIT_L(0); PG8_BAR; PG8_MMA(0, 0, At, B0); PG8_MMA(0, 1, At, B1); PG8_BAR; PG8_SCHED;
;             PG8_LDA(At, 1, 1); PG8_STAGE(PG8_SB(1, 0), b3, voffB); PG8_STAGE(PG8_SB(1, 1), b3 + hstep, voffB); PG8_STAGE(PG8_SA(1, 0), a3, voffA);
	s_setprio 2
	v_mfma_f32_16x16x32_bf16 v[4:7], v[148:151], v[214:217], v[4:7]
	v_mfma_f32_16x16x32_bf16 v[0:3], v[174:177], v[214:217], v[0:3]
	s_setprio 0
	s_add_i32 s24, 0, 0x18000
	s_add_i32 s25, 0, 0x1c000
	v_add_u32_e32 v140, 0x18000, v172
	v_add_u32_e32 v174, 0x1c000, v172
	ds_read_b128 v[128:131], v140
	ds_read_b128 v[132:135], v140 offset:1024
	ds_read_b128 v[136:139], v140 offset:2048
	ds_read_b128 v[140:143], v140 offset:3072
	ds_read_b128 v[144:147], v174
	ds_read_b128 v[148:151], v174 offset:1024
	ds_read_b128 v[164:167], v174 offset:2048
	ds_read_b128 v[174:177], v174 offset:3072
	s_add_u32 s18, s38, 0x160000
	s_addc_u32 s19, s39, 0
	s_mov_b32 m0, s45
	v_lshl_add_u64 v[230:231], s[18:19], 0, v[158:159]
	ds_read_b128 v[178:181], v173 offset:32768
	ds_read_b128 v[182:185], v173 offset:33792
	ds_read_b128 v[186:189], v173 offset:34816
	ds_read_b128 v[194:197], v173 offset:35840
	ds_read_b128 v[202:205], v173 offset:36864
	ds_read_b128 v[206:209], v173 offset:37888
	ds_read_b128 v[210:213], v173 offset:38912
	ds_read_b128 v[214:217], v173 offset:39936
	global_load_lds_dwordx4 v[230:231], off
	s_mov_b32 m0, s46
	v_lshl_add_u64 v[230:231], s[18:19], 0, v[154:155]
	global_load_lds_dwordx4 v[230:231], off
	s_waitcnt vmcnt(8)
	s_waitcnt lgkmcnt(0)
	s_barrier
	s_setprio 1
	s_waitcnt lgkmcnt(0)
	v_mfma_f32_16x16x32_bf16 v[124:127], v[128:131], v[178:181], v[124:127]
	v_mfma_f32_16x16x32_bf16 v[120:123], v[136:139], v[178:181], v[120:123]
	v_mfma_f32_16x16x32_bf16 v[108:111], v[128:131], v[186:189], v[108:111]
	v_mfma_f32_16x16x32_bf16 v[104:107], v[136:139], v[186:189], v[104:107]
	v_mfma_f32_16x16x32_bf16 v[92:95], v[128:131], v[202:205], v[92:95]
	v_mfma_f32_16x16x32_bf16 v[88:91], v[136:139], v[202:205], v[88:91]
	v_mfma_f32_16x16x32_bf16 v[76:79], v[128:131], v[210:213], v[76:79]
	v_mfma_f32_16x16x32_bf16 v[72:75], v[136:139], v[210:213], v[72:75]
	v_mfma_f32_16x16x32_bf16 v[124:127], v[132:135], v[182:185], v[124:127]
	v_mfma_f32_16x16x32_bf16 v[120:123], v[140:143], v[182:185], v[120:123]
	v_mfma_f32_16x16x32_bf16 v[108:111], v[132:135], v[194:197], v[108:111]
	v_mfma_f32_16x16x32_bf16 v[104:107], v[140:143], v[194:197], v[104:107]
	v_mfma_f32_16x16x32_bf16 v[92:95], v[132:135], v[206:209], v[92:95]
	v_mfma_f32_16x16x32_bf16 v[88:91], v[140:143], v[206:209], v[88:91]
	v_mfma_f32_16x16x32_bf16 v[76:79], v[132:135], v[214:217], v[76:79]
	v_mfma_f32_16x16x32_bf16 v[72:75], v[140:143], v[214:217], v[72:75]
	s_setprio 0
	s_setprio 1
	v_mfma_f32_16x16x32_bf16 v[116:119], v[144:147], v[178:181], v[116:119]
	v_mfma_f32_16x16x32_bf16 v[112:115], v[164:167], v[178:181], v[112:115]
	v_mfma_f32_16x16x32_bf16 v[100:103], v[144:147], v[186:189], v[100:103]
	v_mfma_f32_16x16x32_bf16 v[96:99], v[164:167], v[186:189], v[96:99]
	v_mfma_f32_16x16x32_bf16 v[84:87], v[144:147], v[202:205], v[84:87]
	v_mfma_f32_16x16x32_bf16 v[80:83], v[164:167], v[202:205], v[80:83]
	v_mfma_f32_16x16x32_bf16 v[68:71], v[144:147], v[210:213], v[68:71]
	v_mfma_f32_16x16x32_bf16 v[64:67], v[164:167], v[210:213], v[64:67]
	v_mfma_f32_16x16x32_bf16 v[116:119], v[148:151], v[182:185], v[116:119]
	v_mfma_f32_16x16x32_bf16 v[112:115], v[174:177], v[182:185], v[112:115]
	v_mfma_f32_16x16x32_bf16 v[100:103], v[148:151], v[194:197], v[100:103]
	v_mfma_f32_16x16x32_bf16 v[96:99], v[174:177], v[194:197], v[96:99]
	v_mfma_f32_16x16x32_bf16 v[84:87], v[148:151], v[206:209], v[84:87]
	v_mfma_f32_16x16x32_bf16 v[80:83], v[174:177], v[206:209], v[80:83]
	s_barrier
	s_setprio 2
	v_mfma_f32_16x16x32_bf16 v[68:71], v[148:151], v[214:217], v[68:71]
	v_mfma_f32_16x16x32_bf16 v[64:67], v[174:177], v[214:217], v[64:67]
	s_setprio 0
	s_add_i32 s18, s24, s43
	v_lshl_add_u64 v[168:169], v[168:169], 0, s[16:17]
	s_mov_b32 m0, s18
	ds_read_b128 v[178:181], v173 offset:49152
	ds_read_b128 v[182:185], v173 offset:50176
	ds_read_b128 v[186:189], v173 offset:51200
	ds_read_b128 v[194:197], v173 offset:52224
	ds_read_b128 v[202:205], v173 offset:53248
	ds_read_b128 v[206:209], v173 offset:54272
	ds_read_b128 v[210:213], v173 offset:55296
	ds_read_b128 v[214:217], v173 offset:56320
	global_load_lds_dwordx4 v[168:169], off
	s_add_i32 m0, s18, 0x2000
	s_add_u32 s18, s36, 0x160080
	v_lshl_add_u64 v[168:169], v[190:191], 0, s[16:17]
	s_addc_u32 s19, s37, 0
	s_add_i32 s24, s25, s43
	global_load_lds_dwordx4 v[168:169], off
	s_mov_b32 m0, s24
	v_lshl_add_u64 v[168:169], s[18:19], 0, v[156:157]
	global_load_lds_dwordx4 v[168:169], off
	s_add_i32 m0, s24, 0x2000
	v_lshl_add_u64 v[168:169], s[18:19], 0, v[152:153]
	global_load_lds_dwordx4 v[168:169], off
	s_mov_b32 m0, s51
	v_lshl_add_u64 v[168:169], v[218:219], 0, s[16:17]
	global_load_lds_dwordx4 v[168:169], off
	s_mov_b32 m0, s52
	v_lshl_add_u64 v[168:169], v[220:221], 0, s[16:17]
	global_load_lds_dwordx4 v[168:169], off
	s_waitcnt vmcnt(8)
	s_waitcnt lgkmcnt(0)
	s_barrier
; #define PG8_STAGE(bufoff, gbase, voff) do { _Pragma("unroll") for (int _i = 0; _i < 2; ++_i) \
;         __builtin_amdgcn_global_load_lds((const unsigned*)((const char*)(gbase) + (voff)[_i]), (PG8_LAS unsigned*)(lds + (bufoff) + ldsw + _i * 8192), 16, 0, 0); } while (0)
; #define PG8_LDA(dst, b, h) do { _Pragma("unroll") for (int m = 0; m < 4; ++m) _Pragma("unroll") for (int k = 0; k < 2; ++k) dst[m][k] = *(const PG8_LAS bf16x8*)(lds + PG8_SA(b, h) + aoff + m * 2048 + k * 1024); } while (0)
; #define PG8_LDB(dst, b, h) do { _Pragma("unroll") for (int n = 0; n < 2; ++n) _Pragma("unroll") for (int k = 0; k < 2; ++k) dst[n][k] = *(const PG8_LAS bf16x8*)(lds + PG8_SB(b, h) + boff + n * 2048 + k * 1024); } while (0)
; #define PG8_MMA(ai, bj, At, Bt) do { __builtin_amdgcn_s_setprio(1); _Pragma("unroll") for (int m = 0; m < 4; ++m) _Pragma("unroll") for (int n = 0; n < 2; ++n) _Pragma("unroll") for (int k = 0; k < 2; ++k) \
;         acc[ai][bj][m][n] = __builtin_amdgcn_mfma_f32_16x16x32_bf16(Bt[n][k], At[m][k], acc[ai][bj][m][n], 0, 0, 0); __builtin_amdgcn_s_setprio(0); } while (0)
; #define PG8_WAIT_V(n) asm volatile("s_waitcnt vmcnt(" #n ")" ::: "memory")
; template <class Epi, class Sched, bool ALIGN_EPI = false, bool SP2 = false>
; __device__ __forceinline__ void gemm_phase(PG8_LAS unsigned char* lds, const Gemm g, const Sched& S, const Epi& E) {
;     ...
;             PG8_LDB(B0, 0, 0); PG8_LDB(B1, 0, 1); PG8_SCHED; PG8_LDA(At, 0, 0); PG8_STAGE(PG8_SA(1, 1), a1 + hstep, voffA);
;             PG8_WAIT_V(8); PG8_WAIT_L(0); PG8_BAR; PG8_MMA(0, 0, At, B0); PG8_MMA(0, 1, At, B1); PG8_BAR; PG8_SCHED;
;             PG8_LDA(At, 0, 1); PG8_STAGE(PG8_SB(0, 0), b2, voffB); PG8_STAGE(PG8_SB(0, 1), b2 + hstep, voffB); PG8_STAGE(PG8_SA(0, 0), a2, voffA);
;             PG8_WAIT_V(8); PG8_WAIT_L(0); PG8_BAR; PG8_MMA(1, 0, At, B0); PG8_MMA(1, 1, At, B1); PG8_BAR; PG8_SCHED;
;             PG8_LDB(B0, 1, 0); PG8_LDB(B1, 1, 1); PG8_SCHED; PG8_LDA(At, 1, 0); PG8_STAGE(PG8_SA(0, 1), a2 + hstep, voffA);
;             PG8_WAIT_V(8); PG8_WAIT_L(0); PG8_BAR; PG8_MMA(0, 0, At, B0); PG8_MMA(0, 1, At, B1); PG8_BAR; PG8_SCHED;
;             PG8_LDA(At, 1, 1); PG8_STAGE(PG8_SB(1, 0), b3, voffB); PG8_STAGE(PG8_SB(1, 1), b3 + hstep, voffB); PG8_STAGE(PG8_SA(1, 0), a3, voffA);
;             PG8_WAIT_V(8); PG8_WAIT_L(0); PG8_BAR; PG8_MMA(1, 0, At, B0); PG8_MMA(1, 1, At, B1); PG8_BAR; PG8_SCHED;
	s_setprio 1
	s_waitcnt lgkmcnt(0)
	v_mfma_f32_16x16x32_bf16 v[60:63], v[128:131], v[178:181], v[60:63]
	v_mfma_f32_16x16x32_bf16 v[56:59], v[136:139], v[178:181], v[56:59]
	v_mfma_f32_16x16x32_bf16 v[44:47], v[128:131], v[186:189], v[44:47]
	v_mfma_f32_16x16x32_bf16 v[40:43], v[136:139], v[186:189], v[40:43]
	v_mfma_f32_16x16x32_bf16 v[28:31], v[128:131], v[202:205], v[28:31]
	v_mfma_f32_16x16x32_bf16 v[24:27], v[136:139], v[202:205], v[24:27]
	v_mfma_f32_16x16x32_bf16 v[12:15], v[128:131], v[210:213], v[12:15]
	v_mfma_f32_16x16x32_bf16 v[8:11], v[136:139], v[210:213], v[8:11]
	v_mfma_f32_16x16x32_bf16 v[60:63], v[132:135], v[182:185], v[60:63]
	v_mfma_f32_16x16x32_bf16 v[56:59], v[140:143], v[182:185], v[56:59]
	v_mfma_f32_16x16x32_bf16 v[44:47], v[132:135], v[194:197], v[44:47]
	v_mfma_f32_16x16x32_bf16 v[40:43], v[140:143], v[194:197], v[40:43]
	v_mfma_f32_16x16x32_bf16 v[28:31], v[132:135], v[206:209], v[28:31]
	v_mfma_f32_16x16x32_bf16 v[24:27], v[140:143], v[206:209], v[24:27]
	v_mfma_f32_16x16x32_bf16 v[12:15], v[132:135], v[214:217], v[12:15]
	v_mfma_f32_16x16x32_bf16 v[8:11], v[140:143], v[214:217], v[8:11]
	s_setprio 0
	s_setprio 1
	v_mfma_f32_16x16x32_bf16 v[52:55], v[144:147], v[178:181], v[52:55]
	v_mfma_f32_16x16x32_bf16 v[48:51], v[164:167], v[178:181], v[48:51]
	v_mfma_f32_16x16x32_bf16 v[36:39], v[144:147], v[186:189], v[36:39]
	v_mfma_f32_16x16x32_bf16 v[32:35], v[164:167], v[186:189], v[32:35]
	v_mfma_f32_16x16x32_bf16 v[20:23], v[144:147], v[202:205], v[20:23]
	v_mfma_f32_16x16x32_bf16 v[16:19], v[164:167], v[202:205], v[16:19]
	v_mfma_f32_16x16x32_bf16 v[4:7], v[144:147], v[210:213], v[4:7]
	v_mfma_f32_16x16x32_bf16 v[0:3], v[164:167], v[210:213], v[0:3]
	v_mfma_f32_16x16x32_bf16 v[52:55], v[148:151], v[182:185], v[52:55]
	v_mfma_f32_16x16x32_bf16 v[48:51], v[174:177], v[182:185], v[48:51]
	v_mfma_f32_16x16x32_bf16 v[36:39], v[148:151], v[194:197], v[36:39]
	v_mfma_f32_16x16x32_bf16 v[32:35], v[174:177], v[194:197], v[32:35]
	v_mfma_f32_16x16x32_bf16 v[20:23], v[148:151], v[206:209], v[20:23]
	v_mfma_f32_16x16x32_bf16 v[16:19], v[174:177], v[206:209], v[16:19]
	s_barrier
	s_setprio 2
	v_mfma_f32_16x16x32_bf16 v[4:7], v[148:151], v[214:217], v[4:7]
	v_mfma_f32_16x16x32_bf16 v[0:3], v[174:177], v[214:217], v[0:3]
	s_setprio 0
	s_add_i32 s61, s61, 2
	s_add_u32 s59, s59, 0x100
	s_addc_u32 s60, s60, 0
	s_cmpk_gt_u32 s61, 0x55
	s_mov_b64 s[18:19], s[30:31]
	s_branch .LBB0_817
.LBB0_817:
	v_add_u32_e32 v140, 0x10000, v172
	v_add_u32_e32 v168, 0x14000, v172
	ds_read_b128 v[128:131], v140
	ds_read_b128 v[132:135], v140 offset:1024
	ds_read_b128 v[136:139], v140 offset:2048
	ds_read_b128 v[140:143], v140 offset:3072
	ds_read_b128 v[144:147], v168
	ds_read_b128 v[148:151], v168 offset:1024
	ds_read_b128 v[164:167], v168 offset:2048
	ds_read_b128 v[174:177], v168 offset:3072
	v_lshl_add_u64 v[168:169], s[18:19], 0, v[160:161]
	s_add_i32 m0, s2, 0xc000
	ds_read_b128 v[178:181], v173
	ds_read_b128 v[182:185], v173 offset:1024
	ds_read_b128 v[186:189], v173 offset:2048
	ds_read_b128 v[194:197], v173 offset:3072
	ds_read_b128 v[202:205], v173 offset:4096
	ds_read_b128 v[206:209], v173 offset:5120
	ds_read_b128 v[210:213], v173 offset:6144
	ds_read_b128 v[214:217], v173 offset:7168
	global_load_lds_dwordx4 v[168:169], off
	s_add_i32 m0, s2, 0xe000
	v_lshl_add_u64 v[168:169], s[18:19], 0, v[162:163]
	global_load_lds_dwordx4 v[168:169], off
	s_add_u32 s30, s18, 0x100
	s_addc_u32 s31, s19, 0
	s_add_i32 s24, 0, 0x10000
	s_cmpk_eq_i32 s61, 0x54
	s_cselect_b32 s39, s5, s31
	s_cselect_b32 s38, s4, s30
	s_cselect_b32 s37, s15, s60
	s_cselect_b32 s36, s14, s59
	s_add_i32 s25, 0, 0x14000
	s_waitcnt vmcnt(8)
	s_waitcnt lgkmcnt(0)
	s_barrier
	s_setprio 1
	s_waitcnt lgkmcnt(0)
	v_mfma_f32_16x16x32_bf16 v[124:127], v[128:131], v[178:181], v[124:127]
	v_mfma_f32_16x16x32_bf16 v[120:123], v[136:139], v[178:181], v[120:123]
	v_mfma_f32_16x16x32_bf16 v[108:111], v[128:131], v[186:189], v[108:111]
	v_mfma_f32_16x16x32_bf16 v[104:107], v[136:139], v[186:189], v[104:107]
	v_mfma_f32_16x16x32_bf16 v[92:95], v[128:131], v[202:205], v[92:95]
	v_mfma_f32_16x16x32_bf16 v[88:91], v[136:139], v[202:205], v[88:91]
	v_mfma_f32_16x16x32_bf16 v[76:79], v[128:131], v[210:213], v[76:79]
	v_mfma_f32_16x16x32_bf16 v[72:75], v[136:139], v[210:213], v[72:75]
	v_mfma_f32_16x16x32_bf16 v[124:127], v[132:135], v[182:185], v[124:127]
	v_mfma_f32_16x16x32_bf16 v[120:123], v[140:143], v[182:185], v[120:123]
	v_mfma_f32_16x16x32_bf16 v[108:111], v[132:135], v[194:197], v[108:111]
	v_mfma_f32_16x16x32_bf16 v[104:107], v[140:143], v[194:197], v[104:107]
	v_mfma_f32_16x16x32_bf16 v[92:95], v[132:135], v[206:209], v[92:95]
	v_mfma_f32_16x16x32_bf16 v[88:91], v[140:143], v[206:209], v[88:91]
	v_mfma_f32_16x16x32_bf16 v[76:79], v[132:135], v[214:217], v[76:79]
	v_mfma_f32_16x16x32_bf16 v[72:75], v[140:143], v[214:217], v[72:75]
	s_setprio 0
	s_setprio 1
	v_mfma_f32_16x16x32_bf16 v[116:119], v[144:147], v[178:181], v[116:119]
	v_mfma_f32_16x16x32_bf16 v[112:115], v[164:167], v[178:181], v[112:115]
	v_mfma_f32_16x16x32_bf16 v[100:103], v[144:147], v[186:189], v[100:103]
	v_mfma_f32_16x16x32_bf16 v[96:99], v[164:167], v[186:189], v[96:99]
	v_mfma_f32_16x16x32_bf16 v[84:87], v[144:147], v[202:205], v[84:87]
	v_mfma_f32_16x16x32_bf16 v[80:83], v[164:167], v[202:205], v[80:83]
	v_mfma_f32_16x16x32_bf16 v[68:71], v[144:147], v[210:213], v[68:71]
	v_mfma_f32_16x16x32_bf16 v[64:67], v[164:167], v[210:213], v[64:67]
	v_mfma_f32_16x16x32_bf16 v[116:119], v[148:151], v[182:185], v[116:119]
	v_mfma_f32_16x16x32_bf16 v[112:115], v[174:177], v[182:185], v[112:115]
	v_mfma_f32_16x16x32_bf16 v[100:103], v[148:151], v[194:197], v[100:103]
	v_mfma_f32_16x16x32_bf16 v[96:99], v[174:177], v[194:197], v[96:99]
	v_mfma_f32_16x16x32_bf16 v[84:87], v[148:151], v[206:209], v[84:87]
	v_mfma_f32_16x16x32_bf16 v[80:83], v[174:177], v[206:209], v[80:83]
	s_barrier
; #define PG8_STAGE(bufoff, gbase, voff) do { _Pragma("unroll") for (int _i = 0; _i < 2; ++_i) \
;         __builtin_amdgcn_global_load_lds((const unsigned*)((const char*)(gbase) + (voff)[_i]), (PG8_LAS unsigned*)(lds + (bufoff) + ldsw + _i * 8192), 16, 0, 0); } while (0)
; #define PG8_LDA(dst, b, h) do { _Pragma("unroll") for (int m = 0; m < 4; ++m) _Pragma("unroll") for (int k = 0; k < 2; ++k) dst[m][k] = *(const PG8_LAS bf16x8*)(lds + PG8_SA(b, h) + aoff + m * 2048 + k * 1024); } while (0)
; #define PG8_LDB(dst, b, h) do { _Pragma("unroll") for (int n = 0; n < 2; ++n) _Pragma("unroll") for (int k = 0; k < 2; ++k) dst[n][k] = *(const PG8_LAS bf16x8*)(lds + PG8_SB(b, h) + boff + n * 2048 + k * 1024); } while (0)
; #define PG8_MMA(ai, bj, At, Bt) do { __builtin_amdgcn_s_setprio(1); _Pragma("unroll") for (int m = 0; m < 4; ++m) _Pragma("unroll") for (int n = 0; n < 2; ++n) _Pragma("unroll") for (int k = 0; k < 2; ++k) \
;         acc[ai][bj][m][n] = __builtin_amdgcn_mfma_f32_16x16x32_bf16(Bt[n][k], At[m][k], acc[ai][bj][m][n], 0, 0, 0); __builtin_amdgcn_s_setprio(0); } while (0)
; #define PG8_WAIT_V(n) asm volatile("s_waitcnt vmcnt(" #n ")" ::: "memory")
; #define PG8_WAIT_L(n) asm volatile("s_waitcnt lgkmcnt(" #n ")" ::: "memory")
; #define PG8_BAR __builtin_amdgcn_s_barrier()
; #define PG8_SCHED __builtin_amdgcn_sched_barrier(0)
; template <class Epi, class Sched, bool ALIGN_EPI = false, bool SP2 = false>
; __device__ __forceinline__ void gemm_phase(PG8_LAS unsigned char* lds, const Gemm g, const Sched& S, const Epi& E) {
;     ...
;             PG8_WAIT_V(8); PG8_WAIT_L(0); PG8_BAR; PG8_MMA(0, 0, At, B0); PG8_MMA(0, 1, At, B1); PG8_BAR; PG8_SCHED;
;             PG8_LDA(At, 0, 1); PG8_STAGE(PG8_SB(0, 0), b2, voffB); PG8_STAGE(PG8_SB(0, 1), b2 + hstep, voffB); PG8_STAGE(PG8_SA(0, 0), a2, voffA);
;             PG8_WAIT_V(8); PG8_WAIT_L(0); PG8_BAR; PG8_MMA(1, 0, At, B0); PG8_MMA(1, 1, At, B1); PG8_BAR; PG8_SCHED;
;             PG8_LDB(B0, 1, 0); PG8_LDB(B1, 1, 1); PG8_SCHED; PG8_LDA(At, 1, 0); PG8_STAGE(PG8_SA(0, 1), a2 + hstep, voffA);
;             PG8_WAIT_V(8); PG8_WAIT_L(0); PG8_BAR; PG8_MMA(0, 0, At, B0); PG8_MMA(0, 1, At, B1); PG8_BAR; PG8_SCHED;
	s_setprio 2
	v_mfma_f32_16x16x32_bf16 v[68:71], v[148:151], v[214:217], v[68:71]
	v_mfma_f32_16x16x32_bf16 v[64:67], v[174:177], v[214:217], v[64:67]
	s_setprio 0
	s_add_i32 s18, s24, s43
	v_lshl_add_u64 v[168:169], s[36:37], 0, v[156:157]
	s_mov_b32 m0, s18
	ds_read_b128 v[178:181], v173 offset:16384
	ds_read_b128 v[182:185], v173 offset:17408
	ds_read_b128 v[186:189], v173 offset:18432
	ds_read_b128 v[194:197], v173 offset:19456
	ds_read_b128 v[202:205], v173 offset:20480
	ds_read_b128 v[206:209], v173 offset:21504
	ds_read_b128 v[210:213], v173 offset:22528
	ds_read_b128 v[214:217], v173 offset:23552
	global_load_lds_dwordx4 v[168:169], off
	s_add_i32 m0, s18, 0x2000
	s_add_u32 s18, s36, 0x160000
	v_lshl_add_u64 v[190:191], s[36:37], 0, v[152:153]
	s_addc_u32 s19, s37, 0
	s_add_i32 s24, s25, s43
	global_load_lds_dwordx4 v[190:191], off
	v_lshl_add_u64 v[218:219], s[18:19], 0, v[156:157]
	s_mov_b32 m0, s24
	v_lshl_add_u64 v[220:221], s[38:39], 0, v[154:155]
	global_load_lds_dwordx4 v[218:219], off
	s_add_i32 m0, s24, 0x2000
	v_lshl_add_u64 v[218:219], s[18:19], 0, v[152:153]
	global_load_lds_dwordx4 v[218:219], off
	s_mov_b32 m0, s2
	v_lshl_add_u64 v[218:219], s[38:39], 0, v[158:159]
	global_load_lds_dwordx4 v[218:219], off
	s_mov_b32 m0, s44
	s_nop 0
	global_load_lds_dwordx4 v[220:221], off
	s_waitcnt vmcnt(8)
	s_waitcnt lgkmcnt(0)
	s_barrier
	s_setprio 1
	s_waitcnt lgkmcnt(0)
	v_mfma_f32_16x16x32_bf16 v[60:63], v[128:131], v[178:181], v[60:63]
	v_mfma_f32_16x16x32_bf16 v[56:59], v[136:139], v[178:181], v[56:59]
	v_mfma_f32_16x16x32_bf16 v[44:47], v[128:131], v[186:189], v[44:47]
	v_mfma_f32_16x16x32_bf16 v[40:43], v[136:139], v[186:189], v[40:43]
	v_mfma_f32_16x16x32_bf16 v[28:31], v[128:131], v[202:205], v[28:31]
	v_mfma_f32_16x16x32_bf16 v[24:27], v[136:139], v[202:205], v[24:27]
	v_mfma_f32_16x16x32_bf16 v[12:15], v[128:131], v[210:213], v[12:15]
	v_mfma_f32_16x16x32_bf16 v[8:11], v[136:139], v[210:213], v[8:11]
	v_mfma_f32_16x16x32_bf16 v[60:63], v[132:135], v[182:185], v[60:63]
	v_mfma_f32_16x16x32_bf16 v[56:59], v[140:143], v[182:185], v[56:59]
	v_mfma_f32_16x16x32_bf16 v[44:47], v[132:135], v[194:197], v[44:47]
	v_mfma_f32_16x16x32_bf16 v[40:43], v[140:143], v[194:197], v[40:43]
	v_mfma_f32_16x16x32_bf16 v[28:31], v[132:135], v[206:209], v[28:31]
	v_mfma_f32_16x16x32_bf16 v[24:27], v[140:143], v[206:209], v[24:27]
	v_mfma_f32_16x16x32_bf16 v[12:15], v[132:135], v[214:217], v[12:15]
	v_mfma_f32_16x16x32_bf16 v[8:11], v[140:143], v[214:217], v[8:11]
	s_setprio 0
	s_setprio 1
	v_mfma_f32_16x16x32_bf16 v[52:55], v[144:147], v[178:181], v[52:55]
	v_mfma_f32_16x16x32_bf16 v[48:51], v[164:167], v[178:181], v[48:51]
	v_mfma_f32_16x16x32_bf16 v[36:39], v[144:147], v[186:189], v[36:39]
	v_mfma_f32_16x16x32_bf16 v[32:35], v[164:167], v[186:189], v[32:35]
	v_mfma_f32_16x16x32_bf16 v[20:23], v[144:147], v[202:205], v[20:23]
	v_mfma_f32_16x16x32_bf16 v[16:19], v[164:167], v[202:205], v[16:19]
	v_mfma_f32_16x16x32_bf16 v[4:7], v[144:147], v[210:213], v[4:7]
	v_mfma_f32_16x16x32_bf16 v[0:3], v[164:167], v[210:213], v[0:3]
	v_mfma_f32_16x16x32_bf16 v[52:55], v[148:151], v[182:185], v[52:55]
	v_mfma_f32_16x16x32_bf16 v[48:51], v[174:177], v[182:185], v[48:51]
	v_mfma_f32_16x16x32_bf16 v[36:39], v[148:151], v[194:197], v[36:39]
	v_mfma_f32_16x16x32_bf16 v[32:35], v[174:177], v[194:197], v[32:35]
	v_mfma_f32_16x16x32_bf16 v[20:23], v[148:151], v[206:209], v[20:23]
	v_mfma_f32_16x16x32_bf16 v[16:19], v[174:177], v[206:209], v[16:19]
	s_barrier
	s_setprio 2
	v_mfma_f32_16x16x32_bf16 v[4:7], v[148:151], v[214:217], v[4:7]
	v_mfma_f32_16x16x32_bf16 v[0:3], v[174:177], v[214:217], v[0:3]
	s_setprio 0
	s_add_i32 s24, 0, 0x18000
	s_add_i32 s25, 0, 0x1c000
	v_add_u32_e32 v140, 0x18000, v172
	v_add_u32_e32 v174, 0x1c000, v172
	ds_read_b128 v[128:131], v140
	ds_read_b128 v[132:135], v140 offset:1024
	ds_read_b128 v[136:139], v140 offset:2048
	ds_read_b128 v[140:143], v140 offset:3072
	ds_read_b128 v[144:147], v174
	ds_read_b128 v[148:151], v174 offset:1024
	ds_read_b128 v[164:167], v174 offset:2048
	ds_read_b128 v[174:177], v174 offset:3072
	s_add_u32 s18, s38, 0x160000
	s_addc_u32 s19, s39, 0
	s_mov_b32 m0, s45
	v_lshl_add_u64 v[230:231], s[18:19], 0, v[158:159]
	ds_read_b128 v[178:181], v173 offset:32768
	ds_read_b128 v[182:185], v173 offset:33792
	ds_read_b128 v[186:189], v173 offset:34816
	ds_read_b128 v[194:197], v173 offset:35840
	ds_read_b128 v[202:205], v173 offset:36864
	ds_read_b128 v[206:209], v173 offset:37888
	ds_read_b128 v[210:213], v173 offset:38912
	ds_read_b128 v[214:217], v173 offset:39936
	global_load_lds_dwordx4 v[230:231], off
	s_mov_b32 m0, s46
	v_lshl_add_u64 v[230:231], s[18:19], 0, v[154:155]
	global_load_lds_dwordx4 v[230:231], off
	s_waitcnt vmcnt(8)
	s_waitcnt lgkmcnt(0)
	s_barrier
; #define PG8_STAGE(bufoff, gbase, voff) do { _Pragma("unroll") for (int _i = 0; _i < 2; ++_i) \
;         __builtin_amdgcn_global_load_lds((const unsigned*)((const char*)(gbase) + (voff)[_i]), (PG8_LAS unsigned*)(lds + (bufoff) + ldsw + _i * 8192), 16, 0, 0); } while (0)
; #define PG8_LDA(dst, b, h) do { _Pragma("unroll") for (int m = 0; m < 4; ++m) _Pragma("unroll") for (int k = 0; k < 2; ++k) dst[m][k] = *(const PG8_LAS bf16x8*)(lds + PG8_SA(b, h) + aoff + m * 2048 + k * 1024); } while (0)
; #define PG8_MMA(ai, bj, At, Bt) do { __builtin_amdgcn_s_setprio(1); _Pragma("unroll") for (int m = 0; m < 4; ++m) _Pragma("unroll") for (int n = 0; n < 2; ++n) _Pragma("unroll") for (int k = 0; k < 2; ++k) \
;         acc[ai][bj][m][n] = __builtin_amdgcn_mfma_f32_16x16x32_bf16(Bt[n][k], At[m][k], acc[ai][bj][m][n], 0, 0, 0); __builtin_amdgcn_s_setprio(0); } while (0)
; #define PG8_WAIT_V(n) asm volatile("s_waitcnt vmcnt(" #n ")" ::: "memory")
; #define PG8_WAIT_L(n) asm volatile("s_waitcnt lgkmcnt(" #n ")" ::: "memory")
; #define PG8_BAR __builtin_amdgcn_s_barrier()
; #define PG8_SCHED __builtin_amdgcn_sched_barrier(0)
; template <class Epi, class Sched, bool ALIGN_EPI = false, bool SP2 = false>
; __device__ __forceinline__ void gemm_phase(PG8_LAS unsigned char* lds, const Gemm g, const Sched& S, const Epi& E) {
;     ...
;         for (int t = 0; t < nt; t += 2) {
;     ...
;             PG8_WAIT_V(8); PG8_WAIT_L(0); PG8_BAR; PG8_MMA(0, 0, At, B0); PG8_MMA(0, 1, At, B1); PG8_BAR; PG8_SCHED;
;             PG8_LDA(At, 1, 1); PG8_STAGE(PG8_SB(1, 0), b3, voffB); PG8_STAGE(PG8_SB(1, 1), b3 + hstep, voffB); PG8_STAGE(PG8_SA(1, 0), a3, voffA);
;             PG8_WAIT_V(8); PG8_WAIT_L(0); PG8_BAR; PG8_MMA(1, 0, At, B0); PG8_MMA(1, 1, At, B1); PG8_BAR; PG8_SCHED;
	s_setprio 1
	s_waitcnt lgkmcnt(0)
	v_mfma_f32_16x16x32_bf16 v[124:127], v[128:131], v[178:181], v[124:127]
	v_mfma_f32_16x16x32_bf16 v[120:123], v[136:139], v[178:181], v[120:123]
	v_mfma_f32_16x16x32_bf16 v[108:111], v[128:131], v[186:189], v[108:111]
	v_mfma_f32_16x16x32_bf16 v[104:107], v[136:139], v[186:189], v[104:107]
	v_mfma_f32_16x16x32_bf16 v[92:95], v[128:131], v[202:205], v[92:95]
	v_mfma_f32_16x16x32_bf16 v[88:91], v[136:139], v[202:205], v[88:91]
	v_mfma_f32_16x16x32_bf16 v[76:79], v[128:131], v[210:213], v[76:79]
	v_mfma_f32_16x16x32_bf16 v[72:75], v[136:139], v[210:213], v[72:75]
	v_mfma_f32_16x16x32_bf16 v[124:127], v[132:135], v[182:185], v[124:127]
	v_mfma_f32_16x16x32_bf16 v[120:123], v[140:143], v[182:185], v[120:123]
	v_mfma_f32_16x16x32_bf16 v[108:111], v[132:135], v[194:197], v[108:111]
	v_mfma_f32_16x16x32_bf16 v[104:107], v[140:143], v[194:197], v[104:107]
	v_mfma_f32_16x16x32_bf16 v[92:95], v[132:135], v[206:209], v[92:95]
	v_mfma_f32_16x16x32_bf16 v[88:91], v[140:143], v[206:209], v[88:91]
	v_mfma_f32_16x16x32_bf16 v[76:79], v[132:135], v[214:217], v[76:79]
	v_mfma_f32_16x16x32_bf16 v[72:75], v[140:143], v[214:217], v[72:75]
	s_setprio 0
	s_setprio 1
	v_mfma_f32_16x16x32_bf16 v[116:119], v[144:147], v[178:181], v[116:119]
	v_mfma_f32_16x16x32_bf16 v[112:115], v[164:167], v[178:181], v[112:115]
	v_mfma_f32_16x16x32_bf16 v[100:103], v[144:147], v[186:189], v[100:103]
	v_mfma_f32_16x16x32_bf16 v[96:99], v[164:167], v[186:189], v[96:99]
	v_mfma_f32_16x16x32_bf16 v[84:87], v[144:147], v[202:205], v[84:87]
	v_mfma_f32_16x16x32_bf16 v[80:83], v[164:167], v[202:205], v[80:83]
	v_mfma_f32_16x16x32_bf16 v[68:71], v[144:147], v[210:213], v[68:71]
	v_mfma_f32_16x16x32_bf16 v[64:67], v[164:167], v[210:213], v[64:67]
	v_mfma_f32_16x16x32_bf16 v[116:119], v[148:151], v[182:185], v[116:119]
	v_mfma_f32_16x16x32_bf16 v[112:115], v[174:177], v[182:185], v[112:115]
	v_mfma_f32_16x16x32_bf16 v[100:103], v[148:151], v[194:197], v[100:103]
	v_mfma_f32_16x16x32_bf16 v[96:99], v[174:177], v[194:197], v[96:99]
	v_mfma_f32_16x16x32_bf16 v[84:87], v[148:151], v[206:209], v[84:87]
	v_mfma_f32_16x16x32_bf16 v[80:83], v[174:177], v[206:209], v[80:83]
	s_barrier
	s_setprio 2
	v_mfma_f32_16x16x32_bf16 v[68:71], v[148:151], v[214:217], v[68:71]
	v_mfma_f32_16x16x32_bf16 v[64:67], v[174:177], v[214:217], v[64:67]
	s_setprio 0
	s_add_i32 s18, s24, s43
	v_lshl_add_u64 v[168:169], v[168:169], 0, s[16:17]
	s_mov_b32 m0, s18
	ds_read_b128 v[178:181], v173 offset:49152
	ds_read_b128 v[182:185], v173 offset:50176
	ds_read_b128 v[186:189], v173 offset:51200
	ds_read_b128 v[194:197], v173 offset:52224
	ds_read_b128 v[202:205], v173 offset:53248
	ds_read_b128 v[206:209], v173 offset:54272
	ds_read_b128 v[210:213], v173 offset:55296
	ds_read_b128 v[214:217], v173 offset:56320
	global_load_lds_dwordx4 v[168:169], off
	s_add_i32 m0, s18, 0x2000
	s_add_u32 s18, s36, 0x160080
	v_lshl_add_u64 v[168:169], v[190:191], 0, s[16:17]
	s_addc_u32 s19, s37, 0
	s_add_i32 s24, s25, s43
	global_load_lds_dwordx4 v[168:169], off
	s_mov_b32 m0, s24
	v_lshl_add_u64 v[168:169], s[18:19], 0, v[156:157]
	global_load_lds_dwordx4 v[168:169], off
	s_add_i32 m0, s24, 0x2000
	v_lshl_add_u64 v[168:169], s[18:19], 0, v[152:153]
	global_load_lds_dwordx4 v[168:169], off
	s_mov_b32 m0, s51
	v_lshl_add_u64 v[168:169], v[218:219], 0, s[16:17]
	global_load_lds_dwordx4 v[168:169], off
	s_mov_b32 m0, s52
	v_lshl_add_u64 v[168:169], v[220:221], 0, s[16:17]
	global_load_lds_dwordx4 v[168:169], off
	s_waitcnt vmcnt(8)
	s_waitcnt lgkmcnt(0)
	s_barrier
	s_setprio 1
	s_waitcnt lgkmcnt(0)
	v_mfma_f32_16x16x32_bf16 v[60:63], v[128:131], v[178:181], v[60:63]
	v_mfma_f32_16x16x32_bf16 v[56:59], v[136:139], v[178:181], v[56:59]
	v_mfma_f32_16x16x32_bf16 v[44:47], v[128:131], v[186:189], v[44:47]
	v_mfma_f32_16x16x32_bf16 v[40:43], v[136:139], v[186:189], v[40:43]
	v_mfma_f32_16x16x32_bf16 v[28:31], v[128:131], v[202:205], v[28:31]
	v_mfma_f32_16x16x32_bf16 v[24:27], v[136:139], v[202:205], v[24:27]
	v_mfma_f32_16x16x32_bf16 v[12:15], v[128:131], v[210:213], v[12:15]
	v_mfma_f32_16x16x32_bf16 v[8:11], v[136:139], v[210:213], v[8:11]
	v_mfma_f32_16x16x32_bf16 v[60:63], v[132:135], v[182:185], v[60:63]
	v_mfma_f32_16x16x32_bf16 v[56:59], v[140:143], v[182:185], v[56:59]
	v_mfma_f32_16x16x32_bf16 v[44:47], v[132:135], v[194:197], v[44:47]
	v_mfma_f32_16x16x32_bf16 v[40:43], v[140:143], v[194:197], v[40:43]
	v_mfma_f32_16x16x32_bf16 v[28:31], v[132:135], v[206:209], v[28:31]
	v_mfma_f32_16x16x32_bf16 v[24:27], v[140:143], v[206:209], v[24:27]
	v_mfma_f32_16x16x32_bf16 v[12:15], v[132:135], v[214:217], v[12:15]
	v_mfma_f32_16x16x32_bf16 v[8:11], v[140:143], v[214:217], v[8:11]
	s_setprio 0
	s_setprio 1
	v_mfma_f32_16x16x32_bf16 v[52:55], v[144:147], v[178:181], v[52:55]
	v_mfma_f32_16x16x32_bf16 v[48:51], v[164:167], v[178:181], v[48:51]
	v_mfma_f32_16x16x32_bf16 v[36:39], v[144:147], v[186:189], v[36:39]
	v_mfma_f32_16x16x32_bf16 v[32:35], v[164:167], v[186:189], v[32:35]
	v_mfma_f32_16x16x32_bf16 v[20:23], v[144:147], v[202:205], v[20:23]
	v_mfma_f32_16x16x32_bf16 v[16:19], v[164:167], v[202:205], v[16:19]
	v_mfma_f32_16x16x32_bf16 v[4:7], v[144:147], v[210:213], v[4:7]
	v_mfma_f32_16x16x32_bf16 v[0:3], v[164:167], v[210:213], v[0:3]
	v_mfma_f32_16x16x32_bf16 v[52:55], v[148:151], v[182:185], v[52:55]
	v_mfma_f32_16x16x32_bf16 v[48:51], v[174:177], v[182:185], v[48:51]
	v_mfma_f32_16x16x32_bf16 v[36:39], v[148:151], v[194:197], v[36:39]
	v_mfma_f32_16x16x32_bf16 v[32:35], v[174:177], v[194:197], v[32:35]
	v_mfma_f32_16x16x32_bf16 v[20:23], v[148:151], v[206:209], v[20:23]
	v_mfma_f32_16x16x32_bf16 v[16:19], v[174:177], v[206:209], v[16:19]
	s_barrier
	s_setprio 2
	v_mfma_f32_16x16x32_bf16 v[4:7], v[148:151], v[214:217], v[4:7]
	v_mfma_f32_16x16x32_bf16 v[0:3], v[174:177], v[214:217], v[0:3]
	s_setprio 0
	s_add_i32 s61, s61, 2
	s_add_u32 s59, s59, 0x100
	s_addc_u32 s60, s60, 0
	s_cmpk_gt_u32 s61, 0x55
	s_mov_b64 s[18:19], s[30:31]
	s_cbranch_scc0 .LBB0_817
	s_and_b64 vcc, exec, s[12:13]
	s_cbranch_vccz .LBB0_820
	s_barrier
